# v11 + K-loop hand-off trim: s_setprio 1 issued before the barrier that opens an MFMA segment, redundant lgkmcnt(0) behind it removed
# speedup vs baseline: 1.0083x; 1.0054x over previous
; #define GAS __attribute__((address_space(1)))
; #define PG8_STAGE(bufoff, gbase, voff) do { _Pragma("unroll") for (int _i = 0; _i < 2; ++_i) \
;         __builtin_amdgcn_global_load_lds((const GAS unsigned*)((const GAS char*)(gbase) + (voff)[_i]), (LAS unsigned*)(lds + (bufoff) + ldsw + _i * 8192), 16, 0, 0); } while (0)
; #define PG8_LDA(dst, b, h) do { _Pragma("unroll") for (int m = 0; m < 4; ++m) _Pragma("unroll") for (int k = 0; k < 2; ++k) dst[m][k] = *(const LAS bf16x8*)(lds + PG8_SA(b, h) + aoff + m * 2048 + k * 1024); } while (0)
; #define PG8_LDB(dst, b, h) do { _Pragma("unroll") for (int n = 0; n < 2; ++n) _Pragma("unroll") for (int k = 0; k < 2; ++k) dst[n][k] = *(const LAS bf16x8*)(lds + PG8_SB(b, h) + boff + n * 2048 + k * 1024); } while (0)
; #define PG8_MMA(ai, bj, At, Bt) do { __builtin_amdgcn_s_setprio(1); _Pragma("unroll") for (int m = 0; m < 4; ++m) _Pragma("unroll") for (int n = 0; n < 2; ++n) _Pragma("unroll") for (int k = 0; k < 2; ++k) \
;         acc[ai][bj][m][n] = __builtin_amdgcn_mfma_f32_16x16x32_bf16(Bt[n][k], At[m][k], acc[ai][bj][m][n], 0, 0, 0); __builtin_amdgcn_s_setprio(0); } while (0)
; #define PG8_WAIT_V(n) asm volatile("s_waitcnt vmcnt(" #n ")" ::: "memory")
; #define PG8_WAIT_L(n) asm volatile("s_waitcnt lgkmcnt(" #n ")" ::: "memory")
; template <class Epi, class Sched, bool ALIGN_EPI>
; __device__ __forceinline__ void gemm_phase(LAS unsigned char* lds, const Gemm g, const Sched& S, const Epi& E, int wave_id) {
;     ...
;         for (int t = 0; t < nt; t += 2) {
;             const bool last = (t == nt - 2);
;             const GAS char* a1 = cA + (size_t)(t + 1) * kstep;
;             const GAS char* a2 = last ? nA : cA + (size_t)(t + 2) * kstep; const GAS char* b2 = last ? nB : cB + (size_t)(t + 2) * kstep;
;             const GAS char* a3 = a2 + kstep; const GAS char* b3 = b2 + kstep;
;             PG8_LDB(B0, 0, 0); PG8_LDB(B1, 0, 1); PG8_SCHED; PG8_LDA(At, 0, 0); PG8_STAGE(PG8_SA(1, 1), a1 + hsA, voffA);
;             PG8_WAIT_V(8); PG8_WAIT_L(0); PG8_BAR; PG8_MMA(0, 0, At, B0); PG8_MMA(0, 1, At, B1); PG8_BAR; PG8_SCHED;
;             PG8_LDA(At, 0, 1); PG8_STAGE(PG8_SB(0, 0), b2, voffB); PG8_STAGE(PG8_SB(0, 1), b2 + hsB, voffB); PG8_STAGE(PG8_SA(0, 0), a2, voffA);
;             PG8_WAIT_V(8); PG8_WAIT_L(0); PG8_BAR; PG8_MMA(1, 0, At, B0); PG8_MMA(1, 1, At, B1); PG8_BAR; PG8_SCHED;
.LBB0_1117:
	s_add_u32 s58, s0, 0xfff80080
	s_addc_u32 s59, s1, -1
	s_cmp_eq_u32 s76, 28
	s_cselect_b32 s61, s33, s59
	s_cselect_b32 s60, s47, s58
	s_cselect_b32 s59, s49, s74
	s_cselect_b32 s58, s57, s71
	s_mov_b32 m0, s87
	v_lshl_add_u64 v[206:207], s[0:1], 0, v[204:205]
	global_load_lds_dwordx4 v[206:207], off
	v_lshl_add_u64 v[206:207], s[0:1], 0, v[202:203]
	s_mov_b32 m0, s88
	s_nop 0
	global_load_lds_dwordx4 v[206:207], off
	v_add_u32_e32 v0, 0x10400, v250
	ds_read_b128 v[130:133], v0
	ds_read_b128 v[134:137], v0 offset:1024
	ds_read_b128 v[138:141], v0 offset:2048
	ds_read_b128 v[142:145], v0 offset:3072
	v_add_u32_e32 v0, 0x14400, v250
	ds_read_b128 v[146:149], v0
	ds_read_b128 v[150:153], v0 offset:1024
	ds_read_b128 v[154:157], v0 offset:2048
	ds_read_b128 v[158:161], v0 offset:3072
	ds_read_b128 v[162:165], v253 offset:1024
	ds_read_b128 v[166:169], v253 offset:2048
	ds_read_b128 v[170:173], v253 offset:3072
	ds_read_b128 v[174:177], v253 offset:4096
	ds_read_b128 v[178:181], v253 offset:5120
	ds_read_b128 v[182:185], v253 offset:6144
	ds_read_b128 v[186:189], v253 offset:7168
	ds_read_b128 v[190:193], v253 offset:8192
	s_waitcnt vmcnt(8)
	s_waitcnt lgkmcnt(0)
	s_setprio 1
	s_barrier
	v_mfma_f32_16x16x32_bf16 v[126:129], v[130:133], v[162:165], v[126:129]
	v_mfma_f32_16x16x32_bf16 v[122:125], v[138:141], v[162:165], v[122:125]
	v_mfma_f32_16x16x32_bf16 v[110:113], v[130:133], v[170:173], v[110:113]
	v_mfma_f32_16x16x32_bf16 v[106:109], v[138:141], v[170:173], v[106:109]
	v_mfma_f32_16x16x32_bf16 v[94:97], v[130:133], v[178:181], v[94:97]
	v_mfma_f32_16x16x32_bf16 v[90:93], v[138:141], v[178:181], v[90:93]
	v_mfma_f32_16x16x32_bf16 v[78:81], v[130:133], v[186:189], v[78:81]
	v_mfma_f32_16x16x32_bf16 v[74:77], v[138:141], v[186:189], v[74:77]
	v_mfma_f32_16x16x32_bf16 v[126:129], v[134:137], v[166:169], v[126:129]
	v_mfma_f32_16x16x32_bf16 v[122:125], v[142:145], v[166:169], v[122:125]
	v_mfma_f32_16x16x32_bf16 v[110:113], v[134:137], v[174:177], v[110:113]
	v_mfma_f32_16x16x32_bf16 v[106:109], v[142:145], v[174:177], v[106:109]
	v_mfma_f32_16x16x32_bf16 v[94:97], v[134:137], v[182:185], v[94:97]
	v_mfma_f32_16x16x32_bf16 v[90:93], v[142:145], v[182:185], v[90:93]
	v_mfma_f32_16x16x32_bf16 v[78:81], v[134:137], v[190:193], v[78:81]
	v_mfma_f32_16x16x32_bf16 v[74:77], v[142:145], v[190:193], v[74:77]
	s_setprio 0
	s_setprio 1
	v_mfma_f32_16x16x32_bf16 v[118:121], v[146:149], v[162:165], v[118:121]
	v_mfma_f32_16x16x32_bf16 v[114:117], v[154:157], v[162:165], v[114:117]
	v_mfma_f32_16x16x32_bf16 v[102:105], v[146:149], v[170:173], v[102:105]
	v_mfma_f32_16x16x32_bf16 v[98:101], v[154:157], v[170:173], v[98:101]
	v_mfma_f32_16x16x32_bf16 v[86:89], v[146:149], v[178:181], v[86:89]
	v_mfma_f32_16x16x32_bf16 v[82:85], v[154:157], v[178:181], v[82:85]
	v_mfma_f32_16x16x32_bf16 v[70:73], v[146:149], v[186:189], v[70:73]
	v_mfma_f32_16x16x32_bf16 v[66:69], v[154:157], v[186:189], v[66:69]
	v_mfma_f32_16x16x32_bf16 v[118:121], v[150:153], v[166:169], v[118:121]
	v_mfma_f32_16x16x32_bf16 v[114:117], v[158:161], v[166:169], v[114:117]
	v_mfma_f32_16x16x32_bf16 v[102:105], v[150:153], v[174:177], v[102:105]
	v_mfma_f32_16x16x32_bf16 v[98:101], v[158:161], v[174:177], v[98:101]
	v_mfma_f32_16x16x32_bf16 v[86:89], v[150:153], v[182:185], v[86:89]
	v_mfma_f32_16x16x32_bf16 v[82:85], v[158:161], v[182:185], v[82:85]
	v_mfma_f32_16x16x32_bf16 v[70:73], v[150:153], v[190:193], v[70:73]
	v_mfma_f32_16x16x32_bf16 v[66:69], v[158:161], v[190:193], v[66:69]
	s_setprio 0
	s_barrier
	s_mov_b32 m0, s15
	v_lshl_add_u64 v[206:207], s[58:59], 0, v[196:197]
	s_add_u32 vcc_lo, s58, 0x80000
	global_load_lds_dwordx4 v[206:207], off
	v_lshl_add_u64 v[208:209], s[58:59], 0, v[200:201]
	s_mov_b32 m0, s73
	s_addc_u32 vcc_hi, s59, 0
	global_load_lds_dwordx4 v[208:209], off
	v_lshl_add_u64 v[210:211], vcc, 0, v[196:197]
	s_mov_b32 m0, s75
	v_lshl_add_u64 v[212:213], s[60:61], 0, v[198:199]
	global_load_lds_dwordx4 v[210:211], off
	v_lshl_add_u64 v[210:211], vcc, 0, v[200:201]
	s_mov_b32 m0, s80
	s_nop 0
	global_load_lds_dwordx4 v[210:211], off
	v_lshl_add_u64 v[210:211], s[60:61], 0, v[194:195]
	s_mov_b32 m0, s81
	s_nop 0
	global_load_lds_dwordx4 v[210:211], off
	s_mov_b32 m0, s82
	s_nop 0
	global_load_lds_dwordx4 v[212:213], off
	ds_read_b128 v[162:165], v253 offset:17408
	ds_read_b128 v[166:169], v253 offset:18432
	ds_read_b128 v[170:173], v253 offset:19456
	ds_read_b128 v[174:177], v253 offset:20480
	ds_read_b128 v[178:181], v253 offset:21504
	ds_read_b128 v[182:185], v253 offset:22528
	ds_read_b128 v[186:189], v253 offset:23552
	ds_read_b128 v[190:193], v253 offset:24576
	s_waitcnt vmcnt(8)
	s_waitcnt lgkmcnt(0)
	s_setprio 1
	s_barrier
; #define PG8_STAGE(bufoff, gbase, voff) do { _Pragma("unroll") for (int _i = 0; _i < 2; ++_i) \
;         __builtin_amdgcn_global_load_lds((const GAS unsigned*)((const GAS char*)(gbase) + (voff)[_i]), (LAS unsigned*)(lds + (bufoff) + ldsw + _i * 8192), 16, 0, 0); } while (0)
; #define PG8_LDA(dst, b, h) do { _Pragma("unroll") for (int m = 0; m < 4; ++m) _Pragma("unroll") for (int k = 0; k < 2; ++k) dst[m][k] = *(const LAS bf16x8*)(lds + PG8_SA(b, h) + aoff + m * 2048 + k * 1024); } while (0)
; #define PG8_LDB(dst, b, h) do { _Pragma("unroll") for (int n = 0; n < 2; ++n) _Pragma("unroll") for (int k = 0; k < 2; ++k) dst[n][k] = *(const LAS bf16x8*)(lds + PG8_SB(b, h) + boff + n * 2048 + k * 1024); } while (0)
; #define PG8_MMA(ai, bj, At, Bt) do { __builtin_amdgcn_s_setprio(1); _Pragma("unroll") for (int m = 0; m < 4; ++m) _Pragma("unroll") for (int n = 0; n < 2; ++n) _Pragma("unroll") for (int k = 0; k < 2; ++k) \
;         acc[ai][bj][m][n] = __builtin_amdgcn_mfma_f32_16x16x32_bf16(Bt[n][k], At[m][k], acc[ai][bj][m][n], 0, 0, 0); __builtin_amdgcn_s_setprio(0); } while (0)
; #define PG8_WAIT_V(n) asm volatile("s_waitcnt vmcnt(" #n ")" ::: "memory")
; #define PG8_WAIT_L(n) asm volatile("s_waitcnt lgkmcnt(" #n ")" ::: "memory")
; #define PG8_BAR __builtin_amdgcn_s_barrier()
; #define PG8_SCHED __builtin_amdgcn_sched_barrier(0)
; template <class Epi, class Sched, bool ALIGN_EPI>
; __device__ __forceinline__ void gemm_phase(LAS unsigned char* lds, const Gemm g, const Sched& S, const Epi& E, int wave_id) {
;     ...
;             PG8_WAIT_V(8); PG8_WAIT_L(0); PG8_BAR; PG8_MMA(1, 0, At, B0); PG8_MMA(1, 1, At, B1); PG8_BAR; PG8_SCHED;
;             PG8_LDB(B0, 1, 0); PG8_LDB(B1, 1, 1); PG8_SCHED; PG8_LDA(At, 1, 0); PG8_STAGE(PG8_SA(0, 1), a2 + hsA, voffA);
;             PG8_WAIT_V(8); PG8_WAIT_L(0); PG8_BAR; PG8_MMA(0, 0, At, B0); PG8_MMA(0, 1, At, B1); PG8_BAR; PG8_SCHED;
	v_mfma_f32_16x16x32_bf16 v[62:65], v[130:133], v[162:165], v[62:65]
	v_mfma_f32_16x16x32_bf16 v[58:61], v[138:141], v[162:165], v[58:61]
	v_mfma_f32_16x16x32_bf16 v[46:49], v[130:133], v[170:173], v[46:49]
	v_mfma_f32_16x16x32_bf16 v[42:45], v[138:141], v[170:173], v[42:45]
	v_mfma_f32_16x16x32_bf16 v[30:33], v[130:133], v[178:181], v[30:33]
	v_mfma_f32_16x16x32_bf16 v[26:29], v[138:141], v[178:181], v[26:29]
	v_mfma_f32_16x16x32_bf16 v[14:17], v[130:133], v[186:189], v[14:17]
	v_mfma_f32_16x16x32_bf16 v[10:13], v[138:141], v[186:189], v[10:13]
	v_mfma_f32_16x16x32_bf16 v[62:65], v[134:137], v[166:169], v[62:65]
	v_mfma_f32_16x16x32_bf16 v[58:61], v[142:145], v[166:169], v[58:61]
	v_mfma_f32_16x16x32_bf16 v[46:49], v[134:137], v[174:177], v[46:49]
	v_mfma_f32_16x16x32_bf16 v[42:45], v[142:145], v[174:177], v[42:45]
	v_mfma_f32_16x16x32_bf16 v[30:33], v[134:137], v[182:185], v[30:33]
	v_mfma_f32_16x16x32_bf16 v[26:29], v[142:145], v[182:185], v[26:29]
	v_mfma_f32_16x16x32_bf16 v[14:17], v[134:137], v[190:193], v[14:17]
	v_mfma_f32_16x16x32_bf16 v[10:13], v[142:145], v[190:193], v[10:13]
	s_setprio 0
	s_setprio 1
	v_mfma_f32_16x16x32_bf16 v[54:57], v[146:149], v[162:165], v[54:57]
	v_mfma_f32_16x16x32_bf16 v[50:53], v[154:157], v[162:165], v[50:53]
	v_mfma_f32_16x16x32_bf16 v[38:41], v[146:149], v[170:173], v[38:41]
	v_mfma_f32_16x16x32_bf16 v[34:37], v[154:157], v[170:173], v[34:37]
	v_mfma_f32_16x16x32_bf16 v[22:25], v[146:149], v[178:181], v[22:25]
	v_mfma_f32_16x16x32_bf16 v[18:21], v[154:157], v[178:181], v[18:21]
	v_mfma_f32_16x16x32_bf16 v[6:9], v[146:149], v[186:189], v[6:9]
	v_mfma_f32_16x16x32_bf16 v[2:5], v[154:157], v[186:189], v[2:5]
	v_mfma_f32_16x16x32_bf16 v[54:57], v[150:153], v[166:169], v[54:57]
	v_mfma_f32_16x16x32_bf16 v[50:53], v[158:161], v[166:169], v[50:53]
	v_mfma_f32_16x16x32_bf16 v[38:41], v[150:153], v[174:177], v[38:41]
	v_mfma_f32_16x16x32_bf16 v[34:37], v[158:161], v[174:177], v[34:37]
	v_mfma_f32_16x16x32_bf16 v[22:25], v[150:153], v[182:185], v[22:25]
	v_mfma_f32_16x16x32_bf16 v[18:21], v[158:161], v[182:185], v[18:21]
	v_mfma_f32_16x16x32_bf16 v[6:9], v[150:153], v[190:193], v[6:9]
	v_mfma_f32_16x16x32_bf16 v[2:5], v[158:161], v[190:193], v[2:5]
	s_setprio 0
	s_barrier
	s_add_u32 s60, s60, 0x80000
	s_addc_u32 s61, s61, 0
	s_mov_b32 m0, s83
	v_lshl_add_u64 v[214:215], s[60:61], 0, v[194:195]
	global_load_lds_dwordx4 v[214:215], off
	v_lshl_add_u64 v[214:215], s[60:61], 0, v[198:199]
	s_mov_b32 m0, s84
	s_nop 0
	global_load_lds_dwordx4 v[214:215], off
	v_add_u32_e32 v0, 0x18400, v250
	ds_read_b128 v[130:133], v0
	ds_read_b128 v[134:137], v0 offset:1024
	ds_read_b128 v[138:141], v0 offset:2048
	ds_read_b128 v[142:145], v0 offset:3072
	v_add_u32_e32 v0, 0x1c400, v250
	ds_read_b128 v[146:149], v0
	ds_read_b128 v[150:153], v0 offset:1024
	ds_read_b128 v[154:157], v0 offset:2048
	ds_read_b128 v[158:161], v0 offset:3072
	ds_read_b128 v[162:165], v253 offset:33792
	ds_read_b128 v[166:169], v253 offset:34816
	ds_read_b128 v[170:173], v253 offset:35840
	ds_read_b128 v[174:177], v253 offset:36864
	ds_read_b128 v[178:181], v253 offset:37888
	ds_read_b128 v[182:185], v253 offset:38912
	ds_read_b128 v[186:189], v253 offset:39936
	ds_read_b128 v[190:193], v253 offset:40960
	s_waitcnt vmcnt(8)
	s_waitcnt lgkmcnt(0)
	s_setprio 1
	s_barrier
	v_mfma_f32_16x16x32_bf16 v[126:129], v[130:133], v[162:165], v[126:129]
	v_mfma_f32_16x16x32_bf16 v[122:125], v[138:141], v[162:165], v[122:125]
	v_mfma_f32_16x16x32_bf16 v[110:113], v[130:133], v[170:173], v[110:113]
	v_mfma_f32_16x16x32_bf16 v[106:109], v[138:141], v[170:173], v[106:109]
	v_mfma_f32_16x16x32_bf16 v[94:97], v[130:133], v[178:181], v[94:97]
	v_mfma_f32_16x16x32_bf16 v[90:93], v[138:141], v[178:181], v[90:93]
	v_mfma_f32_16x16x32_bf16 v[78:81], v[130:133], v[186:189], v[78:81]
	v_mfma_f32_16x16x32_bf16 v[74:77], v[138:141], v[186:189], v[74:77]
	v_mfma_f32_16x16x32_bf16 v[126:129], v[134:137], v[166:169], v[126:129]
	v_mfma_f32_16x16x32_bf16 v[122:125], v[142:145], v[166:169], v[122:125]
	v_mfma_f32_16x16x32_bf16 v[110:113], v[134:137], v[174:177], v[110:113]
	v_mfma_f32_16x16x32_bf16 v[106:109], v[142:145], v[174:177], v[106:109]
	v_mfma_f32_16x16x32_bf16 v[94:97], v[134:137], v[182:185], v[94:97]
	v_mfma_f32_16x16x32_bf16 v[90:93], v[142:145], v[182:185], v[90:93]
	v_mfma_f32_16x16x32_bf16 v[78:81], v[134:137], v[190:193], v[78:81]
	v_mfma_f32_16x16x32_bf16 v[74:77], v[142:145], v[190:193], v[74:77]
	s_setprio 0
	s_setprio 1
	v_mfma_f32_16x16x32_bf16 v[118:121], v[146:149], v[162:165], v[118:121]
	v_mfma_f32_16x16x32_bf16 v[114:117], v[154:157], v[162:165], v[114:117]
	v_mfma_f32_16x16x32_bf16 v[102:105], v[146:149], v[170:173], v[102:105]
	v_mfma_f32_16x16x32_bf16 v[98:101], v[154:157], v[170:173], v[98:101]
	v_mfma_f32_16x16x32_bf16 v[86:89], v[146:149], v[178:181], v[86:89]
	v_mfma_f32_16x16x32_bf16 v[82:85], v[154:157], v[178:181], v[82:85]
	v_mfma_f32_16x16x32_bf16 v[70:73], v[146:149], v[186:189], v[70:73]
	v_mfma_f32_16x16x32_bf16 v[66:69], v[154:157], v[186:189], v[66:69]
	v_mfma_f32_16x16x32_bf16 v[118:121], v[150:153], v[166:169], v[118:121]
	v_mfma_f32_16x16x32_bf16 v[114:117], v[158:161], v[166:169], v[114:117]
	v_mfma_f32_16x16x32_bf16 v[102:105], v[150:153], v[174:177], v[102:105]
	v_mfma_f32_16x16x32_bf16 v[98:101], v[158:161], v[174:177], v[98:101]
	v_mfma_f32_16x16x32_bf16 v[86:89], v[150:153], v[182:185], v[86:89]
	v_mfma_f32_16x16x32_bf16 v[82:85], v[158:161], v[182:185], v[82:85]
	v_mfma_f32_16x16x32_bf16 v[70:73], v[150:153], v[190:193], v[70:73]
	v_mfma_f32_16x16x32_bf16 v[66:69], v[158:161], v[190:193], v[66:69]
	s_setprio 0
	s_barrier
; #define PG8_STAGE(bufoff, gbase, voff) do { _Pragma("unroll") for (int _i = 0; _i < 2; ++_i) \
;         __builtin_amdgcn_global_load_lds((const GAS unsigned*)((const GAS char*)(gbase) + (voff)[_i]), (LAS unsigned*)(lds + (bufoff) + ldsw + _i * 8192), 16, 0, 0); } while (0)
; #define PG8_LDA(dst, b, h) do { _Pragma("unroll") for (int m = 0; m < 4; ++m) _Pragma("unroll") for (int k = 0; k < 2; ++k) dst[m][k] = *(const LAS bf16x8*)(lds + PG8_SA(b, h) + aoff + m * 2048 + k * 1024); } while (0)
; #define PG8_MMA(ai, bj, At, Bt) do { __builtin_amdgcn_s_setprio(1); _Pragma("unroll") for (int m = 0; m < 4; ++m) _Pragma("unroll") for (int n = 0; n < 2; ++n) _Pragma("unroll") for (int k = 0; k < 2; ++k) \
;         acc[ai][bj][m][n] = __builtin_amdgcn_mfma_f32_16x16x32_bf16(Bt[n][k], At[m][k], acc[ai][bj][m][n], 0, 0, 0); __builtin_amdgcn_s_setprio(0); } while (0)
; #define PG8_WAIT_V(n) asm volatile("s_waitcnt vmcnt(" #n ")" ::: "memory")
; #define PG8_WAIT_L(n) asm volatile("s_waitcnt lgkmcnt(" #n ")" ::: "memory")
; #define PG8_BAR __builtin_amdgcn_s_barrier()
; #define PG8_SCHED __builtin_amdgcn_sched_barrier(0)
; template <class Epi, class Sched, bool ALIGN_EPI>
; __device__ __forceinline__ void gemm_phase(LAS unsigned char* lds, const Gemm g, const Sched& S, const Epi& E, int wave_id) {
;     ...
;             PG8_LDA(At, 1, 1); PG8_STAGE(PG8_SB(1, 0), b3, voffB); PG8_STAGE(PG8_SB(1, 1), b3 + hsB, voffB); PG8_STAGE(PG8_SA(1, 0), a3, voffA);
;             PG8_WAIT_V(8); PG8_WAIT_L(0); PG8_BAR; PG8_MMA(1, 0, At, B0); PG8_MMA(1, 1, At, B1); PG8_BAR; PG8_SCHED;
;         }
	s_mov_b32 m0, s95
	v_lshl_add_u64 v[206:207], v[206:207], 0, s[92:93]
	s_add_u32 s58, s58, 0x80080
	global_load_lds_dwordx4 v[206:207], off
	v_lshl_add_u64 v[206:207], v[208:209], 0, s[92:93]
	s_mov_b32 m0, s96
	s_addc_u32 s59, s59, 0
	global_load_lds_dwordx4 v[206:207], off
	v_lshl_add_u64 v[206:207], s[58:59], 0, v[196:197]
	s_mov_b32 m0, s17
	s_nop 0
	global_load_lds_dwordx4 v[206:207], off
	v_lshl_add_u64 v[206:207], s[58:59], 0, v[200:201]
	s_mov_b32 m0, s18
	s_nop 0
	global_load_lds_dwordx4 v[206:207], off
	v_lshl_add_u64 v[206:207], v[210:211], 0, s[92:93]
	s_mov_b32 m0, s97
	s_nop 0
	global_load_lds_dwordx4 v[206:207], off
	v_lshl_add_u64 v[206:207], v[212:213], 0, s[92:93]
	s_mov_b32 m0, s16
	s_nop 0
	global_load_lds_dwordx4 v[206:207], off
	ds_read_b128 v[162:165], v253 offset:50176
	ds_read_b128 v[166:169], v253 offset:51200
	ds_read_b128 v[170:173], v253 offset:52224
	ds_read_b128 v[174:177], v253 offset:53248
	ds_read_b128 v[178:181], v253 offset:54272
	ds_read_b128 v[182:185], v253 offset:55296
	ds_read_b128 v[186:189], v253 offset:56320
	ds_read_b128 v[190:193], v253 offset:57344
	s_waitcnt vmcnt(8)
	s_waitcnt lgkmcnt(0)
	s_setprio 1
	s_barrier
	v_mfma_f32_16x16x32_bf16 v[62:65], v[130:133], v[162:165], v[62:65]
	v_mfma_f32_16x16x32_bf16 v[58:61], v[138:141], v[162:165], v[58:61]
	v_mfma_f32_16x16x32_bf16 v[46:49], v[130:133], v[170:173], v[46:49]
	v_mfma_f32_16x16x32_bf16 v[42:45], v[138:141], v[170:173], v[42:45]
	v_mfma_f32_16x16x32_bf16 v[30:33], v[130:133], v[178:181], v[30:33]
	v_mfma_f32_16x16x32_bf16 v[26:29], v[138:141], v[178:181], v[26:29]
	v_mfma_f32_16x16x32_bf16 v[14:17], v[130:133], v[186:189], v[14:17]
	v_mfma_f32_16x16x32_bf16 v[10:13], v[138:141], v[186:189], v[10:13]
	v_mfma_f32_16x16x32_bf16 v[62:65], v[134:137], v[166:169], v[62:65]
	v_mfma_f32_16x16x32_bf16 v[58:61], v[142:145], v[166:169], v[58:61]
	v_mfma_f32_16x16x32_bf16 v[46:49], v[134:137], v[174:177], v[46:49]
	v_mfma_f32_16x16x32_bf16 v[42:45], v[142:145], v[174:177], v[42:45]
	v_mfma_f32_16x16x32_bf16 v[30:33], v[134:137], v[182:185], v[30:33]
	v_mfma_f32_16x16x32_bf16 v[26:29], v[142:145], v[182:185], v[26:29]
	v_mfma_f32_16x16x32_bf16 v[14:17], v[134:137], v[190:193], v[14:17]
	v_mfma_f32_16x16x32_bf16 v[10:13], v[142:145], v[190:193], v[10:13]
	s_setprio 0
	s_setprio 1
	v_mfma_f32_16x16x32_bf16 v[54:57], v[146:149], v[162:165], v[54:57]
	v_mfma_f32_16x16x32_bf16 v[50:53], v[154:157], v[162:165], v[50:53]
	v_mfma_f32_16x16x32_bf16 v[38:41], v[146:149], v[170:173], v[38:41]
	v_mfma_f32_16x16x32_bf16 v[34:37], v[154:157], v[170:173], v[34:37]
	v_mfma_f32_16x16x32_bf16 v[22:25], v[146:149], v[178:181], v[22:25]
	v_mfma_f32_16x16x32_bf16 v[18:21], v[154:157], v[178:181], v[18:21]
	v_mfma_f32_16x16x32_bf16 v[6:9], v[146:149], v[186:189], v[6:9]
	v_mfma_f32_16x16x32_bf16 v[2:5], v[154:157], v[186:189], v[2:5]
	v_mfma_f32_16x16x32_bf16 v[54:57], v[150:153], v[166:169], v[54:57]
	v_mfma_f32_16x16x32_bf16 v[50:53], v[158:161], v[166:169], v[50:53]
	v_mfma_f32_16x16x32_bf16 v[38:41], v[150:153], v[174:177], v[38:41]
	v_mfma_f32_16x16x32_bf16 v[34:37], v[158:161], v[174:177], v[34:37]
	v_mfma_f32_16x16x32_bf16 v[22:25], v[150:153], v[182:185], v[22:25]
	v_mfma_f32_16x16x32_bf16 v[18:21], v[158:161], v[182:185], v[18:21]
	v_mfma_f32_16x16x32_bf16 v[6:9], v[150:153], v[190:193], v[6:9]
	v_mfma_f32_16x16x32_bf16 v[2:5], v[158:161], v[190:193], v[2:5]
	s_setprio 0
	s_barrier
	s_add_i32 s76, s76, 2
	s_add_u32 s71, s71, 0x100
	s_addc_u32 s74, s74, 0
	s_add_u32 s0, s0, 0x100
	s_addc_u32 s1, s1, 0
	s_cmp_gt_u32 s76, 29
	s_cbranch_scc0 .LBB0_1117
	s_and_b64 vcc, exec, s[44:45]
	s_cbranch_vccz .LBB0_1120
	s_barrier

; #define GAS __attribute__((address_space(1)))
; #define PG8_STAGE(bufoff, gbase, voff) do { _Pragma("unroll") for (int _i = 0; _i < 2; ++_i) \
;         __builtin_amdgcn_global_load_lds((const GAS unsigned*)((const GAS char*)(gbase) + (voff)[_i]), (LAS unsigned*)(lds + (bufoff) + ldsw + _i * 8192), 16, 0, 0); } while (0)
; #define PG8_LDA(dst, b, h) do { _Pragma("unroll") for (int m = 0; m < 4; ++m) _Pragma("unroll") for (int k = 0; k < 2; ++k) dst[m][k] = *(const LAS bf16x8*)(lds + PG8_SA(b, h) + aoff + m * 2048 + k * 1024); } while (0)
; #define PG8_LDB(dst, b, h) do { _Pragma("unroll") for (int n = 0; n < 2; ++n) _Pragma("unroll") for (int k = 0; k < 2; ++k) dst[n][k] = *(const LAS bf16x8*)(lds + PG8_SB(b, h) + boff + n * 2048 + k * 1024); } while (0)
; #define PG8_MMA(ai, bj, At, Bt) do { __builtin_amdgcn_s_setprio(1); _Pragma("unroll") for (int m = 0; m < 4; ++m) _Pragma("unroll") for (int n = 0; n < 2; ++n) _Pragma("unroll") for (int k = 0; k < 2; ++k) \
;         acc[ai][bj][m][n] = __builtin_amdgcn_mfma_f32_16x16x32_bf16(Bt[n][k], At[m][k], acc[ai][bj][m][n], 0, 0, 0); __builtin_amdgcn_s_setprio(0); } while (0)
; #define PG8_WAIT_V(n) asm volatile("s_waitcnt vmcnt(" #n ")" ::: "memory")
; #define PG8_WAIT_L(n) asm volatile("s_waitcnt lgkmcnt(" #n ")" ::: "memory")
; template <class Epi, class Sched, bool ALIGN_EPI>
; __device__ __forceinline__ void gemm_phase(LAS unsigned char* lds, const Gemm g, const Sched& S, const Epi& E, int wave_id) {
;     ...
;         for (int t = 0; t < nt; t += 2) {
;             const bool last = (t == nt - 2);
;             const GAS char* a1 = cA + (size_t)(t + 1) * kstep;
;             const GAS char* a2 = last ? nA : cA + (size_t)(t + 2) * kstep; const GAS char* b2 = last ? nB : cB + (size_t)(t + 2) * kstep;
;             const GAS char* a3 = a2 + kstep; const GAS char* b3 = b2 + kstep;
;             PG8_LDB(B0, 0, 0); PG8_LDB(B1, 0, 1); PG8_SCHED; PG8_LDA(At, 0, 0); PG8_STAGE(PG8_SA(1, 1), a1 + hsA, voffA);
;             PG8_WAIT_V(8); PG8_WAIT_L(0); PG8_BAR; PG8_MMA(0, 0, At, B0); PG8_MMA(0, 1, At, B1); PG8_BAR; PG8_SCHED;
;             PG8_LDA(At, 0, 1); PG8_STAGE(PG8_SB(0, 0), b2, voffB); PG8_STAGE(PG8_SB(0, 1), b2 + hsB, voffB); PG8_STAGE(PG8_SA(0, 0), a2, voffA);
;             PG8_WAIT_V(8); PG8_WAIT_L(0); PG8_BAR; PG8_MMA(1, 0, At, B0); PG8_MMA(1, 1, At, B1); PG8_BAR; PG8_SCHED;
.LBB0_1335:
	s_add_u32 s34, s12, s26
	s_addc_u32 s35, s13, s27
	s_add_u32 s30, s34, 0x100
	s_addc_u32 s31, s35, 0
	s_and_b64 s[28:29], s[24:25], exec
	s_cselect_b32 s29, s17, s31
	s_cselect_b32 s28, s16, s30
	s_add_u32 s26, s10, s26
	s_addc_u32 s27, s11, s27
	s_add_u32 s26, s26, 0x100
	s_addc_u32 s27, s27, 0
	s_and_b64 s[24:25], s[24:25], exec
	s_cselect_b32 s31, s60, s27
	s_cselect_b32 s30, s61, s26
	s_add_u32 s36, s34, 0x18080
	s_addc_u32 s37, s35, 0
	s_add_i32 m0, s40, 0xc400
	s_add_i32 s62, s40, 0xe400
	s_add_u32 s34, s30, 0x10000
	s_addc_u32 s35, s31, 0
	s_add_u32 s26, s28, 0x18000
	s_addc_u32 s27, s29, 0
	s_add_u32 s24, s30, 0x10080
	s_addc_u32 s25, s31, 0
	v_lshl_add_u64 v[122:123], s[36:37], 0, v[70:71]
	global_load_lds_dwordx4 v[122:123], off
	v_lshl_add_u64 v[122:123], s[36:37], 0, v[68:69]
	s_mov_b32 m0, s62
	s_nop 0
	global_load_lds_dwordx4 v[122:123], off
	v_add_u32_e32 v86, 0x10400, v73
	ds_read_b128 v[74:77], v86
	ds_read_b128 v[78:81], v86 offset:1024
	ds_read_b128 v[82:85], v86 offset:2048
	ds_read_b128 v[86:89], v86 offset:3072
	ds_read_b128 v[90:93], v72 offset:1024
	ds_read_b128 v[94:97], v72 offset:2048
	ds_read_b128 v[98:101], v72 offset:3072
	ds_read_b128 v[102:105], v72 offset:4096
	ds_read_b128 v[106:109], v72 offset:5120
	ds_read_b128 v[110:113], v72 offset:6144
	ds_read_b128 v[114:117], v72 offset:7168
	ds_read_b128 v[118:121], v72 offset:8192
	s_waitcnt vmcnt(8)
	s_waitcnt lgkmcnt(0)
	s_setprio 1
	s_barrier
	v_mfma_f32_16x16x32_bf16 v[62:65], v[74:77], v[90:93], v[62:65]
	v_mfma_f32_16x16x32_bf16 v[58:61], v[82:85], v[90:93], v[58:61]
	v_mfma_f32_16x16x32_bf16 v[54:57], v[74:77], v[98:101], v[54:57]
	v_mfma_f32_16x16x32_bf16 v[50:53], v[82:85], v[98:101], v[50:53]
	v_mfma_f32_16x16x32_bf16 v[46:49], v[74:77], v[106:109], v[46:49]
	v_mfma_f32_16x16x32_bf16 v[42:45], v[82:85], v[106:109], v[42:45]
	v_mfma_f32_16x16x32_bf16 v[38:41], v[74:77], v[114:117], v[38:41]
	v_mfma_f32_16x16x32_bf16 v[34:37], v[82:85], v[114:117], v[34:37]
	v_mfma_f32_16x16x32_bf16 v[62:65], v[78:81], v[94:97], v[62:65]
	v_mfma_f32_16x16x32_bf16 v[58:61], v[86:89], v[94:97], v[58:61]
	v_mfma_f32_16x16x32_bf16 v[54:57], v[78:81], v[102:105], v[54:57]
	v_mfma_f32_16x16x32_bf16 v[50:53], v[86:89], v[102:105], v[50:53]
	v_mfma_f32_16x16x32_bf16 v[46:49], v[78:81], v[110:113], v[46:49]
	v_mfma_f32_16x16x32_bf16 v[42:45], v[86:89], v[110:113], v[42:45]
	v_mfma_f32_16x16x32_bf16 v[38:41], v[78:81], v[118:121], v[38:41]
	v_mfma_f32_16x16x32_bf16 v[34:37], v[86:89], v[118:121], v[34:37]
	s_setprio 0
	s_setprio 1
	s_setprio 0
	s_barrier
	s_mov_b32 m0, s41
	v_lshl_add_u64 v[122:123], s[30:31], 0, v[0:1]
	global_load_lds_dwordx4 v[122:123], off
	v_lshl_add_u64 v[124:125], s[30:31], 0, v[66:67]
	s_mov_b32 m0, s42
	v_lshl_add_u64 v[126:127], s[34:35], 0, v[0:1]
	global_load_lds_dwordx4 v[124:125], off
	s_mov_b32 m0, s43
	v_lshl_add_u64 v[128:129], s[28:29], 0, v[68:69]
	global_load_lds_dwordx4 v[126:127], off
	v_lshl_add_u64 v[126:127], s[34:35], 0, v[66:67]
	s_mov_b32 m0, s44
	s_nop 0
	global_load_lds_dwordx4 v[126:127], off
	v_lshl_add_u64 v[126:127], s[28:29], 0, v[70:71]
	s_mov_b32 m0, s45
	s_nop 0
	global_load_lds_dwordx4 v[126:127], off
	s_mov_b32 m0, s46
	s_nop 0
	global_load_lds_dwordx4 v[128:129], off
	ds_read_b128 v[90:93], v72 offset:17408
	ds_read_b128 v[94:97], v72 offset:18432
	ds_read_b128 v[98:101], v72 offset:19456
	ds_read_b128 v[102:105], v72 offset:20480
	ds_read_b128 v[106:109], v72 offset:21504
	ds_read_b128 v[110:113], v72 offset:22528
	ds_read_b128 v[114:117], v72 offset:23552
	ds_read_b128 v[118:121], v72 offset:24576
	s_waitcnt vmcnt(8)
	s_waitcnt lgkmcnt(0)
	s_setprio 1
	s_barrier
	v_mfma_f32_16x16x32_bf16 v[30:33], v[74:77], v[90:93], v[30:33]
	v_mfma_f32_16x16x32_bf16 v[26:29], v[82:85], v[90:93], v[26:29]
	v_mfma_f32_16x16x32_bf16 v[22:25], v[74:77], v[98:101], v[22:25]
	v_mfma_f32_16x16x32_bf16 v[18:21], v[82:85], v[98:101], v[18:21]
	v_mfma_f32_16x16x32_bf16 v[14:17], v[74:77], v[106:109], v[14:17]
	v_mfma_f32_16x16x32_bf16 v[10:13], v[82:85], v[106:109], v[10:13]
	v_mfma_f32_16x16x32_bf16 v[6:9], v[74:77], v[114:117], v[6:9]
	v_mfma_f32_16x16x32_bf16 v[2:5], v[82:85], v[114:117], v[2:5]
	v_mfma_f32_16x16x32_bf16 v[30:33], v[78:81], v[94:97], v[30:33]
	v_mfma_f32_16x16x32_bf16 v[26:29], v[86:89], v[94:97], v[26:29]
	v_mfma_f32_16x16x32_bf16 v[22:25], v[78:81], v[102:105], v[22:25]
	v_mfma_f32_16x16x32_bf16 v[18:21], v[86:89], v[102:105], v[18:21]
	v_mfma_f32_16x16x32_bf16 v[14:17], v[78:81], v[110:113], v[14:17]
	v_mfma_f32_16x16x32_bf16 v[10:13], v[86:89], v[110:113], v[10:13]
	v_mfma_f32_16x16x32_bf16 v[6:9], v[78:81], v[118:121], v[6:9]
	v_mfma_f32_16x16x32_bf16 v[2:5], v[86:89], v[118:121], v[2:5]
	s_setprio 0
	s_setprio 1
	s_setprio 0
	s_barrier
; #define PG8_STAGE(bufoff, gbase, voff) do { _Pragma("unroll") for (int _i = 0; _i < 2; ++_i) \
;         __builtin_amdgcn_global_load_lds((const GAS unsigned*)((const GAS char*)(gbase) + (voff)[_i]), (LAS unsigned*)(lds + (bufoff) + ldsw + _i * 8192), 16, 0, 0); } while (0)
; #define PG8_LDA(dst, b, h) do { _Pragma("unroll") for (int m = 0; m < 4; ++m) _Pragma("unroll") for (int k = 0; k < 2; ++k) dst[m][k] = *(const LAS bf16x8*)(lds + PG8_SA(b, h) + aoff + m * 2048 + k * 1024); } while (0)
; #define PG8_LDB(dst, b, h) do { _Pragma("unroll") for (int n = 0; n < 2; ++n) _Pragma("unroll") for (int k = 0; k < 2; ++k) dst[n][k] = *(const LAS bf16x8*)(lds + PG8_SB(b, h) + boff + n * 2048 + k * 1024); } while (0)
; #define PG8_MMA(ai, bj, At, Bt) do { __builtin_amdgcn_s_setprio(1); _Pragma("unroll") for (int m = 0; m < 4; ++m) _Pragma("unroll") for (int n = 0; n < 2; ++n) _Pragma("unroll") for (int k = 0; k < 2; ++k) \
;         acc[ai][bj][m][n] = __builtin_amdgcn_mfma_f32_16x16x32_bf16(Bt[n][k], At[m][k], acc[ai][bj][m][n], 0, 0, 0); __builtin_amdgcn_s_setprio(0); } while (0)
; #define PG8_WAIT_V(n) asm volatile("s_waitcnt vmcnt(" #n ")" ::: "memory")
; #define PG8_WAIT_L(n) asm volatile("s_waitcnt lgkmcnt(" #n ")" ::: "memory")
; #define PG8_BAR __builtin_amdgcn_s_barrier()
; #define PG8_SCHED __builtin_amdgcn_sched_barrier(0)
; template <class Epi, class Sched, bool ALIGN_EPI>
; __device__ __forceinline__ void gemm_phase(LAS unsigned char* lds, const Gemm g, const Sched& S, const Epi& E, int wave_id) {
;     ...
;             PG8_LDB(B0, 1, 0); PG8_LDB(B1, 1, 1); PG8_SCHED; PG8_LDA(At, 1, 0); PG8_STAGE(PG8_SA(0, 1), a2 + hsA, voffA);
;             PG8_WAIT_V(8); PG8_WAIT_L(0); PG8_BAR; PG8_MMA(0, 0, At, B0); PG8_MMA(0, 1, At, B1); PG8_BAR; PG8_SCHED;
;             PG8_LDA(At, 1, 1); PG8_STAGE(PG8_SB(1, 0), b3, voffB); PG8_STAGE(PG8_SB(1, 1), b3 + hsB, voffB); PG8_STAGE(PG8_SA(1, 0), a3, voffA);
;             PG8_WAIT_V(8); PG8_WAIT_L(0); PG8_BAR; PG8_MMA(1, 0, At, B0); PG8_MMA(1, 1, At, B1); PG8_BAR; PG8_SCHED;
;         }
;         if constexpr (ALIGN_EPI) { if (wr == 0) PG8_BAR; }
	s_mov_b32 m0, s47
	v_lshl_add_u64 v[130:131], s[26:27], 0, v[70:71]
	global_load_lds_dwordx4 v[130:131], off
	v_lshl_add_u64 v[130:131], s[26:27], 0, v[68:69]
	s_mov_b32 m0, s48
	s_nop 0
	global_load_lds_dwordx4 v[130:131], off
	v_add_u32_e32 v86, 0x18400, v73
	ds_read_b128 v[74:77], v86
	ds_read_b128 v[78:81], v86 offset:1024
	ds_read_b128 v[82:85], v86 offset:2048
	ds_read_b128 v[86:89], v86 offset:3072
	ds_read_b128 v[90:93], v72 offset:33792
	ds_read_b128 v[94:97], v72 offset:34816
	ds_read_b128 v[98:101], v72 offset:35840
	ds_read_b128 v[102:105], v72 offset:36864
	ds_read_b128 v[106:109], v72 offset:37888
	ds_read_b128 v[110:113], v72 offset:38912
	ds_read_b128 v[114:117], v72 offset:39936
	ds_read_b128 v[118:121], v72 offset:40960
	s_waitcnt vmcnt(8)
	s_waitcnt lgkmcnt(0)
	s_setprio 1
	s_barrier
	v_mfma_f32_16x16x32_bf16 v[62:65], v[74:77], v[90:93], v[62:65]
	v_mfma_f32_16x16x32_bf16 v[58:61], v[82:85], v[90:93], v[58:61]
	v_mfma_f32_16x16x32_bf16 v[54:57], v[74:77], v[98:101], v[54:57]
	v_mfma_f32_16x16x32_bf16 v[50:53], v[82:85], v[98:101], v[50:53]
	v_mfma_f32_16x16x32_bf16 v[46:49], v[74:77], v[106:109], v[46:49]
	v_mfma_f32_16x16x32_bf16 v[42:45], v[82:85], v[106:109], v[42:45]
	v_mfma_f32_16x16x32_bf16 v[38:41], v[74:77], v[114:117], v[38:41]
	v_mfma_f32_16x16x32_bf16 v[34:37], v[82:85], v[114:117], v[34:37]
	v_mfma_f32_16x16x32_bf16 v[62:65], v[78:81], v[94:97], v[62:65]
	v_mfma_f32_16x16x32_bf16 v[58:61], v[86:89], v[94:97], v[58:61]
	v_mfma_f32_16x16x32_bf16 v[54:57], v[78:81], v[102:105], v[54:57]
	v_mfma_f32_16x16x32_bf16 v[50:53], v[86:89], v[102:105], v[50:53]
	v_mfma_f32_16x16x32_bf16 v[46:49], v[78:81], v[110:113], v[46:49]
	v_mfma_f32_16x16x32_bf16 v[42:45], v[86:89], v[110:113], v[42:45]
	v_mfma_f32_16x16x32_bf16 v[38:41], v[78:81], v[118:121], v[38:41]
	v_mfma_f32_16x16x32_bf16 v[34:37], v[86:89], v[118:121], v[34:37]
	s_setprio 0
	s_setprio 1
	s_setprio 0
	s_barrier
	s_mov_b32 m0, s51
	v_lshl_add_u64 v[122:123], v[122:123], 0, s[92:93]
	global_load_lds_dwordx4 v[122:123], off
	v_lshl_add_u64 v[122:123], v[124:125], 0, s[92:93]
	s_mov_b32 m0, s52
	s_nop 0
	global_load_lds_dwordx4 v[122:123], off
	v_lshl_add_u64 v[122:123], s[24:25], 0, v[0:1]
	s_mov_b32 m0, s55
	s_nop 0
	global_load_lds_dwordx4 v[122:123], off
	v_lshl_add_u64 v[122:123], s[24:25], 0, v[66:67]
	s_mov_b32 m0, s56
	s_nop 0
	global_load_lds_dwordx4 v[122:123], off
	v_lshl_add_u64 v[122:123], v[126:127], 0, s[92:93]
	s_mov_b32 m0, s53
	s_nop 0
	global_load_lds_dwordx4 v[122:123], off
	v_lshl_add_u64 v[122:123], v[128:129], 0, s[92:93]
	s_mov_b32 m0, s54
	s_nop 0
	global_load_lds_dwordx4 v[122:123], off
	ds_read_b128 v[90:93], v72 offset:50176
	ds_read_b128 v[94:97], v72 offset:51200
	ds_read_b128 v[98:101], v72 offset:52224
	ds_read_b128 v[102:105], v72 offset:53248
	ds_read_b128 v[106:109], v72 offset:54272
	ds_read_b128 v[110:113], v72 offset:55296
	ds_read_b128 v[114:117], v72 offset:56320
	ds_read_b128 v[118:121], v72 offset:57344
	s_waitcnt vmcnt(8)
	s_waitcnt lgkmcnt(0)
	s_setprio 1
	s_barrier
	v_mfma_f32_16x16x32_bf16 v[30:33], v[74:77], v[90:93], v[30:33]
	v_mfma_f32_16x16x32_bf16 v[26:29], v[82:85], v[90:93], v[26:29]
	v_mfma_f32_16x16x32_bf16 v[22:25], v[74:77], v[98:101], v[22:25]
	v_mfma_f32_16x16x32_bf16 v[18:21], v[82:85], v[98:101], v[18:21]
	v_mfma_f32_16x16x32_bf16 v[14:17], v[74:77], v[106:109], v[14:17]
	v_mfma_f32_16x16x32_bf16 v[10:13], v[82:85], v[106:109], v[10:13]
	v_mfma_f32_16x16x32_bf16 v[6:9], v[74:77], v[114:117], v[6:9]
	v_mfma_f32_16x16x32_bf16 v[2:5], v[82:85], v[114:117], v[2:5]
	v_mfma_f32_16x16x32_bf16 v[30:33], v[78:81], v[94:97], v[30:33]
	v_mfma_f32_16x16x32_bf16 v[26:29], v[86:89], v[94:97], v[26:29]
	v_mfma_f32_16x16x32_bf16 v[22:25], v[78:81], v[102:105], v[22:25]
	v_mfma_f32_16x16x32_bf16 v[18:21], v[86:89], v[102:105], v[18:21]
	v_mfma_f32_16x16x32_bf16 v[14:17], v[78:81], v[110:113], v[14:17]
	v_mfma_f32_16x16x32_bf16 v[10:13], v[86:89], v[110:113], v[10:13]
	v_mfma_f32_16x16x32_bf16 v[6:9], v[78:81], v[118:121], v[6:9]
	v_mfma_f32_16x16x32_bf16 v[2:5], v[86:89], v[118:121], v[2:5]
	s_setprio 0
	s_setprio 1
	s_setprio 0
	s_barrier
	s_andn2_b64 vcc, exec, s[22:23]
	s_mov_b64 s[24:25], -1
	s_mov_b64 s[22:23], 0
	s_mov_b64 s[26:27], 0x100
	s_cbranch_vccz .LBB0_1335
	s_and_b64 vcc, exec, s[14:15]
	s_cbranch_vccz .LBB0_1338
	s_barrier

; #define GAS __attribute__((address_space(1)))
; #define PG8_STAGE(bufoff, gbase, voff) do { _Pragma("unroll") for (int _i = 0; _i < 2; ++_i) \
;         __builtin_amdgcn_global_load_lds((const GAS unsigned*)((const GAS char*)(gbase) + (voff)[_i]), (LAS unsigned*)(lds + (bufoff) + ldsw + _i * 8192), 16, 0, 0); } while (0)
; #define PG8_LDA(dst, b, h) do { _Pragma("unroll") for (int m = 0; m < 4; ++m) _Pragma("unroll") for (int k = 0; k < 2; ++k) dst[m][k] = *(const LAS bf16x8*)(lds + PG8_SA(b, h) + aoff + m * 2048 + k * 1024); } while (0)
; #define PG8_LDB(dst, b, h) do { _Pragma("unroll") for (int n = 0; n < 2; ++n) _Pragma("unroll") for (int k = 0; k < 2; ++k) dst[n][k] = *(const LAS bf16x8*)(lds + PG8_SB(b, h) + boff + n * 2048 + k * 1024); } while (0)
; #define PG8_MMA(ai, bj, At, Bt) do { __builtin_amdgcn_s_setprio(1); _Pragma("unroll") for (int m = 0; m < 4; ++m) _Pragma("unroll") for (int n = 0; n < 2; ++n) _Pragma("unroll") for (int k = 0; k < 2; ++k) \
;         acc[ai][bj][m][n] = __builtin_amdgcn_mfma_f32_16x16x32_bf16(Bt[n][k], At[m][k], acc[ai][bj][m][n], 0, 0, 0); __builtin_amdgcn_s_setprio(0); } while (0)
; #define PG8_WAIT_V(n) asm volatile("s_waitcnt vmcnt(" #n ")" ::: "memory")
; #define PG8_WAIT_L(n) asm volatile("s_waitcnt lgkmcnt(" #n ")" ::: "memory")
; #define PG8_BAR __builtin_amdgcn_s_barrier()
; template <class Epi, class Sched, bool ALIGN_EPI>
; __device__ __forceinline__ void gemm_phase(LAS unsigned char* lds, const Gemm g, const Sched& S, const Epi& E, int wave_id) {
;     ...
;             const bool last = (t == nt - 2);
;             const GAS char* a1 = cA + (size_t)(t + 1) * kstep;
;             const GAS char* a2 = last ? nA : cA + (size_t)(t + 2) * kstep; const GAS char* b2 = last ? nB : cB + (size_t)(t + 2) * kstep;
;             const GAS char* a3 = a2 + kstep; const GAS char* b3 = b2 + kstep;
;             PG8_LDB(B0, 0, 0); PG8_LDB(B1, 0, 1); PG8_SCHED; PG8_LDA(At, 0, 0); PG8_STAGE(PG8_SA(1, 1), a1 + hsA, voffA);
;             PG8_WAIT_V(8); PG8_WAIT_L(0); PG8_BAR; PG8_MMA(0, 0, At, B0); PG8_MMA(0, 1, At, B1); PG8_BAR; PG8_SCHED;
;             PG8_LDA(At, 0, 1); PG8_STAGE(PG8_SB(0, 0), b2, voffB); PG8_STAGE(PG8_SB(0, 1), b2 + hsB, voffB); PG8_STAGE(PG8_SA(0, 0), a2, voffA);
;             PG8_WAIT_V(8); PG8_WAIT_L(0); PG8_BAR; PG8_MMA(1, 0, At, B0); PG8_MMA(1, 1, At, B1); PG8_BAR; PG8_SCHED;
.LBB0_1458:
	s_add_u32 s21, s26, s34
	s_addc_u32 s33, s27, s35
	s_add_u32 s38, s21, 0x100
	s_addc_u32 s39, s33, 0
	s_and_b64 s[36:37], s[30:31], exec
	s_cselect_b32 s37, s3, s39
	s_cselect_b32 s36, s5, s38
	s_add_u32 s34, s6, s34
	s_addc_u32 s35, s7, s35
	s_add_u32 s34, s34, 0x100
	s_addc_u32 s35, s35, 0
	s_and_b64 s[30:31], s[30:31], exec
	s_cselect_b32 s39, s9, s35
	s_cselect_b32 s38, s19, s34
	s_add_u32 s42, s21, 0x10080
	s_addc_u32 s43, s33, 0
	s_add_i32 m0, s49, 0xc400
	s_add_i32 s21, s49, 0xe400
	s_add_u32 s40, s38, 0x10000
	s_addc_u32 s41, s39, 0
	s_add_u32 s34, s36, 0x10000
	s_addc_u32 s35, s37, 0
	s_add_u32 s30, s38, 0x10080
	s_addc_u32 s31, s39, 0
	v_lshl_add_u64 v[2:3], s[42:43], 0, v[140:141]
	global_load_lds_dwordx4 v[2:3], off
	v_lshl_add_u64 v[2:3], s[42:43], 0, v[144:145]
	s_mov_b32 m0, s21
	s_nop 0
	global_load_lds_dwordx4 v[2:3], off
	v_add_u32_e32 v0, 0x10400, v159
	ds_read_b128 v[100:103], v0
	ds_read_b128 v[108:111], v0 offset:1024
	ds_read_b128 v[148:151], v0 offset:2048
	ds_read_b128 v[152:155], v0 offset:3072
	v_add_u32_e32 v0, 0x14400, v159
	ds_read_b128 v[160:163], v0
	ds_read_b128 v[164:167], v0 offset:1024
	ds_read_b128 v[168:171], v0 offset:2048
	ds_read_b128 v[172:175], v0 offset:3072
	ds_read_b128 v[176:179], v158 offset:1024
	ds_read_b128 v[180:183], v158 offset:2048
	ds_read_b128 v[184:187], v158 offset:3072
	ds_read_b128 v[188:191], v158 offset:4096
	ds_read_b128 v[192:195], v158 offset:5120
	ds_read_b128 v[196:199], v158 offset:6144
	ds_read_b128 v[200:203], v158 offset:7168
	ds_read_b128 v[204:207], v158 offset:8192
	s_waitcnt vmcnt(8)
	s_waitcnt lgkmcnt(0)
	s_setprio 1
	s_barrier
	v_mfma_f32_16x16x32_bf16 v[136:139], v[100:103], v[176:179], v[136:139]
	v_mfma_f32_16x16x32_bf16 v[132:135], v[148:151], v[176:179], v[132:135]
	v_mfma_f32_16x16x32_bf16 v[128:131], v[100:103], v[184:187], v[128:131]
	v_mfma_f32_16x16x32_bf16 v[124:127], v[148:151], v[184:187], v[124:127]
	v_mfma_f32_16x16x32_bf16 v[120:123], v[100:103], v[192:195], v[120:123]
	v_mfma_f32_16x16x32_bf16 v[116:119], v[148:151], v[192:195], v[116:119]
	v_mfma_f32_16x16x32_bf16 v[112:115], v[100:103], v[200:203], v[112:115]
	v_mfma_f32_16x16x32_bf16 v[104:107], v[148:151], v[200:203], v[104:107]
	v_mfma_f32_16x16x32_bf16 v[136:139], v[108:111], v[180:183], v[136:139]
	v_mfma_f32_16x16x32_bf16 v[132:135], v[152:155], v[180:183], v[132:135]
	v_mfma_f32_16x16x32_bf16 v[128:131], v[108:111], v[188:191], v[128:131]
	v_mfma_f32_16x16x32_bf16 v[124:127], v[152:155], v[188:191], v[124:127]
	v_mfma_f32_16x16x32_bf16 v[120:123], v[108:111], v[196:199], v[120:123]
	v_mfma_f32_16x16x32_bf16 v[116:119], v[152:155], v[196:199], v[116:119]
	v_mfma_f32_16x16x32_bf16 v[112:115], v[108:111], v[204:207], v[112:115]
	v_mfma_f32_16x16x32_bf16 v[104:107], v[152:155], v[204:207], v[104:107]
	s_setprio 0
	s_setprio 1
	v_mfma_f32_16x16x32_bf16 v[64:67], v[160:163], v[176:179], v[64:67]
	v_mfma_f32_16x16x32_bf16 v[60:63], v[168:171], v[176:179], v[60:63]
	v_mfma_f32_16x16x32_bf16 v[56:59], v[160:163], v[184:187], v[56:59]
	v_mfma_f32_16x16x32_bf16 v[52:55], v[168:171], v[184:187], v[52:55]
	v_mfma_f32_16x16x32_bf16 v[48:51], v[160:163], v[192:195], v[48:51]
	v_mfma_f32_16x16x32_bf16 v[44:47], v[168:171], v[192:195], v[44:47]
	v_mfma_f32_16x16x32_bf16 v[40:43], v[160:163], v[200:203], v[40:43]
	v_mfma_f32_16x16x32_bf16 v[36:39], v[168:171], v[200:203], v[36:39]
	v_mfma_f32_16x16x32_bf16 v[64:67], v[164:167], v[180:183], v[64:67]
	v_mfma_f32_16x16x32_bf16 v[60:63], v[172:175], v[180:183], v[60:63]
	v_mfma_f32_16x16x32_bf16 v[56:59], v[164:167], v[188:191], v[56:59]
	v_mfma_f32_16x16x32_bf16 v[52:55], v[172:175], v[188:191], v[52:55]
	v_mfma_f32_16x16x32_bf16 v[48:51], v[164:167], v[196:199], v[48:51]
	v_mfma_f32_16x16x32_bf16 v[44:47], v[172:175], v[196:199], v[44:47]
	v_mfma_f32_16x16x32_bf16 v[40:43], v[164:167], v[204:207], v[40:43]
	v_mfma_f32_16x16x32_bf16 v[36:39], v[172:175], v[204:207], v[36:39]
	s_setprio 0
	s_barrier
	s_mov_b32 m0, s50
	v_lshl_add_u64 v[156:157], s[38:39], 0, v[142:143]
	global_load_lds_dwordx4 v[156:157], off
	v_lshl_add_u64 v[208:209], s[38:39], 0, v[146:147]
	s_mov_b32 m0, s51
	v_lshl_add_u64 v[2:3], s[40:41], 0, v[142:143]
	global_load_lds_dwordx4 v[208:209], off
	s_mov_b32 m0, s52
	v_lshl_add_u64 v[210:211], s[36:37], 0, v[140:141]
	global_load_lds_dwordx4 v[2:3], off
	v_lshl_add_u64 v[2:3], s[40:41], 0, v[146:147]
	s_mov_b32 m0, s53
	v_lshl_add_u64 v[212:213], s[36:37], 0, v[144:145]
	global_load_lds_dwordx4 v[2:3], off
	s_mov_b32 m0, s54
	s_nop 0
	global_load_lds_dwordx4 v[210:211], off
	s_mov_b32 m0, s55
	s_nop 0
	global_load_lds_dwordx4 v[212:213], off
	ds_read_b128 v[176:179], v158 offset:17408
	ds_read_b128 v[180:183], v158 offset:18432
	ds_read_b128 v[184:187], v158 offset:19456
	ds_read_b128 v[188:191], v158 offset:20480
	ds_read_b128 v[192:195], v158 offset:21504
	ds_read_b128 v[196:199], v158 offset:22528
	ds_read_b128 v[200:203], v158 offset:23552
	ds_read_b128 v[204:207], v158 offset:24576
	s_waitcnt vmcnt(8)
	s_waitcnt lgkmcnt(0)
	s_setprio 1
	s_barrier
; #define PG8_STAGE(bufoff, gbase, voff) do { _Pragma("unroll") for (int _i = 0; _i < 2; ++_i) \
;         __builtin_amdgcn_global_load_lds((const GAS unsigned*)((const GAS char*)(gbase) + (voff)[_i]), (LAS unsigned*)(lds + (bufoff) + ldsw + _i * 8192), 16, 0, 0); } while (0)
; #define PG8_LDA(dst, b, h) do { _Pragma("unroll") for (int m = 0; m < 4; ++m) _Pragma("unroll") for (int k = 0; k < 2; ++k) dst[m][k] = *(const LAS bf16x8*)(lds + PG8_SA(b, h) + aoff + m * 2048 + k * 1024); } while (0)
; #define PG8_LDB(dst, b, h) do { _Pragma("unroll") for (int n = 0; n < 2; ++n) _Pragma("unroll") for (int k = 0; k < 2; ++k) dst[n][k] = *(const LAS bf16x8*)(lds + PG8_SB(b, h) + boff + n * 2048 + k * 1024); } while (0)
; #define PG8_MMA(ai, bj, At, Bt) do { __builtin_amdgcn_s_setprio(1); _Pragma("unroll") for (int m = 0; m < 4; ++m) _Pragma("unroll") for (int n = 0; n < 2; ++n) _Pragma("unroll") for (int k = 0; k < 2; ++k) \
;         acc[ai][bj][m][n] = __builtin_amdgcn_mfma_f32_16x16x32_bf16(Bt[n][k], At[m][k], acc[ai][bj][m][n], 0, 0, 0); __builtin_amdgcn_s_setprio(0); } while (0)
; #define PG8_WAIT_V(n) asm volatile("s_waitcnt vmcnt(" #n ")" ::: "memory")
; #define PG8_WAIT_L(n) asm volatile("s_waitcnt lgkmcnt(" #n ")" ::: "memory")
; #define PG8_BAR __builtin_amdgcn_s_barrier()
; #define PG8_SCHED __builtin_amdgcn_sched_barrier(0)
; template <class Epi, class Sched, bool ALIGN_EPI>
; __device__ __forceinline__ void gemm_phase(LAS unsigned char* lds, const Gemm g, const Sched& S, const Epi& E, int wave_id) {
;     ...
;             PG8_WAIT_V(8); PG8_WAIT_L(0); PG8_BAR; PG8_MMA(1, 0, At, B0); PG8_MMA(1, 1, At, B1); PG8_BAR; PG8_SCHED;
;             PG8_LDB(B0, 1, 0); PG8_LDB(B1, 1, 1); PG8_SCHED; PG8_LDA(At, 1, 0); PG8_STAGE(PG8_SA(0, 1), a2 + hsA, voffA);
;             PG8_WAIT_V(8); PG8_WAIT_L(0); PG8_BAR; PG8_MMA(0, 0, At, B0); PG8_MMA(0, 1, At, B1); PG8_BAR; PG8_SCHED;
	v_mfma_f32_16x16x32_bf16 v[96:99], v[100:103], v[176:179], v[96:99]
	v_mfma_f32_16x16x32_bf16 v[92:95], v[148:151], v[176:179], v[92:95]
	v_mfma_f32_16x16x32_bf16 v[88:91], v[100:103], v[184:187], v[88:91]
	v_mfma_f32_16x16x32_bf16 v[84:87], v[148:151], v[184:187], v[84:87]
	v_mfma_f32_16x16x32_bf16 v[80:83], v[100:103], v[192:195], v[80:83]
	v_mfma_f32_16x16x32_bf16 v[76:79], v[148:151], v[192:195], v[76:79]
	v_mfma_f32_16x16x32_bf16 v[72:75], v[100:103], v[200:203], v[72:75]
	v_mfma_f32_16x16x32_bf16 v[68:71], v[148:151], v[200:203], v[68:71]
	v_mfma_f32_16x16x32_bf16 v[96:99], v[108:111], v[180:183], v[96:99]
	v_mfma_f32_16x16x32_bf16 v[92:95], v[152:155], v[180:183], v[92:95]
	v_mfma_f32_16x16x32_bf16 v[88:91], v[108:111], v[188:191], v[88:91]
	v_mfma_f32_16x16x32_bf16 v[84:87], v[152:155], v[188:191], v[84:87]
	v_mfma_f32_16x16x32_bf16 v[80:83], v[108:111], v[196:199], v[80:83]
	v_mfma_f32_16x16x32_bf16 v[76:79], v[152:155], v[196:199], v[76:79]
	v_mfma_f32_16x16x32_bf16 v[72:75], v[108:111], v[204:207], v[72:75]
	v_mfma_f32_16x16x32_bf16 v[68:71], v[152:155], v[204:207], v[68:71]
	s_setprio 0
	s_setprio 1
	v_mfma_f32_16x16x32_bf16 v[32:35], v[160:163], v[176:179], v[32:35]
	v_mfma_f32_16x16x32_bf16 v[28:31], v[168:171], v[176:179], v[28:31]
	v_mfma_f32_16x16x32_bf16 v[24:27], v[160:163], v[184:187], v[24:27]
	v_mfma_f32_16x16x32_bf16 v[20:23], v[168:171], v[184:187], v[20:23]
	v_mfma_f32_16x16x32_bf16 v[16:19], v[160:163], v[192:195], v[16:19]
	v_mfma_f32_16x16x32_bf16 v[12:15], v[168:171], v[192:195], v[12:15]
	v_mfma_f32_16x16x32_bf16 v[8:11], v[160:163], v[200:203], v[8:11]
	v_mfma_f32_16x16x32_bf16 v[2:5], v[168:171], v[200:203], v[4:7]
	v_mfma_f32_16x16x32_bf16 v[32:35], v[164:167], v[180:183], v[32:35]
	v_mfma_f32_16x16x32_bf16 v[28:31], v[172:175], v[180:183], v[28:31]
	v_mfma_f32_16x16x32_bf16 v[24:27], v[164:167], v[188:191], v[24:27]
	v_mfma_f32_16x16x32_bf16 v[20:23], v[172:175], v[188:191], v[20:23]
	v_mfma_f32_16x16x32_bf16 v[16:19], v[164:167], v[196:199], v[16:19]
	v_mfma_f32_16x16x32_bf16 v[12:15], v[172:175], v[196:199], v[12:15]
	v_mfma_f32_16x16x32_bf16 v[8:11], v[164:167], v[204:207], v[8:11]
	v_mfma_f32_16x16x32_bf16 v[2:5], v[172:175], v[204:207], v[2:5]
	s_setprio 0
	s_barrier
	s_mov_b32 m0, s56
	v_lshl_add_u64 v[6:7], s[34:35], 0, v[140:141]
	global_load_lds_dwordx4 v[6:7], off
	v_lshl_add_u64 v[6:7], s[34:35], 0, v[144:145]
	s_mov_b32 m0, s57
	s_nop 0
	global_load_lds_dwordx4 v[6:7], off
	v_add_u32_e32 v0, 0x18400, v159
	ds_read_b128 v[100:103], v0
	ds_read_b128 v[108:111], v0 offset:1024
	ds_read_b128 v[148:151], v0 offset:2048
	ds_read_b128 v[152:155], v0 offset:3072
	v_add_u32_e32 v0, 0x1c400, v159
	ds_read_b128 v[160:163], v0
	ds_read_b128 v[164:167], v0 offset:1024
	ds_read_b128 v[168:171], v0 offset:2048
	ds_read_b128 v[172:175], v0 offset:3072
	ds_read_b128 v[176:179], v158 offset:33792
	ds_read_b128 v[180:183], v158 offset:34816
	ds_read_b128 v[184:187], v158 offset:35840
	ds_read_b128 v[188:191], v158 offset:36864
	ds_read_b128 v[192:195], v158 offset:37888
	ds_read_b128 v[196:199], v158 offset:38912
	ds_read_b128 v[200:203], v158 offset:39936
	ds_read_b128 v[204:207], v158 offset:40960
	s_waitcnt vmcnt(8)
	s_waitcnt lgkmcnt(0)
	s_setprio 1
	s_barrier
	v_mfma_f32_16x16x32_bf16 v[136:139], v[100:103], v[176:179], v[136:139]
	v_mfma_f32_16x16x32_bf16 v[132:135], v[148:151], v[176:179], v[132:135]
	v_mfma_f32_16x16x32_bf16 v[128:131], v[100:103], v[184:187], v[128:131]
	v_mfma_f32_16x16x32_bf16 v[124:127], v[148:151], v[184:187], v[124:127]
	v_mfma_f32_16x16x32_bf16 v[120:123], v[100:103], v[192:195], v[120:123]
	v_mfma_f32_16x16x32_bf16 v[116:119], v[148:151], v[192:195], v[116:119]
	v_mfma_f32_16x16x32_bf16 v[112:115], v[100:103], v[200:203], v[112:115]
	v_mfma_f32_16x16x32_bf16 v[104:107], v[148:151], v[200:203], v[104:107]
	v_mfma_f32_16x16x32_bf16 v[136:139], v[108:111], v[180:183], v[136:139]
	v_mfma_f32_16x16x32_bf16 v[132:135], v[152:155], v[180:183], v[132:135]
	v_mfma_f32_16x16x32_bf16 v[128:131], v[108:111], v[188:191], v[128:131]
	v_mfma_f32_16x16x32_bf16 v[124:127], v[152:155], v[188:191], v[124:127]
	v_mfma_f32_16x16x32_bf16 v[120:123], v[108:111], v[196:199], v[120:123]
	v_mfma_f32_16x16x32_bf16 v[116:119], v[152:155], v[196:199], v[116:119]
	v_mfma_f32_16x16x32_bf16 v[112:115], v[108:111], v[204:207], v[112:115]
	v_mfma_f32_16x16x32_bf16 v[104:107], v[152:155], v[204:207], v[104:107]
	s_setprio 0
	s_setprio 1
	v_mfma_f32_16x16x32_bf16 v[64:67], v[160:163], v[176:179], v[64:67]
	v_mfma_f32_16x16x32_bf16 v[60:63], v[168:171], v[176:179], v[60:63]
	v_mfma_f32_16x16x32_bf16 v[56:59], v[160:163], v[184:187], v[56:59]
	v_mfma_f32_16x16x32_bf16 v[52:55], v[168:171], v[184:187], v[52:55]
	v_mfma_f32_16x16x32_bf16 v[48:51], v[160:163], v[192:195], v[48:51]
	v_mfma_f32_16x16x32_bf16 v[44:47], v[168:171], v[192:195], v[44:47]
	v_mfma_f32_16x16x32_bf16 v[40:43], v[160:163], v[200:203], v[40:43]
	v_mfma_f32_16x16x32_bf16 v[36:39], v[168:171], v[200:203], v[36:39]
	v_mfma_f32_16x16x32_bf16 v[64:67], v[164:167], v[180:183], v[64:67]
	v_mfma_f32_16x16x32_bf16 v[60:63], v[172:175], v[180:183], v[60:63]
	v_mfma_f32_16x16x32_bf16 v[56:59], v[164:167], v[188:191], v[56:59]
	v_mfma_f32_16x16x32_bf16 v[52:55], v[172:175], v[188:191], v[52:55]
	v_mfma_f32_16x16x32_bf16 v[48:51], v[164:167], v[196:199], v[48:51]
	v_mfma_f32_16x16x32_bf16 v[44:47], v[172:175], v[196:199], v[44:47]
	v_mfma_f32_16x16x32_bf16 v[40:43], v[164:167], v[204:207], v[40:43]
	v_mfma_f32_16x16x32_bf16 v[36:39], v[172:175], v[204:207], v[36:39]
	s_setprio 0
	s_barrier
; #define PG8_STAGE(bufoff, gbase, voff) do { _Pragma("unroll") for (int _i = 0; _i < 2; ++_i) \
;         __builtin_amdgcn_global_load_lds((const GAS unsigned*)((const GAS char*)(gbase) + (voff)[_i]), (LAS unsigned*)(lds + (bufoff) + ldsw + _i * 8192), 16, 0, 0); } while (0)
; #define PG8_LDA(dst, b, h) do { _Pragma("unroll") for (int m = 0; m < 4; ++m) _Pragma("unroll") for (int k = 0; k < 2; ++k) dst[m][k] = *(const LAS bf16x8*)(lds + PG8_SA(b, h) + aoff + m * 2048 + k * 1024); } while (0)
; #define PG8_MMA(ai, bj, At, Bt) do { __builtin_amdgcn_s_setprio(1); _Pragma("unroll") for (int m = 0; m < 4; ++m) _Pragma("unroll") for (int n = 0; n < 2; ++n) _Pragma("unroll") for (int k = 0; k < 2; ++k) \
;         acc[ai][bj][m][n] = __builtin_amdgcn_mfma_f32_16x16x32_bf16(Bt[n][k], At[m][k], acc[ai][bj][m][n], 0, 0, 0); __builtin_amdgcn_s_setprio(0); } while (0)
; #define PG8_WAIT_V(n) asm volatile("s_waitcnt vmcnt(" #n ")" ::: "memory")
; #define PG8_WAIT_L(n) asm volatile("s_waitcnt lgkmcnt(" #n ")" ::: "memory")
; #define PG8_BAR __builtin_amdgcn_s_barrier()
; #define PG8_SCHED __builtin_amdgcn_sched_barrier(0)
; template <class Epi, class Sched, bool ALIGN_EPI>
; __device__ __forceinline__ void gemm_phase(LAS unsigned char* lds, const Gemm g, const Sched& S, const Epi& E, int wave_id) {
;     ...
;             PG8_LDA(At, 1, 1); PG8_STAGE(PG8_SB(1, 0), b3, voffB); PG8_STAGE(PG8_SB(1, 1), b3 + hsB, voffB); PG8_STAGE(PG8_SA(1, 0), a3, voffA);
;             PG8_WAIT_V(8); PG8_WAIT_L(0); PG8_BAR; PG8_MMA(1, 0, At, B0); PG8_MMA(1, 1, At, B1); PG8_BAR; PG8_SCHED;
;         }
;         if constexpr (ALIGN_EPI) { if (wr == 0) PG8_BAR; }
	s_mov_b32 m0, s63
	v_lshl_add_u64 v[6:7], v[156:157], 0, s[92:93]
	global_load_lds_dwordx4 v[6:7], off
	v_lshl_add_u64 v[6:7], v[208:209], 0, s[92:93]
	s_mov_b32 m0, s64
	s_nop 0
	global_load_lds_dwordx4 v[6:7], off
	v_lshl_add_u64 v[6:7], s[30:31], 0, v[142:143]
	s_mov_b32 m0, s67
	s_nop 0
	global_load_lds_dwordx4 v[6:7], off
	v_lshl_add_u64 v[6:7], s[30:31], 0, v[146:147]
	s_mov_b32 m0, s72
	s_nop 0
	global_load_lds_dwordx4 v[6:7], off
	v_lshl_add_u64 v[6:7], v[210:211], 0, s[92:93]
	s_mov_b32 m0, s65
	s_nop 0
	global_load_lds_dwordx4 v[6:7], off
	v_lshl_add_u64 v[6:7], v[212:213], 0, s[92:93]
	s_mov_b32 m0, s66
	s_nop 0
	global_load_lds_dwordx4 v[6:7], off
	ds_read_b128 v[176:179], v158 offset:50176
	ds_read_b128 v[180:183], v158 offset:51200
	ds_read_b128 v[184:187], v158 offset:52224
	ds_read_b128 v[188:191], v158 offset:53248
	ds_read_b128 v[192:195], v158 offset:54272
	ds_read_b128 v[196:199], v158 offset:55296
	ds_read_b128 v[200:203], v158 offset:56320
	ds_read_b128 v[204:207], v158 offset:57344
	s_waitcnt vmcnt(8)
	s_waitcnt lgkmcnt(0)
	s_setprio 1
	s_barrier
	v_mfma_f32_16x16x32_bf16 v[96:99], v[100:103], v[176:179], v[96:99]
	v_mfma_f32_16x16x32_bf16 v[92:95], v[148:151], v[176:179], v[92:95]
	v_mfma_f32_16x16x32_bf16 v[88:91], v[100:103], v[184:187], v[88:91]
	v_mfma_f32_16x16x32_bf16 v[84:87], v[148:151], v[184:187], v[84:87]
	v_mfma_f32_16x16x32_bf16 v[80:83], v[100:103], v[192:195], v[80:83]
	v_mfma_f32_16x16x32_bf16 v[76:79], v[148:151], v[192:195], v[76:79]
	v_mfma_f32_16x16x32_bf16 v[72:75], v[100:103], v[200:203], v[72:75]
	v_mfma_f32_16x16x32_bf16 v[68:71], v[148:151], v[200:203], v[68:71]
	v_mfma_f32_16x16x32_bf16 v[96:99], v[108:111], v[180:183], v[96:99]
	v_mfma_f32_16x16x32_bf16 v[92:95], v[152:155], v[180:183], v[92:95]
	v_mfma_f32_16x16x32_bf16 v[88:91], v[108:111], v[188:191], v[88:91]
	v_mfma_f32_16x16x32_bf16 v[84:87], v[152:155], v[188:191], v[84:87]
	v_mfma_f32_16x16x32_bf16 v[80:83], v[108:111], v[196:199], v[80:83]
	v_mfma_f32_16x16x32_bf16 v[76:79], v[152:155], v[196:199], v[76:79]
	v_mfma_f32_16x16x32_bf16 v[72:75], v[108:111], v[204:207], v[72:75]
	v_mfma_f32_16x16x32_bf16 v[68:71], v[152:155], v[204:207], v[68:71]
	s_setprio 0
	s_setprio 1
	v_mfma_f32_16x16x32_bf16 v[32:35], v[160:163], v[176:179], v[32:35]
	v_mfma_f32_16x16x32_bf16 v[28:31], v[168:171], v[176:179], v[28:31]
	v_mfma_f32_16x16x32_bf16 v[24:27], v[160:163], v[184:187], v[24:27]
	v_mfma_f32_16x16x32_bf16 v[20:23], v[168:171], v[184:187], v[20:23]
	v_mfma_f32_16x16x32_bf16 v[16:19], v[160:163], v[192:195], v[16:19]
	v_mfma_f32_16x16x32_bf16 v[12:15], v[168:171], v[192:195], v[12:15]
	v_mfma_f32_16x16x32_bf16 v[6:9], v[160:163], v[200:203], v[8:11]
	v_mfma_f32_16x16x32_bf16 v[2:5], v[168:171], v[200:203], v[2:5]
	v_mfma_f32_16x16x32_bf16 v[32:35], v[164:167], v[180:183], v[32:35]
	v_mfma_f32_16x16x32_bf16 v[28:31], v[172:175], v[180:183], v[28:31]
	v_mfma_f32_16x16x32_bf16 v[24:27], v[164:167], v[188:191], v[24:27]
	v_mfma_f32_16x16x32_bf16 v[20:23], v[172:175], v[188:191], v[20:23]
	v_mfma_f32_16x16x32_bf16 v[16:19], v[164:167], v[196:199], v[16:19]
	v_mfma_f32_16x16x32_bf16 v[12:15], v[172:175], v[196:199], v[12:15]
	v_mfma_f32_16x16x32_bf16 v[8:11], v[164:167], v[204:207], v[6:9]
	v_mfma_f32_16x16x32_bf16 v[4:7], v[172:175], v[204:207], v[2:5]
	s_setprio 0
	s_barrier
	s_andn2_b64 vcc, exec, s[28:29]
	s_mov_b64 s[30:31], -1
	s_mov_b64 s[28:29], 0
	s_mov_b64 s[34:35], 0x100
	s_cbranch_vccz .LBB0_1458
	s_and_b64 vcc, exec, s[16:17]
	s_cbranch_vccz .LBB0_1461
	s_barrier

; #define GAS __attribute__((address_space(1)))
; #define PG8_STAGE(bufoff, gbase, voff) do { _Pragma("unroll") for (int _i = 0; _i < 2; ++_i) \
;         __builtin_amdgcn_global_load_lds((const GAS unsigned*)((const GAS char*)(gbase) + (voff)[_i]), (LAS unsigned*)(lds + (bufoff) + ldsw + _i * 8192), 16, 0, 0); } while (0)
; #define PG8_LDA(dst, b, h) do { _Pragma("unroll") for (int m = 0; m < 4; ++m) _Pragma("unroll") for (int k = 0; k < 2; ++k) dst[m][k] = *(const LAS bf16x8*)(lds + PG8_SA(b, h) + aoff + m * 2048 + k * 1024); } while (0)
; #define PG8_LDB(dst, b, h) do { _Pragma("unroll") for (int n = 0; n < 2; ++n) _Pragma("unroll") for (int k = 0; k < 2; ++k) dst[n][k] = *(const LAS bf16x8*)(lds + PG8_SB(b, h) + boff + n * 2048 + k * 1024); } while (0)
; #define PG8_MMA(ai, bj, At, Bt) do { __builtin_amdgcn_s_setprio(1); _Pragma("unroll") for (int m = 0; m < 4; ++m) _Pragma("unroll") for (int n = 0; n < 2; ++n) _Pragma("unroll") for (int k = 0; k < 2; ++k) \
;         acc[ai][bj][m][n] = __builtin_amdgcn_mfma_f32_16x16x32_bf16(Bt[n][k], At[m][k], acc[ai][bj][m][n], 0, 0, 0); __builtin_amdgcn_s_setprio(0); } while (0)
; #define PG8_WAIT_V(n) asm volatile("s_waitcnt vmcnt(" #n ")" ::: "memory")
; #define PG8_WAIT_L(n) asm volatile("s_waitcnt lgkmcnt(" #n ")" ::: "memory")
; #define PG8_BAR __builtin_amdgcn_s_barrier()
; template <class Epi, class Sched, bool ALIGN_EPI>
; __device__ __forceinline__ void gemm_phase(LAS unsigned char* lds, const Gemm g, const Sched& S, const Epi& E, int wave_id) {
;     ...
;             const bool last = (t == nt - 2);
;             const GAS char* a1 = cA + (size_t)(t + 1) * kstep;
;             const GAS char* a2 = last ? nA : cA + (size_t)(t + 2) * kstep; const GAS char* b2 = last ? nB : cB + (size_t)(t + 2) * kstep;
;             const GAS char* a3 = a2 + kstep; const GAS char* b3 = b2 + kstep;
;             PG8_LDB(B0, 0, 0); PG8_LDB(B1, 0, 1); PG8_SCHED; PG8_LDA(At, 0, 0); PG8_STAGE(PG8_SA(1, 1), a1 + hsA, voffA);
;             PG8_WAIT_V(8); PG8_WAIT_L(0); PG8_BAR; PG8_MMA(0, 0, At, B0); PG8_MMA(0, 1, At, B1); PG8_BAR; PG8_SCHED;
;             PG8_LDA(At, 0, 1); PG8_STAGE(PG8_SB(0, 0), b2, voffB); PG8_STAGE(PG8_SB(0, 1), b2 + hsB, voffB); PG8_STAGE(PG8_SA(0, 0), a2, voffA);
;             PG8_WAIT_V(8); PG8_WAIT_L(0); PG8_BAR; PG8_MMA(1, 0, At, B0); PG8_MMA(1, 1, At, B1); PG8_BAR; PG8_SCHED;
.LBB0_1645:
	s_add_u32 s20, s18, 0x100
	s_addc_u32 s21, s19, 0
	s_cmp_eq_u32 s55, 2
	s_cselect_b32 s25, s15, s21
	s_cselect_b32 s24, s14, s20
	s_cselect_b32 s23, s17, s54
	s_cselect_b32 s22, s16, s53
	v_lshl_add_u64 v[192:193], s[18:19], 0, v[170:171]
	s_add_i32 m0, s31, 0xc400
	s_nop 0
	global_load_lds_dwordx4 v[192:193], off
	v_lshl_add_u64 v[192:193], s[18:19], 0, v[168:169]
	s_add_i32 m0, s31, 0xe400
	s_nop 0
	global_load_lds_dwordx4 v[192:193], off
	v_add_u32_e32 v134, 0x10400, v195
	v_add_u32_e32 v158, 0x14400, v195
	ds_read_b128 v[114:117], v134
	ds_read_b128 v[118:121], v134 offset:1024
	ds_read_b128 v[130:133], v134 offset:2048
	ds_read_b128 v[134:137], v134 offset:3072
	ds_read_b128 v[146:149], v158
	ds_read_b128 v[150:153], v158 offset:1024
	ds_read_b128 v[154:157], v158 offset:2048
	ds_read_b128 v[158:161], v158 offset:3072
	ds_read_b128 v[172:175], v194 offset:1024
	ds_read_b128 v[176:179], v194 offset:2048
	ds_read_b128 v[180:183], v194 offset:3072
	ds_read_b128 v[184:187], v194 offset:4096
	ds_read_b128 v[188:191], v194 offset:5120
	ds_read_b128 v[196:199], v194 offset:6144
	ds_read_b128 v[200:203], v194 offset:7168
	ds_read_b128 v[204:207], v194 offset:8192
	s_waitcnt vmcnt(8)
	s_waitcnt lgkmcnt(0)
	s_setprio 1
	s_barrier
	v_mfma_f32_16x16x32_bf16 v[142:145], v[114:117], v[172:175], v[142:145]
	v_mfma_f32_16x16x32_bf16 v[138:141], v[130:133], v[172:175], v[138:141]
	v_mfma_f32_16x16x32_bf16 v[126:129], v[114:117], v[180:183], v[126:129]
	v_mfma_f32_16x16x32_bf16 v[122:125], v[130:133], v[180:183], v[122:125]
	v_mfma_f32_16x16x32_bf16 v[110:113], v[114:117], v[188:191], v[110:113]
	v_mfma_f32_16x16x32_bf16 v[106:109], v[130:133], v[188:191], v[106:109]
	v_mfma_f32_16x16x32_bf16 v[102:105], v[114:117], v[200:203], v[102:105]
	v_mfma_f32_16x16x32_bf16 v[98:101], v[130:133], v[200:203], v[98:101]
	v_mfma_f32_16x16x32_bf16 v[142:145], v[118:121], v[176:179], v[142:145]
	v_mfma_f32_16x16x32_bf16 v[138:141], v[134:137], v[176:179], v[138:141]
	v_mfma_f32_16x16x32_bf16 v[126:129], v[118:121], v[184:187], v[126:129]
	v_mfma_f32_16x16x32_bf16 v[122:125], v[134:137], v[184:187], v[122:125]
	v_mfma_f32_16x16x32_bf16 v[110:113], v[118:121], v[196:199], v[110:113]
	v_mfma_f32_16x16x32_bf16 v[106:109], v[134:137], v[196:199], v[106:109]
	v_mfma_f32_16x16x32_bf16 v[102:105], v[118:121], v[204:207], v[102:105]
	v_mfma_f32_16x16x32_bf16 v[98:101], v[134:137], v[204:207], v[98:101]
	s_setprio 0
	s_setprio 1
	v_mfma_f32_16x16x32_bf16 v[62:65], v[146:149], v[172:175], v[62:65]
	v_mfma_f32_16x16x32_bf16 v[58:61], v[154:157], v[172:175], v[58:61]
	v_mfma_f32_16x16x32_bf16 v[54:57], v[146:149], v[180:183], v[54:57]
	v_mfma_f32_16x16x32_bf16 v[50:53], v[154:157], v[180:183], v[50:53]
	v_mfma_f32_16x16x32_bf16 v[46:49], v[146:149], v[188:191], v[46:49]
	v_mfma_f32_16x16x32_bf16 v[42:45], v[154:157], v[188:191], v[42:45]
	v_mfma_f32_16x16x32_bf16 v[38:41], v[146:149], v[200:203], v[38:41]
	v_mfma_f32_16x16x32_bf16 v[34:37], v[154:157], v[200:203], v[34:37]
	v_mfma_f32_16x16x32_bf16 v[62:65], v[150:153], v[176:179], v[62:65]
	v_mfma_f32_16x16x32_bf16 v[58:61], v[158:161], v[176:179], v[58:61]
	v_mfma_f32_16x16x32_bf16 v[54:57], v[150:153], v[184:187], v[54:57]
	v_mfma_f32_16x16x32_bf16 v[50:53], v[158:161], v[184:187], v[50:53]
	v_mfma_f32_16x16x32_bf16 v[46:49], v[150:153], v[196:199], v[46:49]
	v_mfma_f32_16x16x32_bf16 v[42:45], v[158:161], v[196:199], v[42:45]
	v_mfma_f32_16x16x32_bf16 v[38:41], v[150:153], v[204:207], v[38:41]
	v_mfma_f32_16x16x32_bf16 v[34:37], v[158:161], v[204:207], v[34:37]
	s_setprio 0
	s_barrier
	s_mov_b32 m0, s34
	v_lshl_add_u64 v[192:193], s[22:23], 0, v[0:1]
	s_add_u32 s18, s22, 0x18000
	global_load_lds_dwordx4 v[192:193], off
	v_lshl_add_u64 v[208:209], s[22:23], 0, v[162:163]
	s_mov_b32 m0, s35
	s_addc_u32 s19, s23, 0
	global_load_lds_dwordx4 v[208:209], off
	v_lshl_add_u64 v[210:211], s[18:19], 0, v[0:1]
	s_mov_b32 m0, s36
	v_lshl_add_u64 v[212:213], s[24:25], 0, v[164:165]
	global_load_lds_dwordx4 v[210:211], off
	v_lshl_add_u64 v[210:211], s[18:19], 0, v[162:163]
	s_mov_b32 m0, s37
	s_nop 0
	global_load_lds_dwordx4 v[210:211], off
	v_lshl_add_u64 v[210:211], s[24:25], 0, v[166:167]
	s_mov_b32 m0, s38
	s_nop 0
	global_load_lds_dwordx4 v[210:211], off
	s_mov_b32 m0, s39
	s_nop 0
	global_load_lds_dwordx4 v[212:213], off
	ds_read_b128 v[172:175], v194 offset:17408
	ds_read_b128 v[176:179], v194 offset:18432
	ds_read_b128 v[180:183], v194 offset:19456
	ds_read_b128 v[184:187], v194 offset:20480
	ds_read_b128 v[188:191], v194 offset:21504
	ds_read_b128 v[196:199], v194 offset:22528
	ds_read_b128 v[200:203], v194 offset:23552
	ds_read_b128 v[204:207], v194 offset:24576
	s_waitcnt vmcnt(8)
	s_waitcnt lgkmcnt(0)
	s_setprio 1
	s_barrier
; #define PG8_STAGE(bufoff, gbase, voff) do { _Pragma("unroll") for (int _i = 0; _i < 2; ++_i) \
;         __builtin_amdgcn_global_load_lds((const GAS unsigned*)((const GAS char*)(gbase) + (voff)[_i]), (LAS unsigned*)(lds + (bufoff) + ldsw + _i * 8192), 16, 0, 0); } while (0)
; #define PG8_LDA(dst, b, h) do { _Pragma("unroll") for (int m = 0; m < 4; ++m) _Pragma("unroll") for (int k = 0; k < 2; ++k) dst[m][k] = *(const LAS bf16x8*)(lds + PG8_SA(b, h) + aoff + m * 2048 + k * 1024); } while (0)
; #define PG8_LDB(dst, b, h) do { _Pragma("unroll") for (int n = 0; n < 2; ++n) _Pragma("unroll") for (int k = 0; k < 2; ++k) dst[n][k] = *(const LAS bf16x8*)(lds + PG8_SB(b, h) + boff + n * 2048 + k * 1024); } while (0)
; #define PG8_MMA(ai, bj, At, Bt) do { __builtin_amdgcn_s_setprio(1); _Pragma("unroll") for (int m = 0; m < 4; ++m) _Pragma("unroll") for (int n = 0; n < 2; ++n) _Pragma("unroll") for (int k = 0; k < 2; ++k) \
;         acc[ai][bj][m][n] = __builtin_amdgcn_mfma_f32_16x16x32_bf16(Bt[n][k], At[m][k], acc[ai][bj][m][n], 0, 0, 0); __builtin_amdgcn_s_setprio(0); } while (0)
; #define PG8_WAIT_V(n) asm volatile("s_waitcnt vmcnt(" #n ")" ::: "memory")
; #define PG8_WAIT_L(n) asm volatile("s_waitcnt lgkmcnt(" #n ")" ::: "memory")
; #define PG8_BAR __builtin_amdgcn_s_barrier()
; #define PG8_SCHED __builtin_amdgcn_sched_barrier(0)
; template <class Epi, class Sched, bool ALIGN_EPI>
; __device__ __forceinline__ void gemm_phase(LAS unsigned char* lds, const Gemm g, const Sched& S, const Epi& E, int wave_id) {
;     ...
;             PG8_WAIT_V(8); PG8_WAIT_L(0); PG8_BAR; PG8_MMA(1, 0, At, B0); PG8_MMA(1, 1, At, B1); PG8_BAR; PG8_SCHED;
;             PG8_LDB(B0, 1, 0); PG8_LDB(B1, 1, 1); PG8_SCHED; PG8_LDA(At, 1, 0); PG8_STAGE(PG8_SA(0, 1), a2 + hsA, voffA);
;             PG8_WAIT_V(8); PG8_WAIT_L(0); PG8_BAR; PG8_MMA(0, 0, At, B0); PG8_MMA(0, 1, At, B1); PG8_BAR; PG8_SCHED;
	v_mfma_f32_16x16x32_bf16 v[94:97], v[114:117], v[172:175], v[94:97]
	v_mfma_f32_16x16x32_bf16 v[90:93], v[130:133], v[172:175], v[90:93]
	v_mfma_f32_16x16x32_bf16 v[86:89], v[114:117], v[180:183], v[86:89]
	v_mfma_f32_16x16x32_bf16 v[82:85], v[130:133], v[180:183], v[82:85]
	v_mfma_f32_16x16x32_bf16 v[78:81], v[114:117], v[188:191], v[78:81]
	v_mfma_f32_16x16x32_bf16 v[74:77], v[130:133], v[188:191], v[74:77]
	v_mfma_f32_16x16x32_bf16 v[70:73], v[114:117], v[200:203], v[70:73]
	v_mfma_f32_16x16x32_bf16 v[66:69], v[130:133], v[200:203], v[66:69]
	v_mfma_f32_16x16x32_bf16 v[94:97], v[118:121], v[176:179], v[94:97]
	v_mfma_f32_16x16x32_bf16 v[90:93], v[134:137], v[176:179], v[90:93]
	v_mfma_f32_16x16x32_bf16 v[86:89], v[118:121], v[184:187], v[86:89]
	v_mfma_f32_16x16x32_bf16 v[82:85], v[134:137], v[184:187], v[82:85]
	v_mfma_f32_16x16x32_bf16 v[78:81], v[118:121], v[196:199], v[78:81]
	v_mfma_f32_16x16x32_bf16 v[74:77], v[134:137], v[196:199], v[74:77]
	v_mfma_f32_16x16x32_bf16 v[70:73], v[118:121], v[204:207], v[70:73]
	v_mfma_f32_16x16x32_bf16 v[66:69], v[134:137], v[204:207], v[66:69]
	s_setprio 0
	s_setprio 1
	v_mfma_f32_16x16x32_bf16 v[30:33], v[146:149], v[172:175], v[30:33]
	v_mfma_f32_16x16x32_bf16 v[26:29], v[154:157], v[172:175], v[26:29]
	v_mfma_f32_16x16x32_bf16 v[22:25], v[146:149], v[180:183], v[22:25]
	v_mfma_f32_16x16x32_bf16 v[18:21], v[154:157], v[180:183], v[18:21]
	v_mfma_f32_16x16x32_bf16 v[14:17], v[146:149], v[188:191], v[14:17]
	v_mfma_f32_16x16x32_bf16 v[10:13], v[154:157], v[188:191], v[10:13]
	v_mfma_f32_16x16x32_bf16 v[6:9], v[146:149], v[200:203], v[6:9]
	v_mfma_f32_16x16x32_bf16 v[2:5], v[154:157], v[200:203], v[2:5]
	v_mfma_f32_16x16x32_bf16 v[30:33], v[150:153], v[176:179], v[30:33]
	v_mfma_f32_16x16x32_bf16 v[26:29], v[158:161], v[176:179], v[26:29]
	v_mfma_f32_16x16x32_bf16 v[22:25], v[150:153], v[184:187], v[22:25]
	v_mfma_f32_16x16x32_bf16 v[18:21], v[158:161], v[184:187], v[18:21]
	v_mfma_f32_16x16x32_bf16 v[14:17], v[150:153], v[196:199], v[14:17]
	v_mfma_f32_16x16x32_bf16 v[10:13], v[158:161], v[196:199], v[10:13]
	v_mfma_f32_16x16x32_bf16 v[6:9], v[150:153], v[204:207], v[6:9]
	v_mfma_f32_16x16x32_bf16 v[2:5], v[158:161], v[204:207], v[2:5]
	s_setprio 0
	s_barrier
	s_add_u32 s18, s24, 0x18000
	s_addc_u32 s19, s25, 0
	s_mov_b32 m0, s40
	v_lshl_add_u64 v[214:215], s[18:19], 0, v[166:167]
	global_load_lds_dwordx4 v[214:215], off
	v_lshl_add_u64 v[214:215], s[18:19], 0, v[164:165]
	s_mov_b32 m0, s41
	s_nop 0
	global_load_lds_dwordx4 v[214:215], off
	v_add_u32_e32 v134, 0x18400, v195
	v_add_u32_e32 v158, 0x1c400, v195
	ds_read_b128 v[114:117], v134
	ds_read_b128 v[118:121], v134 offset:1024
	ds_read_b128 v[130:133], v134 offset:2048
	ds_read_b128 v[134:137], v134 offset:3072
	ds_read_b128 v[146:149], v158
	ds_read_b128 v[150:153], v158 offset:1024
	ds_read_b128 v[154:157], v158 offset:2048
	ds_read_b128 v[158:161], v158 offset:3072
	ds_read_b128 v[172:175], v194 offset:33792
	ds_read_b128 v[176:179], v194 offset:34816
	ds_read_b128 v[180:183], v194 offset:35840
	ds_read_b128 v[184:187], v194 offset:36864
	ds_read_b128 v[188:191], v194 offset:37888
	ds_read_b128 v[196:199], v194 offset:38912
	ds_read_b128 v[200:203], v194 offset:39936
	ds_read_b128 v[204:207], v194 offset:40960
	s_waitcnt vmcnt(8)
	s_waitcnt lgkmcnt(0)
	s_setprio 1
	s_barrier
	v_mfma_f32_16x16x32_bf16 v[142:145], v[114:117], v[172:175], v[142:145]
	v_mfma_f32_16x16x32_bf16 v[138:141], v[130:133], v[172:175], v[138:141]
	v_mfma_f32_16x16x32_bf16 v[126:129], v[114:117], v[180:183], v[126:129]
	v_mfma_f32_16x16x32_bf16 v[122:125], v[130:133], v[180:183], v[122:125]
	v_mfma_f32_16x16x32_bf16 v[110:113], v[114:117], v[188:191], v[110:113]
	v_mfma_f32_16x16x32_bf16 v[106:109], v[130:133], v[188:191], v[106:109]
	v_mfma_f32_16x16x32_bf16 v[102:105], v[114:117], v[200:203], v[102:105]
	v_mfma_f32_16x16x32_bf16 v[98:101], v[130:133], v[200:203], v[98:101]
	v_mfma_f32_16x16x32_bf16 v[142:145], v[118:121], v[176:179], v[142:145]
	v_mfma_f32_16x16x32_bf16 v[138:141], v[134:137], v[176:179], v[138:141]
	v_mfma_f32_16x16x32_bf16 v[126:129], v[118:121], v[184:187], v[126:129]
	v_mfma_f32_16x16x32_bf16 v[122:125], v[134:137], v[184:187], v[122:125]
	v_mfma_f32_16x16x32_bf16 v[110:113], v[118:121], v[196:199], v[110:113]
	v_mfma_f32_16x16x32_bf16 v[106:109], v[134:137], v[196:199], v[106:109]
	v_mfma_f32_16x16x32_bf16 v[102:105], v[118:121], v[204:207], v[102:105]
	v_mfma_f32_16x16x32_bf16 v[98:101], v[134:137], v[204:207], v[98:101]
	s_setprio 0
	s_setprio 1
	v_mfma_f32_16x16x32_bf16 v[62:65], v[146:149], v[172:175], v[62:65]
	v_mfma_f32_16x16x32_bf16 v[58:61], v[154:157], v[172:175], v[58:61]
	v_mfma_f32_16x16x32_bf16 v[54:57], v[146:149], v[180:183], v[54:57]
	v_mfma_f32_16x16x32_bf16 v[50:53], v[154:157], v[180:183], v[50:53]
	v_mfma_f32_16x16x32_bf16 v[46:49], v[146:149], v[188:191], v[46:49]
	v_mfma_f32_16x16x32_bf16 v[42:45], v[154:157], v[188:191], v[42:45]
	v_mfma_f32_16x16x32_bf16 v[38:41], v[146:149], v[200:203], v[38:41]
	v_mfma_f32_16x16x32_bf16 v[34:37], v[154:157], v[200:203], v[34:37]
	v_mfma_f32_16x16x32_bf16 v[62:65], v[150:153], v[176:179], v[62:65]
	v_mfma_f32_16x16x32_bf16 v[58:61], v[158:161], v[176:179], v[58:61]
	v_mfma_f32_16x16x32_bf16 v[54:57], v[150:153], v[184:187], v[54:57]
	v_mfma_f32_16x16x32_bf16 v[50:53], v[158:161], v[184:187], v[50:53]
	v_mfma_f32_16x16x32_bf16 v[46:49], v[150:153], v[196:199], v[46:49]
	v_mfma_f32_16x16x32_bf16 v[42:45], v[158:161], v[196:199], v[42:45]
	v_mfma_f32_16x16x32_bf16 v[38:41], v[150:153], v[204:207], v[38:41]
	v_mfma_f32_16x16x32_bf16 v[34:37], v[158:161], v[204:207], v[34:37]
	s_setprio 0
	s_barrier
; #define PG8_STAGE(bufoff, gbase, voff) do { _Pragma("unroll") for (int _i = 0; _i < 2; ++_i) \
;         __builtin_amdgcn_global_load_lds((const GAS unsigned*)((const GAS char*)(gbase) + (voff)[_i]), (LAS unsigned*)(lds + (bufoff) + ldsw + _i * 8192), 16, 0, 0); } while (0)
; #define PG8_LDA(dst, b, h) do { _Pragma("unroll") for (int m = 0; m < 4; ++m) _Pragma("unroll") for (int k = 0; k < 2; ++k) dst[m][k] = *(const LAS bf16x8*)(lds + PG8_SA(b, h) + aoff + m * 2048 + k * 1024); } while (0)
; #define PG8_MMA(ai, bj, At, Bt) do { __builtin_amdgcn_s_setprio(1); _Pragma("unroll") for (int m = 0; m < 4; ++m) _Pragma("unroll") for (int n = 0; n < 2; ++n) _Pragma("unroll") for (int k = 0; k < 2; ++k) \
;         acc[ai][bj][m][n] = __builtin_amdgcn_mfma_f32_16x16x32_bf16(Bt[n][k], At[m][k], acc[ai][bj][m][n], 0, 0, 0); __builtin_amdgcn_s_setprio(0); } while (0)
; #define PG8_WAIT_V(n) asm volatile("s_waitcnt vmcnt(" #n ")" ::: "memory")
; #define PG8_WAIT_L(n) asm volatile("s_waitcnt lgkmcnt(" #n ")" ::: "memory")
; #define PG8_BAR __builtin_amdgcn_s_barrier()
; #define PG8_SCHED __builtin_amdgcn_sched_barrier(0)
; template <class Epi, class Sched, bool ALIGN_EPI>
; __device__ __forceinline__ void gemm_phase(LAS unsigned char* lds, const Gemm g, const Sched& S, const Epi& E, int wave_id) {
;     ...
;             PG8_LDA(At, 1, 1); PG8_STAGE(PG8_SB(1, 0), b3, voffB); PG8_STAGE(PG8_SB(1, 1), b3 + hsB, voffB); PG8_STAGE(PG8_SA(1, 0), a3, voffA);
;             PG8_WAIT_V(8); PG8_WAIT_L(0); PG8_BAR; PG8_MMA(1, 0, At, B0); PG8_MMA(1, 1, At, B1); PG8_BAR; PG8_SCHED;
;         }
;         if constexpr (ALIGN_EPI) { if (wr == 0) PG8_BAR; }
	s_mov_b32 m0, s44
	v_lshl_add_u64 v[192:193], v[192:193], 0, s[92:93]
	s_add_u32 s18, s22, 0x18080
	global_load_lds_dwordx4 v[192:193], off
	v_lshl_add_u64 v[192:193], v[208:209], 0, s[92:93]
	s_mov_b32 m0, s45
	s_addc_u32 s19, s23, 0
	global_load_lds_dwordx4 v[192:193], off
	v_lshl_add_u64 v[192:193], s[18:19], 0, v[0:1]
	s_mov_b32 m0, s48
	s_nop 0
	global_load_lds_dwordx4 v[192:193], off
	v_lshl_add_u64 v[192:193], s[18:19], 0, v[162:163]
	s_mov_b32 m0, s49
	s_nop 0
	global_load_lds_dwordx4 v[192:193], off
	v_lshl_add_u64 v[192:193], v[210:211], 0, s[92:93]
	s_mov_b32 m0, s46
	s_nop 0
	global_load_lds_dwordx4 v[192:193], off
	v_lshl_add_u64 v[192:193], v[212:213], 0, s[92:93]
	s_mov_b32 m0, s47
	s_nop 0
	global_load_lds_dwordx4 v[192:193], off
	ds_read_b128 v[172:175], v194 offset:50176
	ds_read_b128 v[176:179], v194 offset:51200
	ds_read_b128 v[180:183], v194 offset:52224
	ds_read_b128 v[184:187], v194 offset:53248
	ds_read_b128 v[188:191], v194 offset:54272
	ds_read_b128 v[196:199], v194 offset:55296
	ds_read_b128 v[200:203], v194 offset:56320
	ds_read_b128 v[204:207], v194 offset:57344
	s_waitcnt vmcnt(8)
	s_waitcnt lgkmcnt(0)
	s_setprio 1
	s_barrier
	v_mfma_f32_16x16x32_bf16 v[94:97], v[114:117], v[172:175], v[94:97]
	v_mfma_f32_16x16x32_bf16 v[90:93], v[130:133], v[172:175], v[90:93]
	v_mfma_f32_16x16x32_bf16 v[86:89], v[114:117], v[180:183], v[86:89]
	v_mfma_f32_16x16x32_bf16 v[82:85], v[130:133], v[180:183], v[82:85]
	v_mfma_f32_16x16x32_bf16 v[78:81], v[114:117], v[188:191], v[78:81]
	v_mfma_f32_16x16x32_bf16 v[74:77], v[130:133], v[188:191], v[74:77]
	v_mfma_f32_16x16x32_bf16 v[70:73], v[114:117], v[200:203], v[70:73]
	v_mfma_f32_16x16x32_bf16 v[66:69], v[130:133], v[200:203], v[66:69]
	v_mfma_f32_16x16x32_bf16 v[94:97], v[118:121], v[176:179], v[94:97]
	v_mfma_f32_16x16x32_bf16 v[90:93], v[134:137], v[176:179], v[90:93]
	v_mfma_f32_16x16x32_bf16 v[86:89], v[118:121], v[184:187], v[86:89]
	v_mfma_f32_16x16x32_bf16 v[82:85], v[134:137], v[184:187], v[82:85]
	v_mfma_f32_16x16x32_bf16 v[78:81], v[118:121], v[196:199], v[78:81]
	v_mfma_f32_16x16x32_bf16 v[74:77], v[134:137], v[196:199], v[74:77]
	v_mfma_f32_16x16x32_bf16 v[70:73], v[118:121], v[204:207], v[70:73]
	v_mfma_f32_16x16x32_bf16 v[66:69], v[134:137], v[204:207], v[66:69]
	s_setprio 0
	s_setprio 1
	v_mfma_f32_16x16x32_bf16 v[30:33], v[146:149], v[172:175], v[30:33]
	v_mfma_f32_16x16x32_bf16 v[26:29], v[154:157], v[172:175], v[26:29]
	v_mfma_f32_16x16x32_bf16 v[22:25], v[146:149], v[180:183], v[22:25]
	v_mfma_f32_16x16x32_bf16 v[18:21], v[154:157], v[180:183], v[18:21]
	v_mfma_f32_16x16x32_bf16 v[14:17], v[146:149], v[188:191], v[14:17]
	v_mfma_f32_16x16x32_bf16 v[10:13], v[154:157], v[188:191], v[10:13]
	v_mfma_f32_16x16x32_bf16 v[6:9], v[146:149], v[200:203], v[6:9]
	v_mfma_f32_16x16x32_bf16 v[2:5], v[154:157], v[200:203], v[2:5]
	v_mfma_f32_16x16x32_bf16 v[30:33], v[150:153], v[176:179], v[30:33]
	v_mfma_f32_16x16x32_bf16 v[26:29], v[158:161], v[176:179], v[26:29]
	v_mfma_f32_16x16x32_bf16 v[22:25], v[150:153], v[184:187], v[22:25]
	v_mfma_f32_16x16x32_bf16 v[18:21], v[158:161], v[184:187], v[18:21]
	v_mfma_f32_16x16x32_bf16 v[14:17], v[150:153], v[196:199], v[14:17]
	v_mfma_f32_16x16x32_bf16 v[10:13], v[158:161], v[196:199], v[10:13]
	v_mfma_f32_16x16x32_bf16 v[6:9], v[150:153], v[204:207], v[6:9]
	v_mfma_f32_16x16x32_bf16 v[2:5], v[158:161], v[204:207], v[2:5]
	s_setprio 0
	s_barrier
	s_add_i32 s55, s55, 2
	s_add_u32 s53, s53, 0x100
	s_addc_u32 s54, s54, 0
	s_cmp_gt_u32 s55, 3
	s_mov_b64 s[18:19], s[20:21]
	s_cbranch_scc0 .LBB0_1645
	s_and_b64 vcc, exec, s[12:13]
	s_cbranch_vccz .LBB0_1648
	s_barrier

; #define GAS __attribute__((address_space(1)))
; #define PG8_STAGE(bufoff, gbase, voff) do { _Pragma("unroll") for (int _i = 0; _i < 2; ++_i) \
;         __builtin_amdgcn_global_load_lds((const GAS unsigned*)((const GAS char*)(gbase) + (voff)[_i]), (LAS unsigned*)(lds + (bufoff) + ldsw + _i * 8192), 16, 0, 0); } while (0)
; #define PG8_LDA(dst, b, h) do { _Pragma("unroll") for (int m = 0; m < 4; ++m) _Pragma("unroll") for (int k = 0; k < 2; ++k) dst[m][k] = *(const LAS bf16x8*)(lds + PG8_SA(b, h) + aoff + m * 2048 + k * 1024); } while (0)
; #define PG8_LDB(dst, b, h) do { _Pragma("unroll") for (int n = 0; n < 2; ++n) _Pragma("unroll") for (int k = 0; k < 2; ++k) dst[n][k] = *(const LAS bf16x8*)(lds + PG8_SB(b, h) + boff + n * 2048 + k * 1024); } while (0)
; #define PG8_MMA(ai, bj, At, Bt) do { __builtin_amdgcn_s_setprio(1); _Pragma("unroll") for (int m = 0; m < 4; ++m) _Pragma("unroll") for (int n = 0; n < 2; ++n) _Pragma("unroll") for (int k = 0; k < 2; ++k) \
;         acc[ai][bj][m][n] = __builtin_amdgcn_mfma_f32_16x16x32_bf16(Bt[n][k], At[m][k], acc[ai][bj][m][n], 0, 0, 0); __builtin_amdgcn_s_setprio(0); } while (0)
; #define PG8_WAIT_V(n) asm volatile("s_waitcnt vmcnt(" #n ")" ::: "memory")
; #define PG8_WAIT_L(n) asm volatile("s_waitcnt lgkmcnt(" #n ")" ::: "memory")
; #define PG8_BAR __builtin_amdgcn_s_barrier()
; template <class Epi, class Sched, bool ALIGN_EPI>
; __device__ __forceinline__ void gemm_phase(LAS unsigned char* lds, const Gemm g, const Sched& S, const Epi& E, int wave_id) {
;     ...
;             const bool last = (t == nt - 2);
;             const GAS char* a1 = cA + (size_t)(t + 1) * kstep;
;             const GAS char* a2 = last ? nA : cA + (size_t)(t + 2) * kstep; const GAS char* b2 = last ? nB : cB + (size_t)(t + 2) * kstep;
;             const GAS char* a3 = a2 + kstep; const GAS char* b3 = b2 + kstep;
;             PG8_LDB(B0, 0, 0); PG8_LDB(B1, 0, 1); PG8_SCHED; PG8_LDA(At, 0, 0); PG8_STAGE(PG8_SA(1, 1), a1 + hsA, voffA);
;             PG8_WAIT_V(8); PG8_WAIT_L(0); PG8_BAR; PG8_MMA(0, 0, At, B0); PG8_MMA(0, 1, At, B1); PG8_BAR; PG8_SCHED;
;             PG8_LDA(At, 0, 1); PG8_STAGE(PG8_SB(0, 0), b2, voffB); PG8_STAGE(PG8_SB(0, 1), b2 + hsB, voffB); PG8_STAGE(PG8_SA(0, 0), a2, voffA);
;             PG8_WAIT_V(8); PG8_WAIT_L(0); PG8_BAR; PG8_MMA(1, 0, At, B0); PG8_MMA(1, 1, At, B1); PG8_BAR; PG8_SCHED;
.LBB0_1837:
	s_add_u32 s42, s40, 0xfffc0080
	s_addc_u32 s43, s41, -1
	s_cmp_eq_u32 s67, 12
	s_cselect_b32 s45, s5, s43
	s_cselect_b32 s44, s25, s42
	s_cselect_b32 s43, s27, s66
	s_cselect_b32 s42, s37, s39
	v_lshl_add_u64 v[196:197], s[40:41], 0, v[182:183]
	s_add_i32 m0, s1, 0xc400
	s_nop 0
	global_load_lds_dwordx4 v[196:197], off
	v_lshl_add_u64 v[196:197], s[40:41], 0, v[180:181]
	s_add_i32 m0, s1, 0xe400
	s_nop 0
	global_load_lds_dwordx4 v[196:197], off
	v_add_u32_e32 v142, 0x10400, v199
	v_add_u32_e32 v158, 0x14400, v199
	ds_read_b128 v[130:133], v142
	ds_read_b128 v[134:137], v142 offset:1024
	ds_read_b128 v[138:141], v142 offset:2048
	ds_read_b128 v[142:145], v142 offset:3072
	ds_read_b128 v[146:149], v158
	ds_read_b128 v[150:153], v158 offset:1024
	ds_read_b128 v[154:157], v158 offset:2048
	ds_read_b128 v[158:161], v158 offset:3072
	ds_read_b128 v[162:165], v198 offset:1024
	ds_read_b128 v[166:169], v198 offset:2048
	ds_read_b128 v[170:173], v198 offset:3072
	ds_read_b128 v[184:187], v198 offset:4096
	ds_read_b128 v[188:191], v198 offset:5120
	ds_read_b128 v[192:195], v198 offset:6144
	ds_read_b128 v[200:203], v198 offset:7168
	ds_read_b128 v[204:207], v198 offset:8192
	s_waitcnt vmcnt(8)
	s_waitcnt lgkmcnt(0)
	s_setprio 1
	s_barrier
	v_mfma_f32_16x16x32_bf16 v[126:129], v[130:133], v[162:165], v[126:129]
	v_mfma_f32_16x16x32_bf16 v[122:125], v[138:141], v[162:165], v[122:125]
	v_mfma_f32_16x16x32_bf16 v[114:117], v[130:133], v[170:173], v[114:117]
	v_mfma_f32_16x16x32_bf16 v[106:109], v[138:141], v[170:173], v[106:109]
	v_mfma_f32_16x16x32_bf16 v[98:101], v[130:133], v[188:191], v[98:101]
	v_mfma_f32_16x16x32_bf16 v[90:93], v[138:141], v[188:191], v[90:93]
	v_mfma_f32_16x16x32_bf16 v[82:85], v[130:133], v[200:203], v[82:85]
	v_mfma_f32_16x16x32_bf16 v[74:77], v[138:141], v[200:203], v[74:77]
	v_mfma_f32_16x16x32_bf16 v[126:129], v[134:137], v[166:169], v[126:129]
	v_mfma_f32_16x16x32_bf16 v[122:125], v[142:145], v[166:169], v[122:125]
	v_mfma_f32_16x16x32_bf16 v[114:117], v[134:137], v[184:187], v[114:117]
	v_mfma_f32_16x16x32_bf16 v[106:109], v[142:145], v[184:187], v[106:109]
	v_mfma_f32_16x16x32_bf16 v[98:101], v[134:137], v[192:195], v[98:101]
	v_mfma_f32_16x16x32_bf16 v[90:93], v[142:145], v[192:195], v[90:93]
	v_mfma_f32_16x16x32_bf16 v[82:85], v[134:137], v[204:207], v[82:85]
	v_mfma_f32_16x16x32_bf16 v[74:77], v[142:145], v[204:207], v[74:77]
	s_setprio 0
	s_setprio 1
	v_mfma_f32_16x16x32_bf16 v[118:121], v[146:149], v[162:165], v[118:121]
	v_mfma_f32_16x16x32_bf16 v[110:113], v[154:157], v[162:165], v[110:113]
	v_mfma_f32_16x16x32_bf16 v[102:105], v[146:149], v[170:173], v[102:105]
	v_mfma_f32_16x16x32_bf16 v[94:97], v[154:157], v[170:173], v[94:97]
	v_mfma_f32_16x16x32_bf16 v[86:89], v[146:149], v[188:191], v[86:89]
	v_mfma_f32_16x16x32_bf16 v[78:81], v[154:157], v[188:191], v[78:81]
	v_mfma_f32_16x16x32_bf16 v[70:73], v[146:149], v[200:203], v[70:73]
	v_mfma_f32_16x16x32_bf16 v[66:69], v[154:157], v[200:203], v[66:69]
	v_mfma_f32_16x16x32_bf16 v[118:121], v[150:153], v[166:169], v[118:121]
	v_mfma_f32_16x16x32_bf16 v[110:113], v[158:161], v[166:169], v[110:113]
	v_mfma_f32_16x16x32_bf16 v[102:105], v[150:153], v[184:187], v[102:105]
	v_mfma_f32_16x16x32_bf16 v[94:97], v[158:161], v[184:187], v[94:97]
	v_mfma_f32_16x16x32_bf16 v[86:89], v[150:153], v[192:195], v[86:89]
	v_mfma_f32_16x16x32_bf16 v[78:81], v[158:161], v[192:195], v[78:81]
	v_mfma_f32_16x16x32_bf16 v[70:73], v[150:153], v[204:207], v[70:73]
	v_mfma_f32_16x16x32_bf16 v[66:69], v[158:161], v[204:207], v[66:69]
	s_setprio 0
	s_barrier
	s_mov_b32 m0, s48
	v_lshl_add_u64 v[196:197], s[42:43], 0, v[0:1]
	s_add_u32 s68, s42, 0x40000
	global_load_lds_dwordx4 v[196:197], off
	v_lshl_add_u64 v[208:209], s[42:43], 0, v[178:179]
	s_mov_b32 m0, s49
	s_addc_u32 s69, s43, 0
	global_load_lds_dwordx4 v[208:209], off
	v_lshl_add_u64 v[210:211], s[68:69], 0, v[0:1]
	s_mov_b32 m0, s50
	v_lshl_add_u64 v[212:213], s[44:45], 0, v[176:177]
	global_load_lds_dwordx4 v[210:211], off
	v_lshl_add_u64 v[210:211], s[68:69], 0, v[178:179]
	s_mov_b32 m0, s51
	s_nop 0
	global_load_lds_dwordx4 v[210:211], off
	v_lshl_add_u64 v[210:211], s[44:45], 0, v[174:175]
	s_mov_b32 m0, s52
	s_nop 0
	global_load_lds_dwordx4 v[210:211], off
	s_mov_b32 m0, s53
	s_nop 0
	global_load_lds_dwordx4 v[212:213], off
	ds_read_b128 v[162:165], v198 offset:17408
	ds_read_b128 v[166:169], v198 offset:18432
	ds_read_b128 v[170:173], v198 offset:19456
	ds_read_b128 v[184:187], v198 offset:20480
	ds_read_b128 v[188:191], v198 offset:21504
	ds_read_b128 v[192:195], v198 offset:22528
	ds_read_b128 v[200:203], v198 offset:23552
	ds_read_b128 v[204:207], v198 offset:24576
	s_waitcnt vmcnt(8)
	s_waitcnt lgkmcnt(0)
	s_setprio 1
	s_barrier
; #define PG8_STAGE(bufoff, gbase, voff) do { _Pragma("unroll") for (int _i = 0; _i < 2; ++_i) \
;         __builtin_amdgcn_global_load_lds((const GAS unsigned*)((const GAS char*)(gbase) + (voff)[_i]), (LAS unsigned*)(lds + (bufoff) + ldsw + _i * 8192), 16, 0, 0); } while (0)
; #define PG8_LDA(dst, b, h) do { _Pragma("unroll") for (int m = 0; m < 4; ++m) _Pragma("unroll") for (int k = 0; k < 2; ++k) dst[m][k] = *(const LAS bf16x8*)(lds + PG8_SA(b, h) + aoff + m * 2048 + k * 1024); } while (0)
; #define PG8_LDB(dst, b, h) do { _Pragma("unroll") for (int n = 0; n < 2; ++n) _Pragma("unroll") for (int k = 0; k < 2; ++k) dst[n][k] = *(const LAS bf16x8*)(lds + PG8_SB(b, h) + boff + n * 2048 + k * 1024); } while (0)
; #define PG8_MMA(ai, bj, At, Bt) do { __builtin_amdgcn_s_setprio(1); _Pragma("unroll") for (int m = 0; m < 4; ++m) _Pragma("unroll") for (int n = 0; n < 2; ++n) _Pragma("unroll") for (int k = 0; k < 2; ++k) \
;         acc[ai][bj][m][n] = __builtin_amdgcn_mfma_f32_16x16x32_bf16(Bt[n][k], At[m][k], acc[ai][bj][m][n], 0, 0, 0); __builtin_amdgcn_s_setprio(0); } while (0)
; #define PG8_WAIT_V(n) asm volatile("s_waitcnt vmcnt(" #n ")" ::: "memory")
; #define PG8_WAIT_L(n) asm volatile("s_waitcnt lgkmcnt(" #n ")" ::: "memory")
; #define PG8_BAR __builtin_amdgcn_s_barrier()
; #define PG8_SCHED __builtin_amdgcn_sched_barrier(0)
; template <class Epi, class Sched, bool ALIGN_EPI>
; __device__ __forceinline__ void gemm_phase(LAS unsigned char* lds, const Gemm g, const Sched& S, const Epi& E, int wave_id) {
;     ...
;             PG8_WAIT_V(8); PG8_WAIT_L(0); PG8_BAR; PG8_MMA(1, 0, At, B0); PG8_MMA(1, 1, At, B1); PG8_BAR; PG8_SCHED;
;             PG8_LDB(B0, 1, 0); PG8_LDB(B1, 1, 1); PG8_SCHED; PG8_LDA(At, 1, 0); PG8_STAGE(PG8_SA(0, 1), a2 + hsA, voffA);
;             PG8_WAIT_V(8); PG8_WAIT_L(0); PG8_BAR; PG8_MMA(0, 0, At, B0); PG8_MMA(0, 1, At, B1); PG8_BAR; PG8_SCHED;
	v_mfma_f32_16x16x32_bf16 v[62:65], v[130:133], v[162:165], v[62:65]
	v_mfma_f32_16x16x32_bf16 v[58:61], v[138:141], v[162:165], v[58:61]
	v_mfma_f32_16x16x32_bf16 v[50:53], v[130:133], v[170:173], v[50:53]
	v_mfma_f32_16x16x32_bf16 v[42:45], v[138:141], v[170:173], v[42:45]
	v_mfma_f32_16x16x32_bf16 v[34:37], v[130:133], v[188:191], v[34:37]
	v_mfma_f32_16x16x32_bf16 v[26:29], v[138:141], v[188:191], v[26:29]
	v_mfma_f32_16x16x32_bf16 v[18:21], v[130:133], v[200:203], v[18:21]
	v_mfma_f32_16x16x32_bf16 v[10:13], v[138:141], v[200:203], v[10:13]
	v_mfma_f32_16x16x32_bf16 v[62:65], v[134:137], v[166:169], v[62:65]
	v_mfma_f32_16x16x32_bf16 v[58:61], v[142:145], v[166:169], v[58:61]
	v_mfma_f32_16x16x32_bf16 v[50:53], v[134:137], v[184:187], v[50:53]
	v_mfma_f32_16x16x32_bf16 v[42:45], v[142:145], v[184:187], v[42:45]
	v_mfma_f32_16x16x32_bf16 v[34:37], v[134:137], v[192:195], v[34:37]
	v_mfma_f32_16x16x32_bf16 v[26:29], v[142:145], v[192:195], v[26:29]
	v_mfma_f32_16x16x32_bf16 v[18:21], v[134:137], v[204:207], v[18:21]
	v_mfma_f32_16x16x32_bf16 v[10:13], v[142:145], v[204:207], v[10:13]
	s_setprio 0
	s_setprio 1
	v_mfma_f32_16x16x32_bf16 v[54:57], v[146:149], v[162:165], v[54:57]
	v_mfma_f32_16x16x32_bf16 v[46:49], v[154:157], v[162:165], v[46:49]
	v_mfma_f32_16x16x32_bf16 v[38:41], v[146:149], v[170:173], v[38:41]
	v_mfma_f32_16x16x32_bf16 v[30:33], v[154:157], v[170:173], v[30:33]
	v_mfma_f32_16x16x32_bf16 v[22:25], v[146:149], v[188:191], v[22:25]
	v_mfma_f32_16x16x32_bf16 v[14:17], v[154:157], v[188:191], v[14:17]
	v_mfma_f32_16x16x32_bf16 v[6:9], v[146:149], v[200:203], v[6:9]
	v_mfma_f32_16x16x32_bf16 v[2:5], v[154:157], v[200:203], v[2:5]
	v_mfma_f32_16x16x32_bf16 v[54:57], v[150:153], v[166:169], v[54:57]
	v_mfma_f32_16x16x32_bf16 v[46:49], v[158:161], v[166:169], v[46:49]
	v_mfma_f32_16x16x32_bf16 v[38:41], v[150:153], v[184:187], v[38:41]
	v_mfma_f32_16x16x32_bf16 v[30:33], v[158:161], v[184:187], v[30:33]
	v_mfma_f32_16x16x32_bf16 v[22:25], v[150:153], v[192:195], v[22:25]
	v_mfma_f32_16x16x32_bf16 v[14:17], v[158:161], v[192:195], v[14:17]
	v_mfma_f32_16x16x32_bf16 v[6:9], v[150:153], v[204:207], v[6:9]
	v_mfma_f32_16x16x32_bf16 v[2:5], v[158:161], v[204:207], v[2:5]
	s_setprio 0
	s_barrier
	s_add_u32 s44, s44, 0x40000
	s_addc_u32 s45, s45, 0
	s_mov_b32 m0, s54
	v_lshl_add_u64 v[214:215], s[44:45], 0, v[174:175]
	global_load_lds_dwordx4 v[214:215], off
	v_lshl_add_u64 v[214:215], s[44:45], 0, v[176:177]
	s_mov_b32 m0, s55
	s_nop 0
	global_load_lds_dwordx4 v[214:215], off
	v_add_u32_e32 v142, 0x18400, v199
	v_add_u32_e32 v158, 0x1c400, v199
	ds_read_b128 v[130:133], v142
	ds_read_b128 v[134:137], v142 offset:1024
	ds_read_b128 v[138:141], v142 offset:2048
	ds_read_b128 v[142:145], v142 offset:3072
	ds_read_b128 v[146:149], v158
	ds_read_b128 v[150:153], v158 offset:1024
	ds_read_b128 v[154:157], v158 offset:2048
	ds_read_b128 v[158:161], v158 offset:3072
	ds_read_b128 v[162:165], v198 offset:33792
	ds_read_b128 v[166:169], v198 offset:34816
	ds_read_b128 v[170:173], v198 offset:35840
	ds_read_b128 v[184:187], v198 offset:36864
	ds_read_b128 v[188:191], v198 offset:37888
	ds_read_b128 v[192:195], v198 offset:38912
	ds_read_b128 v[200:203], v198 offset:39936
	ds_read_b128 v[204:207], v198 offset:40960
	s_waitcnt vmcnt(8)
	s_waitcnt lgkmcnt(0)
	s_setprio 1
	s_barrier
	v_mfma_f32_16x16x32_bf16 v[126:129], v[130:133], v[162:165], v[126:129]
	v_mfma_f32_16x16x32_bf16 v[122:125], v[138:141], v[162:165], v[122:125]
	v_mfma_f32_16x16x32_bf16 v[114:117], v[130:133], v[170:173], v[114:117]
	v_mfma_f32_16x16x32_bf16 v[106:109], v[138:141], v[170:173], v[106:109]
	v_mfma_f32_16x16x32_bf16 v[98:101], v[130:133], v[188:191], v[98:101]
	v_mfma_f32_16x16x32_bf16 v[90:93], v[138:141], v[188:191], v[90:93]
	v_mfma_f32_16x16x32_bf16 v[82:85], v[130:133], v[200:203], v[82:85]
	v_mfma_f32_16x16x32_bf16 v[74:77], v[138:141], v[200:203], v[74:77]
	v_mfma_f32_16x16x32_bf16 v[126:129], v[134:137], v[166:169], v[126:129]
	v_mfma_f32_16x16x32_bf16 v[122:125], v[142:145], v[166:169], v[122:125]
	v_mfma_f32_16x16x32_bf16 v[114:117], v[134:137], v[184:187], v[114:117]
	v_mfma_f32_16x16x32_bf16 v[106:109], v[142:145], v[184:187], v[106:109]
	v_mfma_f32_16x16x32_bf16 v[98:101], v[134:137], v[192:195], v[98:101]
	v_mfma_f32_16x16x32_bf16 v[90:93], v[142:145], v[192:195], v[90:93]
	v_mfma_f32_16x16x32_bf16 v[82:85], v[134:137], v[204:207], v[82:85]
	v_mfma_f32_16x16x32_bf16 v[74:77], v[142:145], v[204:207], v[74:77]
	s_setprio 0
	s_setprio 1
	v_mfma_f32_16x16x32_bf16 v[118:121], v[146:149], v[162:165], v[118:121]
	v_mfma_f32_16x16x32_bf16 v[110:113], v[154:157], v[162:165], v[110:113]
	v_mfma_f32_16x16x32_bf16 v[102:105], v[146:149], v[170:173], v[102:105]
	v_mfma_f32_16x16x32_bf16 v[94:97], v[154:157], v[170:173], v[94:97]
	v_mfma_f32_16x16x32_bf16 v[86:89], v[146:149], v[188:191], v[86:89]
	v_mfma_f32_16x16x32_bf16 v[78:81], v[154:157], v[188:191], v[78:81]
	v_mfma_f32_16x16x32_bf16 v[70:73], v[146:149], v[200:203], v[70:73]
	v_mfma_f32_16x16x32_bf16 v[66:69], v[154:157], v[200:203], v[66:69]
	v_mfma_f32_16x16x32_bf16 v[118:121], v[150:153], v[166:169], v[118:121]
	v_mfma_f32_16x16x32_bf16 v[110:113], v[158:161], v[166:169], v[110:113]
	v_mfma_f32_16x16x32_bf16 v[102:105], v[150:153], v[184:187], v[102:105]
	v_mfma_f32_16x16x32_bf16 v[94:97], v[158:161], v[184:187], v[94:97]
	v_mfma_f32_16x16x32_bf16 v[86:89], v[150:153], v[192:195], v[86:89]
	v_mfma_f32_16x16x32_bf16 v[78:81], v[158:161], v[192:195], v[78:81]
	v_mfma_f32_16x16x32_bf16 v[70:73], v[150:153], v[204:207], v[70:73]
	v_mfma_f32_16x16x32_bf16 v[66:69], v[158:161], v[204:207], v[66:69]
	s_setprio 0
	s_barrier
; #define PG8_STAGE(bufoff, gbase, voff) do { _Pragma("unroll") for (int _i = 0; _i < 2; ++_i) \
;         __builtin_amdgcn_global_load_lds((const GAS unsigned*)((const GAS char*)(gbase) + (voff)[_i]), (LAS unsigned*)(lds + (bufoff) + ldsw + _i * 8192), 16, 0, 0); } while (0)
; #define PG8_LDA(dst, b, h) do { _Pragma("unroll") for (int m = 0; m < 4; ++m) _Pragma("unroll") for (int k = 0; k < 2; ++k) dst[m][k] = *(const LAS bf16x8*)(lds + PG8_SA(b, h) + aoff + m * 2048 + k * 1024); } while (0)
; #define PG8_MMA(ai, bj, At, Bt) do { __builtin_amdgcn_s_setprio(1); _Pragma("unroll") for (int m = 0; m < 4; ++m) _Pragma("unroll") for (int n = 0; n < 2; ++n) _Pragma("unroll") for (int k = 0; k < 2; ++k) \
;         acc[ai][bj][m][n] = __builtin_amdgcn_mfma_f32_16x16x32_bf16(Bt[n][k], At[m][k], acc[ai][bj][m][n], 0, 0, 0); __builtin_amdgcn_s_setprio(0); } while (0)
; #define PG8_WAIT_V(n) asm volatile("s_waitcnt vmcnt(" #n ")" ::: "memory")
; #define PG8_WAIT_L(n) asm volatile("s_waitcnt lgkmcnt(" #n ")" ::: "memory")
; #define PG8_BAR __builtin_amdgcn_s_barrier()
; #define PG8_SCHED __builtin_amdgcn_sched_barrier(0)
; template <class Epi, class Sched, bool ALIGN_EPI>
; __device__ __forceinline__ void gemm_phase(LAS unsigned char* lds, const Gemm g, const Sched& S, const Epi& E, int wave_id) {
;     ...
;             PG8_LDA(At, 1, 1); PG8_STAGE(PG8_SB(1, 0), b3, voffB); PG8_STAGE(PG8_SB(1, 1), b3 + hsB, voffB); PG8_STAGE(PG8_SA(1, 0), a3, voffA);
;             PG8_WAIT_V(8); PG8_WAIT_L(0); PG8_BAR; PG8_MMA(1, 0, At, B0); PG8_MMA(1, 1, At, B1); PG8_BAR; PG8_SCHED;
;         }
;         if constexpr (ALIGN_EPI) { if (wr == 0) PG8_BAR; }
	s_mov_b32 m0, s58
	v_lshl_add_u64 v[196:197], v[196:197], 0, s[92:93]
	s_add_u32 s42, s42, 0x40080
	global_load_lds_dwordx4 v[196:197], off
	v_lshl_add_u64 v[196:197], v[208:209], 0, s[92:93]
	s_mov_b32 m0, s59
	s_addc_u32 s43, s43, 0
	global_load_lds_dwordx4 v[196:197], off
	v_lshl_add_u64 v[196:197], s[42:43], 0, v[0:1]
	s_mov_b32 m0, s62
	s_nop 0
	global_load_lds_dwordx4 v[196:197], off
	v_lshl_add_u64 v[196:197], s[42:43], 0, v[178:179]
	s_mov_b32 m0, s63
	s_nop 0
	global_load_lds_dwordx4 v[196:197], off
	v_lshl_add_u64 v[196:197], v[210:211], 0, s[92:93]
	s_mov_b32 m0, s60
	s_nop 0
	global_load_lds_dwordx4 v[196:197], off
	v_lshl_add_u64 v[196:197], v[212:213], 0, s[92:93]
	s_mov_b32 m0, s61
	s_nop 0
	global_load_lds_dwordx4 v[196:197], off
	ds_read_b128 v[162:165], v198 offset:50176
	ds_read_b128 v[166:169], v198 offset:51200
	ds_read_b128 v[170:173], v198 offset:52224
	ds_read_b128 v[184:187], v198 offset:53248
	ds_read_b128 v[188:191], v198 offset:54272
	ds_read_b128 v[192:195], v198 offset:55296
	ds_read_b128 v[200:203], v198 offset:56320
	ds_read_b128 v[204:207], v198 offset:57344
	s_waitcnt vmcnt(8)
	s_waitcnt lgkmcnt(0)
	s_setprio 1
	s_barrier
	v_mfma_f32_16x16x32_bf16 v[62:65], v[130:133], v[162:165], v[62:65]
	v_mfma_f32_16x16x32_bf16 v[58:61], v[138:141], v[162:165], v[58:61]
	v_mfma_f32_16x16x32_bf16 v[50:53], v[130:133], v[170:173], v[50:53]
	v_mfma_f32_16x16x32_bf16 v[42:45], v[138:141], v[170:173], v[42:45]
	v_mfma_f32_16x16x32_bf16 v[34:37], v[130:133], v[188:191], v[34:37]
	v_mfma_f32_16x16x32_bf16 v[26:29], v[138:141], v[188:191], v[26:29]
	v_mfma_f32_16x16x32_bf16 v[18:21], v[130:133], v[200:203], v[18:21]
	v_mfma_f32_16x16x32_bf16 v[10:13], v[138:141], v[200:203], v[10:13]
	v_mfma_f32_16x16x32_bf16 v[62:65], v[134:137], v[166:169], v[62:65]
	v_mfma_f32_16x16x32_bf16 v[58:61], v[142:145], v[166:169], v[58:61]
	v_mfma_f32_16x16x32_bf16 v[50:53], v[134:137], v[184:187], v[50:53]
	v_mfma_f32_16x16x32_bf16 v[42:45], v[142:145], v[184:187], v[42:45]
	v_mfma_f32_16x16x32_bf16 v[34:37], v[134:137], v[192:195], v[34:37]
	v_mfma_f32_16x16x32_bf16 v[26:29], v[142:145], v[192:195], v[26:29]
	v_mfma_f32_16x16x32_bf16 v[18:21], v[134:137], v[204:207], v[18:21]
	v_mfma_f32_16x16x32_bf16 v[10:13], v[142:145], v[204:207], v[10:13]
	s_setprio 0
	s_setprio 1
	v_mfma_f32_16x16x32_bf16 v[54:57], v[146:149], v[162:165], v[54:57]
	v_mfma_f32_16x16x32_bf16 v[46:49], v[154:157], v[162:165], v[46:49]
	v_mfma_f32_16x16x32_bf16 v[38:41], v[146:149], v[170:173], v[38:41]
	v_mfma_f32_16x16x32_bf16 v[30:33], v[154:157], v[170:173], v[30:33]
	v_mfma_f32_16x16x32_bf16 v[22:25], v[146:149], v[188:191], v[22:25]
	v_mfma_f32_16x16x32_bf16 v[14:17], v[154:157], v[188:191], v[14:17]
	v_mfma_f32_16x16x32_bf16 v[6:9], v[146:149], v[200:203], v[6:9]
	v_mfma_f32_16x16x32_bf16 v[2:5], v[154:157], v[200:203], v[2:5]
	v_mfma_f32_16x16x32_bf16 v[54:57], v[150:153], v[166:169], v[54:57]
	v_mfma_f32_16x16x32_bf16 v[46:49], v[158:161], v[166:169], v[46:49]
	v_mfma_f32_16x16x32_bf16 v[38:41], v[150:153], v[184:187], v[38:41]
	v_mfma_f32_16x16x32_bf16 v[30:33], v[158:161], v[184:187], v[30:33]
	v_mfma_f32_16x16x32_bf16 v[22:25], v[150:153], v[192:195], v[22:25]
	v_mfma_f32_16x16x32_bf16 v[14:17], v[158:161], v[192:195], v[14:17]
	v_mfma_f32_16x16x32_bf16 v[6:9], v[150:153], v[204:207], v[6:9]
	v_mfma_f32_16x16x32_bf16 v[2:5], v[158:161], v[204:207], v[2:5]
	s_setprio 0
	s_barrier
	s_add_i32 s67, s67, 2
	s_add_u32 s39, s39, 0x100
	s_addc_u32 s66, s66, 0
	s_add_u32 s40, s40, 0x100
	s_addc_u32 s41, s41, 0
	s_cmp_gt_u32 s67, 13
	s_cbranch_scc0 .LBB0_1837
	s_and_b64 vcc, exec, s[22:23]
	s_cbranch_vccz .LBB0_1840
	s_barrier

; #define GAS __attribute__((address_space(1)))
; #define PG8_STAGE(bufoff, gbase, voff) do { _Pragma("unroll") for (int _i = 0; _i < 2; ++_i) \
;         __builtin_amdgcn_global_load_lds((const GAS unsigned*)((const GAS char*)(gbase) + (voff)[_i]), (LAS unsigned*)(lds + (bufoff) + ldsw + _i * 8192), 16, 0, 0); } while (0)
; #define PG8_LDA(dst, b, h) do { _Pragma("unroll") for (int m = 0; m < 4; ++m) _Pragma("unroll") for (int k = 0; k < 2; ++k) dst[m][k] = *(const LAS bf16x8*)(lds + PG8_SA(b, h) + aoff + m * 2048 + k * 1024); } while (0)
; #define PG8_LDB(dst, b, h) do { _Pragma("unroll") for (int n = 0; n < 2; ++n) _Pragma("unroll") for (int k = 0; k < 2; ++k) dst[n][k] = *(const LAS bf16x8*)(lds + PG8_SB(b, h) + boff + n * 2048 + k * 1024); } while (0)
; #define PG8_MMA(ai, bj, At, Bt) do { __builtin_amdgcn_s_setprio(1); _Pragma("unroll") for (int m = 0; m < 4; ++m) _Pragma("unroll") for (int n = 0; n < 2; ++n) _Pragma("unroll") for (int k = 0; k < 2; ++k) \
;         acc[ai][bj][m][n] = __builtin_amdgcn_mfma_f32_16x16x32_bf16(Bt[n][k], At[m][k], acc[ai][bj][m][n], 0, 0, 0); __builtin_amdgcn_s_setprio(0); } while (0)
; #define PG8_WAIT_V(n) asm volatile("s_waitcnt vmcnt(" #n ")" ::: "memory")
; #define PG8_WAIT_L(n) asm volatile("s_waitcnt lgkmcnt(" #n ")" ::: "memory")
; #define PG8_BAR __builtin_amdgcn_s_barrier()
; template <class Epi, class Sched, bool ALIGN_EPI>
; __device__ __forceinline__ void gemm_phase(LAS unsigned char* lds, const Gemm g, const Sched& S, const Epi& E, int wave_id) {
;     ...
;             const bool last = (t == nt - 2);
;             const GAS char* a1 = cA + (size_t)(t + 1) * kstep;
;             const GAS char* a2 = last ? nA : cA + (size_t)(t + 2) * kstep; const GAS char* b2 = last ? nB : cB + (size_t)(t + 2) * kstep;
;             const GAS char* a3 = a2 + kstep; const GAS char* b3 = b2 + kstep;
;             PG8_LDB(B0, 0, 0); PG8_LDB(B1, 0, 1); PG8_SCHED; PG8_LDA(At, 0, 0); PG8_STAGE(PG8_SA(1, 1), a1 + hsA, voffA);
;             PG8_WAIT_V(8); PG8_WAIT_L(0); PG8_BAR; PG8_MMA(0, 0, At, B0); PG8_MMA(0, 1, At, B1); PG8_BAR; PG8_SCHED;
;             PG8_LDA(At, 0, 1); PG8_STAGE(PG8_SB(0, 0), b2, voffB); PG8_STAGE(PG8_SB(0, 1), b2 + hsB, voffB); PG8_STAGE(PG8_SA(0, 0), a2, voffA);
;             PG8_WAIT_V(8); PG8_WAIT_L(0); PG8_BAR; PG8_MMA(1, 0, At, B0); PG8_MMA(1, 1, At, B1); PG8_BAR; PG8_SCHED;
.LBB0_2565:
	s_add_u32 s28, s26, 0xfffc0080
	s_addc_u32 s29, s27, -1
	s_cmp_eq_u32 s60, 12
	s_cselect_b32 s31, s19, s29
	s_cselect_b32 s30, s33, s28
	s_cselect_b32 s29, s17, s59
	s_cselect_b32 s28, s57, s58
	v_lshl_add_u64 v[206:207], s[26:27], 0, v[138:139]
	s_add_i32 m0, s40, 0xc400
	s_nop 0
	global_load_lds_dwordx4 v[206:207], off
	v_lshl_add_u64 v[206:207], s[26:27], 0, v[136:137]
	s_add_i32 m0, s40, 0xe400
	s_nop 0
	global_load_lds_dwordx4 v[206:207], off
	v_add_u32_e32 v154, 0x10400, v153
	v_add_u32_e32 v170, 0x14400, v153
	ds_read_b128 v[140:143], v154
	ds_read_b128 v[144:147], v154 offset:1024
	ds_read_b128 v[148:151], v154 offset:2048
	ds_read_b128 v[154:157], v154 offset:3072
	ds_read_b128 v[158:161], v170
	ds_read_b128 v[162:165], v170 offset:1024
	ds_read_b128 v[166:169], v170 offset:2048
	ds_read_b128 v[170:173], v170 offset:3072
	ds_read_b128 v[174:177], v152 offset:1024
	ds_read_b128 v[178:181], v152 offset:2048
	ds_read_b128 v[182:185], v152 offset:3072
	ds_read_b128 v[186:189], v152 offset:4096
	ds_read_b128 v[190:193], v152 offset:5120
	ds_read_b128 v[194:197], v152 offset:6144
	ds_read_b128 v[198:201], v152 offset:7168
	ds_read_b128 v[202:205], v152 offset:8192
	s_waitcnt vmcnt(8)
	s_waitcnt lgkmcnt(0)
	s_setprio 1
	s_barrier
	v_mfma_f32_16x16x32_bf16 v[126:129], v[140:143], v[174:177], v[126:129]
	v_mfma_f32_16x16x32_bf16 v[122:125], v[148:151], v[174:177], v[122:125]
	v_mfma_f32_16x16x32_bf16 v[110:113], v[140:143], v[182:185], v[110:113]
	v_mfma_f32_16x16x32_bf16 v[106:109], v[148:151], v[182:185], v[106:109]
	v_mfma_f32_16x16x32_bf16 v[94:97], v[140:143], v[190:193], v[94:97]
	v_mfma_f32_16x16x32_bf16 v[90:93], v[148:151], v[190:193], v[90:93]
	v_mfma_f32_16x16x32_bf16 v[78:81], v[140:143], v[198:201], v[78:81]
	v_mfma_f32_16x16x32_bf16 v[74:77], v[148:151], v[198:201], v[74:77]
	v_mfma_f32_16x16x32_bf16 v[126:129], v[144:147], v[178:181], v[126:129]
	v_mfma_f32_16x16x32_bf16 v[122:125], v[154:157], v[178:181], v[122:125]
	v_mfma_f32_16x16x32_bf16 v[110:113], v[144:147], v[186:189], v[110:113]
	v_mfma_f32_16x16x32_bf16 v[106:109], v[154:157], v[186:189], v[106:109]
	v_mfma_f32_16x16x32_bf16 v[94:97], v[144:147], v[194:197], v[94:97]
	v_mfma_f32_16x16x32_bf16 v[90:93], v[154:157], v[194:197], v[90:93]
	v_mfma_f32_16x16x32_bf16 v[78:81], v[144:147], v[202:205], v[78:81]
	v_mfma_f32_16x16x32_bf16 v[74:77], v[154:157], v[202:205], v[74:77]
	s_setprio 0
	s_setprio 1
	v_mfma_f32_16x16x32_bf16 v[118:121], v[158:161], v[174:177], v[118:121]
	v_mfma_f32_16x16x32_bf16 v[114:117], v[166:169], v[174:177], v[114:117]
	v_mfma_f32_16x16x32_bf16 v[102:105], v[158:161], v[182:185], v[102:105]
	v_mfma_f32_16x16x32_bf16 v[98:101], v[166:169], v[182:185], v[98:101]
	v_mfma_f32_16x16x32_bf16 v[86:89], v[158:161], v[190:193], v[86:89]
	v_mfma_f32_16x16x32_bf16 v[82:85], v[166:169], v[190:193], v[82:85]
	v_mfma_f32_16x16x32_bf16 v[70:73], v[158:161], v[198:201], v[70:73]
	v_mfma_f32_16x16x32_bf16 v[66:69], v[166:169], v[198:201], v[66:69]
	v_mfma_f32_16x16x32_bf16 v[118:121], v[162:165], v[178:181], v[118:121]
	v_mfma_f32_16x16x32_bf16 v[114:117], v[170:173], v[178:181], v[114:117]
	v_mfma_f32_16x16x32_bf16 v[102:105], v[162:165], v[186:189], v[102:105]
	v_mfma_f32_16x16x32_bf16 v[98:101], v[170:173], v[186:189], v[98:101]
	v_mfma_f32_16x16x32_bf16 v[86:89], v[162:165], v[194:197], v[86:89]
	v_mfma_f32_16x16x32_bf16 v[82:85], v[170:173], v[194:197], v[82:85]
	v_mfma_f32_16x16x32_bf16 v[70:73], v[162:165], v[202:205], v[70:73]
	v_mfma_f32_16x16x32_bf16 v[66:69], v[170:173], v[202:205], v[66:69]
	s_setprio 0
	s_barrier
	s_mov_b32 m0, s25
	v_lshl_add_u64 v[206:207], s[28:29], 0, v[0:1]
	s_add_u32 s62, s28, 0x40000
	global_load_lds_dwordx4 v[206:207], off
	v_lshl_add_u64 v[208:209], s[28:29], 0, v[130:131]
	s_mov_b32 m0, s41
	s_addc_u32 s63, s29, 0
	global_load_lds_dwordx4 v[208:209], off
	v_lshl_add_u64 v[210:211], s[62:63], 0, v[0:1]
	s_mov_b32 m0, s42
	v_lshl_add_u64 v[212:213], s[30:31], 0, v[132:133]
	global_load_lds_dwordx4 v[210:211], off
	v_lshl_add_u64 v[210:211], s[62:63], 0, v[130:131]
	s_mov_b32 m0, s43
	s_nop 0
	global_load_lds_dwordx4 v[210:211], off
	v_lshl_add_u64 v[210:211], s[30:31], 0, v[134:135]
	s_mov_b32 m0, s44
	s_nop 0
	global_load_lds_dwordx4 v[210:211], off
	s_mov_b32 m0, s45
	s_nop 0
	global_load_lds_dwordx4 v[212:213], off
	ds_read_b128 v[174:177], v152 offset:17408
	ds_read_b128 v[178:181], v152 offset:18432
	ds_read_b128 v[182:185], v152 offset:19456
	ds_read_b128 v[186:189], v152 offset:20480
	ds_read_b128 v[190:193], v152 offset:21504
	ds_read_b128 v[194:197], v152 offset:22528
	ds_read_b128 v[198:201], v152 offset:23552
	ds_read_b128 v[202:205], v152 offset:24576
	s_waitcnt vmcnt(8)
	s_waitcnt lgkmcnt(0)
	s_setprio 1
	s_barrier
; #define PG8_STAGE(bufoff, gbase, voff) do { _Pragma("unroll") for (int _i = 0; _i < 2; ++_i) \
;         __builtin_amdgcn_global_load_lds((const GAS unsigned*)((const GAS char*)(gbase) + (voff)[_i]), (LAS unsigned*)(lds + (bufoff) + ldsw + _i * 8192), 16, 0, 0); } while (0)
; #define PG8_LDA(dst, b, h) do { _Pragma("unroll") for (int m = 0; m < 4; ++m) _Pragma("unroll") for (int k = 0; k < 2; ++k) dst[m][k] = *(const LAS bf16x8*)(lds + PG8_SA(b, h) + aoff + m * 2048 + k * 1024); } while (0)
; #define PG8_LDB(dst, b, h) do { _Pragma("unroll") for (int n = 0; n < 2; ++n) _Pragma("unroll") for (int k = 0; k < 2; ++k) dst[n][k] = *(const LAS bf16x8*)(lds + PG8_SB(b, h) + boff + n * 2048 + k * 1024); } while (0)
; #define PG8_MMA(ai, bj, At, Bt) do { __builtin_amdgcn_s_setprio(1); _Pragma("unroll") for (int m = 0; m < 4; ++m) _Pragma("unroll") for (int n = 0; n < 2; ++n) _Pragma("unroll") for (int k = 0; k < 2; ++k) \
;         acc[ai][bj][m][n] = __builtin_amdgcn_mfma_f32_16x16x32_bf16(Bt[n][k], At[m][k], acc[ai][bj][m][n], 0, 0, 0); __builtin_amdgcn_s_setprio(0); } while (0)
; #define PG8_WAIT_V(n) asm volatile("s_waitcnt vmcnt(" #n ")" ::: "memory")
; #define PG8_WAIT_L(n) asm volatile("s_waitcnt lgkmcnt(" #n ")" ::: "memory")
; #define PG8_BAR __builtin_amdgcn_s_barrier()
; #define PG8_SCHED __builtin_amdgcn_sched_barrier(0)
; template <class Epi, class Sched, bool ALIGN_EPI>
; __device__ __forceinline__ void gemm_phase(LAS unsigned char* lds, const Gemm g, const Sched& S, const Epi& E, int wave_id) {
;     ...
;             PG8_WAIT_V(8); PG8_WAIT_L(0); PG8_BAR; PG8_MMA(1, 0, At, B0); PG8_MMA(1, 1, At, B1); PG8_BAR; PG8_SCHED;
;             PG8_LDB(B0, 1, 0); PG8_LDB(B1, 1, 1); PG8_SCHED; PG8_LDA(At, 1, 0); PG8_STAGE(PG8_SA(0, 1), a2 + hsA, voffA);
;             PG8_WAIT_V(8); PG8_WAIT_L(0); PG8_BAR; PG8_MMA(0, 0, At, B0); PG8_MMA(0, 1, At, B1); PG8_BAR; PG8_SCHED;
	v_mfma_f32_16x16x32_bf16 v[62:65], v[140:143], v[174:177], v[62:65]
	v_mfma_f32_16x16x32_bf16 v[58:61], v[148:151], v[174:177], v[58:61]
	v_mfma_f32_16x16x32_bf16 v[46:49], v[140:143], v[182:185], v[46:49]
	v_mfma_f32_16x16x32_bf16 v[42:45], v[148:151], v[182:185], v[42:45]
	v_mfma_f32_16x16x32_bf16 v[30:33], v[140:143], v[190:193], v[30:33]
	v_mfma_f32_16x16x32_bf16 v[26:29], v[148:151], v[190:193], v[26:29]
	v_mfma_f32_16x16x32_bf16 v[14:17], v[140:143], v[198:201], v[14:17]
	v_mfma_f32_16x16x32_bf16 v[10:13], v[148:151], v[198:201], v[10:13]
	v_mfma_f32_16x16x32_bf16 v[62:65], v[144:147], v[178:181], v[62:65]
	v_mfma_f32_16x16x32_bf16 v[58:61], v[154:157], v[178:181], v[58:61]
	v_mfma_f32_16x16x32_bf16 v[46:49], v[144:147], v[186:189], v[46:49]
	v_mfma_f32_16x16x32_bf16 v[42:45], v[154:157], v[186:189], v[42:45]
	v_mfma_f32_16x16x32_bf16 v[30:33], v[144:147], v[194:197], v[30:33]
	v_mfma_f32_16x16x32_bf16 v[26:29], v[154:157], v[194:197], v[26:29]
	v_mfma_f32_16x16x32_bf16 v[14:17], v[144:147], v[202:205], v[14:17]
	v_mfma_f32_16x16x32_bf16 v[10:13], v[154:157], v[202:205], v[10:13]
	s_setprio 0
	s_setprio 1
	v_mfma_f32_16x16x32_bf16 v[54:57], v[158:161], v[174:177], v[54:57]
	v_mfma_f32_16x16x32_bf16 v[50:53], v[166:169], v[174:177], v[50:53]
	v_mfma_f32_16x16x32_bf16 v[38:41], v[158:161], v[182:185], v[38:41]
	v_mfma_f32_16x16x32_bf16 v[34:37], v[166:169], v[182:185], v[34:37]
	v_mfma_f32_16x16x32_bf16 v[22:25], v[158:161], v[190:193], v[22:25]
	v_mfma_f32_16x16x32_bf16 v[18:21], v[166:169], v[190:193], v[18:21]
	v_mfma_f32_16x16x32_bf16 v[6:9], v[158:161], v[198:201], v[6:9]
	v_mfma_f32_16x16x32_bf16 v[2:5], v[166:169], v[198:201], v[2:5]
	v_mfma_f32_16x16x32_bf16 v[54:57], v[162:165], v[178:181], v[54:57]
	v_mfma_f32_16x16x32_bf16 v[50:53], v[170:173], v[178:181], v[50:53]
	v_mfma_f32_16x16x32_bf16 v[38:41], v[162:165], v[186:189], v[38:41]
	v_mfma_f32_16x16x32_bf16 v[34:37], v[170:173], v[186:189], v[34:37]
	v_mfma_f32_16x16x32_bf16 v[22:25], v[162:165], v[194:197], v[22:25]
	v_mfma_f32_16x16x32_bf16 v[18:21], v[170:173], v[194:197], v[18:21]
	v_mfma_f32_16x16x32_bf16 v[6:9], v[162:165], v[202:205], v[6:9]
	v_mfma_f32_16x16x32_bf16 v[2:5], v[170:173], v[202:205], v[2:5]
	s_setprio 0
	s_barrier
	s_add_u32 s30, s30, 0x40000
	s_addc_u32 s31, s31, 0
	s_mov_b32 m0, s46
	v_lshl_add_u64 v[214:215], s[30:31], 0, v[134:135]
	global_load_lds_dwordx4 v[214:215], off
	v_lshl_add_u64 v[214:215], s[30:31], 0, v[132:133]
	s_mov_b32 m0, s47
	s_nop 0
	global_load_lds_dwordx4 v[214:215], off
	v_add_u32_e32 v154, 0x18400, v153
	v_add_u32_e32 v170, 0x1c400, v153
	ds_read_b128 v[140:143], v154
	ds_read_b128 v[144:147], v154 offset:1024
	ds_read_b128 v[148:151], v154 offset:2048
	ds_read_b128 v[154:157], v154 offset:3072
	ds_read_b128 v[158:161], v170
	ds_read_b128 v[162:165], v170 offset:1024
	ds_read_b128 v[166:169], v170 offset:2048
	ds_read_b128 v[170:173], v170 offset:3072
	ds_read_b128 v[174:177], v152 offset:33792
	ds_read_b128 v[178:181], v152 offset:34816
	ds_read_b128 v[182:185], v152 offset:35840
	ds_read_b128 v[186:189], v152 offset:36864
	ds_read_b128 v[190:193], v152 offset:37888
	ds_read_b128 v[194:197], v152 offset:38912
	ds_read_b128 v[198:201], v152 offset:39936
	ds_read_b128 v[202:205], v152 offset:40960
	s_waitcnt vmcnt(8)
	s_waitcnt lgkmcnt(0)
	s_setprio 1
	s_barrier
	v_mfma_f32_16x16x32_bf16 v[126:129], v[140:143], v[174:177], v[126:129]
	v_mfma_f32_16x16x32_bf16 v[122:125], v[148:151], v[174:177], v[122:125]
	v_mfma_f32_16x16x32_bf16 v[110:113], v[140:143], v[182:185], v[110:113]
	v_mfma_f32_16x16x32_bf16 v[106:109], v[148:151], v[182:185], v[106:109]
	v_mfma_f32_16x16x32_bf16 v[94:97], v[140:143], v[190:193], v[94:97]
	v_mfma_f32_16x16x32_bf16 v[90:93], v[148:151], v[190:193], v[90:93]
	v_mfma_f32_16x16x32_bf16 v[78:81], v[140:143], v[198:201], v[78:81]
	v_mfma_f32_16x16x32_bf16 v[74:77], v[148:151], v[198:201], v[74:77]
	v_mfma_f32_16x16x32_bf16 v[126:129], v[144:147], v[178:181], v[126:129]
	v_mfma_f32_16x16x32_bf16 v[122:125], v[154:157], v[178:181], v[122:125]
	v_mfma_f32_16x16x32_bf16 v[110:113], v[144:147], v[186:189], v[110:113]
	v_mfma_f32_16x16x32_bf16 v[106:109], v[154:157], v[186:189], v[106:109]
	v_mfma_f32_16x16x32_bf16 v[94:97], v[144:147], v[194:197], v[94:97]
	v_mfma_f32_16x16x32_bf16 v[90:93], v[154:157], v[194:197], v[90:93]
	v_mfma_f32_16x16x32_bf16 v[78:81], v[144:147], v[202:205], v[78:81]
	v_mfma_f32_16x16x32_bf16 v[74:77], v[154:157], v[202:205], v[74:77]
	s_setprio 0
	s_setprio 1
	v_mfma_f32_16x16x32_bf16 v[118:121], v[158:161], v[174:177], v[118:121]
	v_mfma_f32_16x16x32_bf16 v[114:117], v[166:169], v[174:177], v[114:117]
	v_mfma_f32_16x16x32_bf16 v[102:105], v[158:161], v[182:185], v[102:105]
	v_mfma_f32_16x16x32_bf16 v[98:101], v[166:169], v[182:185], v[98:101]
	v_mfma_f32_16x16x32_bf16 v[86:89], v[158:161], v[190:193], v[86:89]
	v_mfma_f32_16x16x32_bf16 v[82:85], v[166:169], v[190:193], v[82:85]
	v_mfma_f32_16x16x32_bf16 v[70:73], v[158:161], v[198:201], v[70:73]
	v_mfma_f32_16x16x32_bf16 v[66:69], v[166:169], v[198:201], v[66:69]
	v_mfma_f32_16x16x32_bf16 v[118:121], v[162:165], v[178:181], v[118:121]
	v_mfma_f32_16x16x32_bf16 v[114:117], v[170:173], v[178:181], v[114:117]
	v_mfma_f32_16x16x32_bf16 v[102:105], v[162:165], v[186:189], v[102:105]
	v_mfma_f32_16x16x32_bf16 v[98:101], v[170:173], v[186:189], v[98:101]
	v_mfma_f32_16x16x32_bf16 v[86:89], v[162:165], v[194:197], v[86:89]
	v_mfma_f32_16x16x32_bf16 v[82:85], v[170:173], v[194:197], v[82:85]
	v_mfma_f32_16x16x32_bf16 v[70:73], v[162:165], v[202:205], v[70:73]
	v_mfma_f32_16x16x32_bf16 v[66:69], v[170:173], v[202:205], v[66:69]
	s_setprio 0
	s_barrier
; #define PG8_STAGE(bufoff, gbase, voff) do { _Pragma("unroll") for (int _i = 0; _i < 2; ++_i) \
;         __builtin_amdgcn_global_load_lds((const GAS unsigned*)((const GAS char*)(gbase) + (voff)[_i]), (LAS unsigned*)(lds + (bufoff) + ldsw + _i * 8192), 16, 0, 0); } while (0)
; #define PG8_LDA(dst, b, h) do { _Pragma("unroll") for (int m = 0; m < 4; ++m) _Pragma("unroll") for (int k = 0; k < 2; ++k) dst[m][k] = *(const LAS bf16x8*)(lds + PG8_SA(b, h) + aoff + m * 2048 + k * 1024); } while (0)
; #define PG8_MMA(ai, bj, At, Bt) do { __builtin_amdgcn_s_setprio(1); _Pragma("unroll") for (int m = 0; m < 4; ++m) _Pragma("unroll") for (int n = 0; n < 2; ++n) _Pragma("unroll") for (int k = 0; k < 2; ++k) \
;         acc[ai][bj][m][n] = __builtin_amdgcn_mfma_f32_16x16x32_bf16(Bt[n][k], At[m][k], acc[ai][bj][m][n], 0, 0, 0); __builtin_amdgcn_s_setprio(0); } while (0)
; #define PG8_WAIT_V(n) asm volatile("s_waitcnt vmcnt(" #n ")" ::: "memory")
; #define PG8_WAIT_L(n) asm volatile("s_waitcnt lgkmcnt(" #n ")" ::: "memory")
; #define PG8_BAR __builtin_amdgcn_s_barrier()
; #define PG8_SCHED __builtin_amdgcn_sched_barrier(0)
; template <class Epi, class Sched, bool ALIGN_EPI>
; __device__ __forceinline__ void gemm_phase(LAS unsigned char* lds, const Gemm g, const Sched& S, const Epi& E, int wave_id) {
;     ...
;             PG8_LDA(At, 1, 1); PG8_STAGE(PG8_SB(1, 0), b3, voffB); PG8_STAGE(PG8_SB(1, 1), b3 + hsB, voffB); PG8_STAGE(PG8_SA(1, 0), a3, voffA);
;             PG8_WAIT_V(8); PG8_WAIT_L(0); PG8_BAR; PG8_MMA(1, 0, At, B0); PG8_MMA(1, 1, At, B1); PG8_BAR; PG8_SCHED;
;         }
;         if constexpr (ALIGN_EPI) { if (wr == 0) PG8_BAR; }
	s_mov_b32 m0, s50
	v_lshl_add_u64 v[206:207], v[206:207], 0, s[92:93]
	s_add_u32 s28, s28, 0x40080
	global_load_lds_dwordx4 v[206:207], off
	v_lshl_add_u64 v[206:207], v[208:209], 0, s[92:93]
	s_mov_b32 m0, s51
	s_addc_u32 s29, s29, 0
	global_load_lds_dwordx4 v[206:207], off
	v_lshl_add_u64 v[206:207], s[28:29], 0, v[0:1]
	s_mov_b32 m0, s54
	s_nop 0
	global_load_lds_dwordx4 v[206:207], off
	v_lshl_add_u64 v[206:207], s[28:29], 0, v[130:131]
	s_mov_b32 m0, s55
	s_nop 0
	global_load_lds_dwordx4 v[206:207], off
	v_lshl_add_u64 v[206:207], v[210:211], 0, s[92:93]
	s_mov_b32 m0, s52
	s_nop 0
	global_load_lds_dwordx4 v[206:207], off
	v_lshl_add_u64 v[206:207], v[212:213], 0, s[92:93]
	s_mov_b32 m0, s53
	s_nop 0
	global_load_lds_dwordx4 v[206:207], off
	ds_read_b128 v[174:177], v152 offset:50176
	ds_read_b128 v[178:181], v152 offset:51200
	ds_read_b128 v[182:185], v152 offset:52224
	ds_read_b128 v[186:189], v152 offset:53248
	ds_read_b128 v[190:193], v152 offset:54272
	ds_read_b128 v[194:197], v152 offset:55296
	ds_read_b128 v[198:201], v152 offset:56320
	ds_read_b128 v[202:205], v152 offset:57344
	s_waitcnt vmcnt(8)
	s_waitcnt lgkmcnt(0)
	s_setprio 1
	s_barrier
	v_mfma_f32_16x16x32_bf16 v[62:65], v[140:143], v[174:177], v[62:65]
	v_mfma_f32_16x16x32_bf16 v[58:61], v[148:151], v[174:177], v[58:61]
	v_mfma_f32_16x16x32_bf16 v[46:49], v[140:143], v[182:185], v[46:49]
	v_mfma_f32_16x16x32_bf16 v[42:45], v[148:151], v[182:185], v[42:45]
	v_mfma_f32_16x16x32_bf16 v[30:33], v[140:143], v[190:193], v[30:33]
	v_mfma_f32_16x16x32_bf16 v[26:29], v[148:151], v[190:193], v[26:29]
	v_mfma_f32_16x16x32_bf16 v[14:17], v[140:143], v[198:201], v[14:17]
	v_mfma_f32_16x16x32_bf16 v[10:13], v[148:151], v[198:201], v[10:13]
	v_mfma_f32_16x16x32_bf16 v[62:65], v[144:147], v[178:181], v[62:65]
	v_mfma_f32_16x16x32_bf16 v[58:61], v[154:157], v[178:181], v[58:61]
	v_mfma_f32_16x16x32_bf16 v[46:49], v[144:147], v[186:189], v[46:49]
	v_mfma_f32_16x16x32_bf16 v[42:45], v[154:157], v[186:189], v[42:45]
	v_mfma_f32_16x16x32_bf16 v[30:33], v[144:147], v[194:197], v[30:33]
	v_mfma_f32_16x16x32_bf16 v[26:29], v[154:157], v[194:197], v[26:29]
	v_mfma_f32_16x16x32_bf16 v[14:17], v[144:147], v[202:205], v[14:17]
	v_mfma_f32_16x16x32_bf16 v[10:13], v[154:157], v[202:205], v[10:13]
	s_setprio 0
	s_setprio 1
	v_mfma_f32_16x16x32_bf16 v[54:57], v[158:161], v[174:177], v[54:57]
	v_mfma_f32_16x16x32_bf16 v[50:53], v[166:169], v[174:177], v[50:53]
	v_mfma_f32_16x16x32_bf16 v[38:41], v[158:161], v[182:185], v[38:41]
	v_mfma_f32_16x16x32_bf16 v[34:37], v[166:169], v[182:185], v[34:37]
	v_mfma_f32_16x16x32_bf16 v[22:25], v[158:161], v[190:193], v[22:25]
	v_mfma_f32_16x16x32_bf16 v[18:21], v[166:169], v[190:193], v[18:21]
	v_mfma_f32_16x16x32_bf16 v[6:9], v[158:161], v[198:201], v[6:9]
	v_mfma_f32_16x16x32_bf16 v[2:5], v[166:169], v[198:201], v[2:5]
	v_mfma_f32_16x16x32_bf16 v[54:57], v[162:165], v[178:181], v[54:57]
	v_mfma_f32_16x16x32_bf16 v[50:53], v[170:173], v[178:181], v[50:53]
	v_mfma_f32_16x16x32_bf16 v[38:41], v[162:165], v[186:189], v[38:41]
	v_mfma_f32_16x16x32_bf16 v[34:37], v[170:173], v[186:189], v[34:37]
	v_mfma_f32_16x16x32_bf16 v[22:25], v[162:165], v[194:197], v[22:25]
	v_mfma_f32_16x16x32_bf16 v[18:21], v[170:173], v[194:197], v[18:21]
	v_mfma_f32_16x16x32_bf16 v[6:9], v[162:165], v[202:205], v[6:9]
	v_mfma_f32_16x16x32_bf16 v[2:5], v[170:173], v[202:205], v[2:5]
	s_setprio 0
	s_barrier
	s_add_i32 s60, s60, 2
	s_add_u32 s58, s58, 0x100
	s_addc_u32 s59, s59, 0
	s_add_u32 s26, s26, 0x100
	s_addc_u32 s27, s27, 0
	s_cmp_gt_u32 s60, 13
	s_cbranch_scc0 .LBB0_2565
	s_and_b64 vcc, exec, s[14:15]
	s_cbranch_vccz .LBB0_2568
	s_barrier

; #define GAS __attribute__((address_space(1)))
; #define PG8_STAGE(bufoff, gbase, voff) do { _Pragma("unroll") for (int _i = 0; _i < 2; ++_i) \
;         __builtin_amdgcn_global_load_lds((const GAS unsigned*)((const GAS char*)(gbase) + (voff)[_i]), (LAS unsigned*)(lds + (bufoff) + ldsw + _i * 8192), 16, 0, 0); } while (0)
; #define PG8_LDA(dst, b, h) do { _Pragma("unroll") for (int m = 0; m < 4; ++m) _Pragma("unroll") for (int k = 0; k < 2; ++k) dst[m][k] = *(const LAS bf16x8*)(lds + PG8_SA(b, h) + aoff + m * 2048 + k * 1024); } while (0)
; #define PG8_LDB(dst, b, h) do { _Pragma("unroll") for (int n = 0; n < 2; ++n) _Pragma("unroll") for (int k = 0; k < 2; ++k) dst[n][k] = *(const LAS bf16x8*)(lds + PG8_SB(b, h) + boff + n * 2048 + k * 1024); } while (0)
; #define PG8_MMA(ai, bj, At, Bt) do { __builtin_amdgcn_s_setprio(1); _Pragma("unroll") for (int m = 0; m < 4; ++m) _Pragma("unroll") for (int n = 0; n < 2; ++n) _Pragma("unroll") for (int k = 0; k < 2; ++k) \
;         acc[ai][bj][m][n] = __builtin_amdgcn_mfma_f32_16x16x32_bf16(Bt[n][k], At[m][k], acc[ai][bj][m][n], 0, 0, 0); __builtin_amdgcn_s_setprio(0); } while (0)
; #define PG8_WAIT_V(n) asm volatile("s_waitcnt vmcnt(" #n ")" ::: "memory")
; #define PG8_WAIT_L(n) asm volatile("s_waitcnt lgkmcnt(" #n ")" ::: "memory")
; #define PG8_BAR __builtin_amdgcn_s_barrier()
; template <class Epi, class Sched, bool ALIGN_EPI>
; __device__ __forceinline__ void gemm_phase(LAS unsigned char* lds, const Gemm g, const Sched& S, const Epi& E, int wave_id) {
;     ...
;             const bool last = (t == nt - 2);
;             const GAS char* a1 = cA + (size_t)(t + 1) * kstep;
;             const GAS char* a2 = last ? nA : cA + (size_t)(t + 2) * kstep; const GAS char* b2 = last ? nB : cB + (size_t)(t + 2) * kstep;
;             const GAS char* a3 = a2 + kstep; const GAS char* b3 = b2 + kstep;
;             PG8_LDB(B0, 0, 0); PG8_LDB(B1, 0, 1); PG8_SCHED; PG8_LDA(At, 0, 0); PG8_STAGE(PG8_SA(1, 1), a1 + hsA, voffA);
;             PG8_WAIT_V(8); PG8_WAIT_L(0); PG8_BAR; PG8_MMA(0, 0, At, B0); PG8_MMA(0, 1, At, B1); PG8_BAR; PG8_SCHED;
;             PG8_LDA(At, 0, 1); PG8_STAGE(PG8_SB(0, 0), b2, voffB); PG8_STAGE(PG8_SB(0, 1), b2 + hsB, voffB); PG8_STAGE(PG8_SA(0, 0), a2, voffA);
;             PG8_WAIT_V(8); PG8_WAIT_L(0); PG8_BAR; PG8_MMA(1, 0, At, B0); PG8_MMA(1, 1, At, B1); PG8_BAR; PG8_SCHED;
.LBB0_2620:
	s_add_u32 s38, s36, 0xfff80080
	s_addc_u32 s39, s37, -1
	s_cmp_eq_u32 s65, 28
	s_cselect_b32 s41, s1, s39
	s_cselect_b32 s40, s5, s38
	s_cselect_b32 s39, s7, s33
	s_cselect_b32 s38, s27, s29
	v_lshl_add_u64 v[194:195], s[36:37], 0, v[218:219]
	s_add_i32 m0, s43, 0xc400
	s_nop 0
	global_load_lds_dwordx4 v[194:195], off
	v_lshl_add_u64 v[194:195], s[36:37], 0, v[216:217]
	s_add_i32 m0, s43, 0xe400
	s_nop 0
	global_load_lds_dwordx4 v[194:195], off
	v_add_u32_e32 v46, 0x10400, v235
	v_add_u32_e32 v62, 0x14400, v235
	ds_read_b128 v[34:37], v46
	ds_read_b128 v[38:41], v46 offset:1024
	ds_read_b128 v[42:45], v46 offset:2048
	ds_read_b128 v[46:49], v46 offset:3072
	ds_read_b128 v[50:53], v62
	ds_read_b128 v[54:57], v62 offset:1024
	ds_read_b128 v[58:61], v62 offset:2048
	ds_read_b128 v[62:65], v62 offset:3072
	ds_read_b128 v[82:85], v234 offset:1024
	ds_read_b128 v[94:97], v234 offset:2048
	ds_read_b128 v[170:173], v234 offset:3072
	ds_read_b128 v[174:177], v234 offset:4096
	ds_read_b128 v[178:181], v234 offset:5120
	ds_read_b128 v[182:185], v234 offset:6144
	ds_read_b128 v[186:189], v234 offset:7168
	ds_read_b128 v[190:193], v234 offset:8192
	s_waitcnt vmcnt(8)
	s_waitcnt lgkmcnt(0)
	s_setprio 1
	s_barrier
	v_mfma_f32_16x16x32_bf16 v[166:169], v[34:37], v[82:85], v[166:169]
	v_mfma_f32_16x16x32_bf16 v[162:165], v[42:45], v[82:85], v[162:165]
	v_mfma_f32_16x16x32_bf16 v[150:153], v[34:37], v[170:173], v[150:153]
	v_mfma_f32_16x16x32_bf16 v[146:149], v[42:45], v[170:173], v[146:149]
	v_mfma_f32_16x16x32_bf16 v[134:137], v[34:37], v[178:181], v[134:137]
	v_mfma_f32_16x16x32_bf16 v[130:133], v[42:45], v[178:181], v[130:133]
	v_mfma_f32_16x16x32_bf16 v[118:121], v[34:37], v[186:189], v[118:121]
	v_mfma_f32_16x16x32_bf16 v[114:117], v[42:45], v[186:189], v[114:117]
	v_mfma_f32_16x16x32_bf16 v[166:169], v[38:41], v[94:97], v[166:169]
	v_mfma_f32_16x16x32_bf16 v[162:165], v[46:49], v[94:97], v[162:165]
	v_mfma_f32_16x16x32_bf16 v[150:153], v[38:41], v[174:177], v[150:153]
	v_mfma_f32_16x16x32_bf16 v[146:149], v[46:49], v[174:177], v[146:149]
	v_mfma_f32_16x16x32_bf16 v[134:137], v[38:41], v[182:185], v[134:137]
	v_mfma_f32_16x16x32_bf16 v[130:133], v[46:49], v[182:185], v[130:133]
	v_mfma_f32_16x16x32_bf16 v[118:121], v[38:41], v[190:193], v[118:121]
	v_mfma_f32_16x16x32_bf16 v[114:117], v[46:49], v[190:193], v[114:117]
	s_setprio 0
	s_setprio 1
	v_mfma_f32_16x16x32_bf16 v[158:161], v[50:53], v[82:85], v[158:161]
	v_mfma_f32_16x16x32_bf16 v[82:85], v[58:61], v[82:85], v[154:157]
	v_mfma_f32_16x16x32_bf16 v[138:141], v[58:61], v[170:173], v[138:141]
	v_mfma_f32_16x16x32_bf16 v[126:129], v[50:53], v[178:181], v[126:129]
	v_mfma_f32_16x16x32_bf16 v[122:125], v[58:61], v[178:181], v[122:125]
	v_mfma_f32_16x16x32_bf16 v[110:113], v[50:53], v[186:189], v[110:113]
	v_mfma_f32_16x16x32_bf16 v[106:109], v[58:61], v[186:189], v[106:109]
	v_mfma_f32_16x16x32_bf16 v[158:161], v[54:57], v[94:97], v[158:161]
	v_mfma_f32_16x16x32_bf16 v[82:85], v[62:65], v[94:97], v[82:85]
	v_mfma_f32_16x16x32_bf16 v[94:97], v[50:53], v[170:173], v[142:145]
	v_mfma_f32_16x16x32_bf16 v[138:141], v[62:65], v[174:177], v[138:141]
	v_mfma_f32_16x16x32_bf16 v[126:129], v[54:57], v[182:185], v[126:129]
	v_mfma_f32_16x16x32_bf16 v[122:125], v[62:65], v[182:185], v[122:125]
	v_mfma_f32_16x16x32_bf16 v[110:113], v[54:57], v[190:193], v[110:113]
	v_mfma_f32_16x16x32_bf16 v[106:109], v[62:65], v[190:193], v[106:109]
	v_mfma_f32_16x16x32_bf16 v[94:97], v[54:57], v[174:177], v[94:97]
	s_setprio 0
	s_barrier
	s_mov_b32 m0, s48
	v_lshl_add_u64 v[202:203], s[38:39], 0, v[0:1]
	s_add_u32 s66, s38, 0x80000
	global_load_lds_dwordx4 v[202:203], off
	v_lshl_add_u64 v[204:205], s[38:39], 0, v[210:211]
	s_mov_b32 m0, s49
	s_addc_u32 s67, s39, 0
	global_load_lds_dwordx4 v[204:205], off
	v_lshl_add_u64 v[194:195], s[66:67], 0, v[0:1]
	s_mov_b32 m0, s50
	v_lshl_add_u64 v[220:221], s[40:41], 0, v[206:207]
	global_load_lds_dwordx4 v[194:195], off
	v_lshl_add_u64 v[194:195], s[66:67], 0, v[210:211]
	s_mov_b32 m0, s51
	v_lshl_add_u64 v[224:225], s[40:41], 0, v[208:209]
	global_load_lds_dwordx4 v[194:195], off
	s_mov_b32 m0, s52
	s_nop 0
	global_load_lds_dwordx4 v[220:221], off
	s_mov_b32 m0, s53
	s_nop 0
	global_load_lds_dwordx4 v[224:225], off
	ds_read_b128 v[142:145], v234 offset:17408
	ds_read_b128 v[154:157], v234 offset:18432
	ds_read_b128 v[170:173], v234 offset:19456
	ds_read_b128 v[174:177], v234 offset:20480
	ds_read_b128 v[178:181], v234 offset:21504
	ds_read_b128 v[182:185], v234 offset:22528
	ds_read_b128 v[186:189], v234 offset:23552
	ds_read_b128 v[190:193], v234 offset:24576
	s_waitcnt vmcnt(8)
	s_waitcnt lgkmcnt(0)
	s_setprio 1
	s_barrier
; #define PG8_STAGE(bufoff, gbase, voff) do { _Pragma("unroll") for (int _i = 0; _i < 2; ++_i) \
;         __builtin_amdgcn_global_load_lds((const GAS unsigned*)((const GAS char*)(gbase) + (voff)[_i]), (LAS unsigned*)(lds + (bufoff) + ldsw + _i * 8192), 16, 0, 0); } while (0)
; #define PG8_LDA(dst, b, h) do { _Pragma("unroll") for (int m = 0; m < 4; ++m) _Pragma("unroll") for (int k = 0; k < 2; ++k) dst[m][k] = *(const LAS bf16x8*)(lds + PG8_SA(b, h) + aoff + m * 2048 + k * 1024); } while (0)
; #define PG8_LDB(dst, b, h) do { _Pragma("unroll") for (int n = 0; n < 2; ++n) _Pragma("unroll") for (int k = 0; k < 2; ++k) dst[n][k] = *(const LAS bf16x8*)(lds + PG8_SB(b, h) + boff + n * 2048 + k * 1024); } while (0)
; #define PG8_MMA(ai, bj, At, Bt) do { __builtin_amdgcn_s_setprio(1); _Pragma("unroll") for (int m = 0; m < 4; ++m) _Pragma("unroll") for (int n = 0; n < 2; ++n) _Pragma("unroll") for (int k = 0; k < 2; ++k) \
;         acc[ai][bj][m][n] = __builtin_amdgcn_mfma_f32_16x16x32_bf16(Bt[n][k], At[m][k], acc[ai][bj][m][n], 0, 0, 0); __builtin_amdgcn_s_setprio(0); } while (0)
; #define PG8_WAIT_V(n) asm volatile("s_waitcnt vmcnt(" #n ")" ::: "memory")
; #define PG8_WAIT_L(n) asm volatile("s_waitcnt lgkmcnt(" #n ")" ::: "memory")
; #define PG8_BAR __builtin_amdgcn_s_barrier()
; #define PG8_SCHED __builtin_amdgcn_sched_barrier(0)
; template <class Epi, class Sched, bool ALIGN_EPI>
; __device__ __forceinline__ void gemm_phase(LAS unsigned char* lds, const Gemm g, const Sched& S, const Epi& E, int wave_id) {
;     ...
;             PG8_WAIT_V(8); PG8_WAIT_L(0); PG8_BAR; PG8_MMA(1, 0, At, B0); PG8_MMA(1, 1, At, B1); PG8_BAR; PG8_SCHED;
;             PG8_LDB(B0, 1, 0); PG8_LDB(B1, 1, 1); PG8_SCHED; PG8_LDA(At, 1, 0); PG8_STAGE(PG8_SA(0, 1), a2 + hsA, voffA);
;             PG8_WAIT_V(8); PG8_WAIT_L(0); PG8_BAR; PG8_MMA(0, 0, At, B0); PG8_MMA(0, 1, At, B1); PG8_BAR; PG8_SCHED;
	v_mfma_f32_16x16x32_bf16 v[102:105], v[34:37], v[142:145], v[102:105]
	v_mfma_f32_16x16x32_bf16 v[98:101], v[42:45], v[142:145], v[98:101]
	v_mfma_f32_16x16x32_bf16 v[78:81], v[34:37], v[170:173], v[78:81]
	v_mfma_f32_16x16x32_bf16 v[74:77], v[42:45], v[170:173], v[74:77]
	v_mfma_f32_16x16x32_bf16 v[30:33], v[34:37], v[178:181], v[30:33]
	v_mfma_f32_16x16x32_bf16 v[26:29], v[42:45], v[178:181], v[26:29]
	v_mfma_f32_16x16x32_bf16 v[14:17], v[34:37], v[186:189], v[14:17]
	v_mfma_f32_16x16x32_bf16 v[10:13], v[42:45], v[186:189], v[10:13]
	v_mfma_f32_16x16x32_bf16 v[102:105], v[38:41], v[154:157], v[102:105]
	v_mfma_f32_16x16x32_bf16 v[98:101], v[46:49], v[154:157], v[98:101]
	v_mfma_f32_16x16x32_bf16 v[78:81], v[38:41], v[174:177], v[78:81]
	v_mfma_f32_16x16x32_bf16 v[74:77], v[46:49], v[174:177], v[74:77]
	v_mfma_f32_16x16x32_bf16 v[30:33], v[38:41], v[182:185], v[30:33]
	v_mfma_f32_16x16x32_bf16 v[26:29], v[46:49], v[182:185], v[26:29]
	v_mfma_f32_16x16x32_bf16 v[14:17], v[38:41], v[190:193], v[14:17]
	v_mfma_f32_16x16x32_bf16 v[10:13], v[46:49], v[190:193], v[10:13]
	s_setprio 0
	s_setprio 1
	v_mfma_f32_16x16x32_bf16 v[22:25], v[50:53], v[178:181], v[22:25]
	v_mfma_f32_16x16x32_bf16 v[18:21], v[58:61], v[178:181], v[18:21]
	v_mfma_f32_16x16x32_bf16 v[6:9], v[50:53], v[186:189], v[6:9]
	v_mfma_f32_16x16x32_bf16 v[2:5], v[58:61], v[186:189], v[2:5]
	v_mfma_f32_16x16x32_bf16 v[34:37], v[50:53], v[142:145], v[90:93]
	v_mfma_f32_16x16x32_bf16 v[38:41], v[58:61], v[142:145], v[86:89]
	v_mfma_f32_16x16x32_bf16 v[42:45], v[50:53], v[170:173], v[70:73]
	v_mfma_f32_16x16x32_bf16 v[46:49], v[58:61], v[170:173], v[66:69]
	v_mfma_f32_16x16x32_bf16 v[22:25], v[54:57], v[182:185], v[22:25]
	v_mfma_f32_16x16x32_bf16 v[18:21], v[62:65], v[182:185], v[18:21]
	v_mfma_f32_16x16x32_bf16 v[6:9], v[54:57], v[190:193], v[6:9]
	v_mfma_f32_16x16x32_bf16 v[2:5], v[62:65], v[190:193], v[2:5]
	v_mfma_f32_16x16x32_bf16 v[34:37], v[54:57], v[154:157], v[34:37]
	v_mfma_f32_16x16x32_bf16 v[38:41], v[62:65], v[154:157], v[38:41]
	v_mfma_f32_16x16x32_bf16 v[42:45], v[54:57], v[174:177], v[42:45]
	v_mfma_f32_16x16x32_bf16 v[46:49], v[62:65], v[174:177], v[46:49]
	s_setprio 0
	s_barrier
	s_add_u32 s40, s40, 0x80000
	s_addc_u32 s41, s41, 0
	s_mov_b32 m0, s54
	v_lshl_add_u64 v[142:143], s[40:41], 0, v[206:207]
	global_load_lds_dwordx4 v[142:143], off
	v_lshl_add_u64 v[142:143], s[40:41], 0, v[208:209]
	s_mov_b32 m0, s55
	s_nop 0
	global_load_lds_dwordx4 v[142:143], off
	v_add_u32_e32 v62, 0x18400, v235
	v_add_u32_e32 v66, 0x1c400, v235
	ds_read_b128 v[50:53], v62
	ds_read_b128 v[54:57], v62 offset:1024
	ds_read_b128 v[58:61], v62 offset:2048
	ds_read_b128 v[62:65], v62 offset:3072
	ds_read_b128 v[170:173], v66
	ds_read_b128 v[174:177], v66 offset:1024
	ds_read_b128 v[178:181], v66 offset:2048
	ds_read_b128 v[182:185], v66 offset:3072
	ds_read_b128 v[66:69], v234 offset:33792
	ds_read_b128 v[70:73], v234 offset:34816
	ds_read_b128 v[86:89], v234 offset:35840
	ds_read_b128 v[90:93], v234 offset:36864
	ds_read_b128 v[186:189], v234 offset:37888
	ds_read_b128 v[190:193], v234 offset:38912
	ds_read_b128 v[194:197], v234 offset:39936
	ds_read_b128 v[198:201], v234 offset:40960
	s_waitcnt vmcnt(8)
	s_waitcnt lgkmcnt(0)
	s_setprio 1
	s_barrier
	v_mfma_f32_16x16x32_bf16 v[142:145], v[50:53], v[66:69], v[166:169]
	v_mfma_f32_16x16x32_bf16 v[166:169], v[54:57], v[70:73], v[142:145]
	v_mfma_f32_16x16x32_bf16 v[142:145], v[58:61], v[66:69], v[162:165]
	v_mfma_f32_16x16x32_bf16 v[162:165], v[62:65], v[70:73], v[142:145]
	v_mfma_f32_16x16x32_bf16 v[142:145], v[50:53], v[86:89], v[150:153]
	v_mfma_f32_16x16x32_bf16 v[150:153], v[54:57], v[90:93], v[142:145]
	v_mfma_f32_16x16x32_bf16 v[142:145], v[58:61], v[86:89], v[146:149]
	v_mfma_f32_16x16x32_bf16 v[134:137], v[50:53], v[186:189], v[134:137]
	v_mfma_f32_16x16x32_bf16 v[130:133], v[58:61], v[186:189], v[130:133]
	v_mfma_f32_16x16x32_bf16 v[118:121], v[50:53], v[194:197], v[118:121]
	v_mfma_f32_16x16x32_bf16 v[114:117], v[58:61], v[194:197], v[114:117]
	v_mfma_f32_16x16x32_bf16 v[146:149], v[62:65], v[90:93], v[142:145]
	v_mfma_f32_16x16x32_bf16 v[134:137], v[54:57], v[190:193], v[134:137]
	v_mfma_f32_16x16x32_bf16 v[130:133], v[62:65], v[190:193], v[130:133]
	v_mfma_f32_16x16x32_bf16 v[118:121], v[54:57], v[198:201], v[118:121]
	v_mfma_f32_16x16x32_bf16 v[114:117], v[62:65], v[198:201], v[114:117]
	s_setprio 0
	s_setprio 1
	v_mfma_f32_16x16x32_bf16 v[142:145], v[170:173], v[66:69], v[158:161]
	v_mfma_f32_16x16x32_bf16 v[66:69], v[178:181], v[66:69], v[82:85]
	v_mfma_f32_16x16x32_bf16 v[154:157], v[182:185], v[70:73], v[66:69]
	v_mfma_f32_16x16x32_bf16 v[66:69], v[170:173], v[86:89], v[94:97]
	v_mfma_f32_16x16x32_bf16 v[158:161], v[174:177], v[70:73], v[142:145]
	v_mfma_f32_16x16x32_bf16 v[142:145], v[174:177], v[90:93], v[66:69]
	v_mfma_f32_16x16x32_bf16 v[66:69], v[178:181], v[86:89], v[138:141]
	v_mfma_f32_16x16x32_bf16 v[138:141], v[182:185], v[90:93], v[66:69]
	v_mfma_f32_16x16x32_bf16 v[66:69], v[170:173], v[186:189], v[126:129]
	v_mfma_f32_16x16x32_bf16 v[126:129], v[174:177], v[190:193], v[66:69]
	v_mfma_f32_16x16x32_bf16 v[66:69], v[178:181], v[186:189], v[122:125]
	v_mfma_f32_16x16x32_bf16 v[122:125], v[182:185], v[190:193], v[66:69]
	v_mfma_f32_16x16x32_bf16 v[66:69], v[170:173], v[194:197], v[110:113]
	v_mfma_f32_16x16x32_bf16 v[110:113], v[174:177], v[198:201], v[66:69]
	v_mfma_f32_16x16x32_bf16 v[66:69], v[178:181], v[194:197], v[106:109]
	v_mfma_f32_16x16x32_bf16 v[106:109], v[182:185], v[198:201], v[66:69]
	s_setprio 0
	s_barrier
; #define PG8_STAGE(bufoff, gbase, voff) do { _Pragma("unroll") for (int _i = 0; _i < 2; ++_i) \
;         __builtin_amdgcn_global_load_lds((const GAS unsigned*)((const GAS char*)(gbase) + (voff)[_i]), (LAS unsigned*)(lds + (bufoff) + ldsw + _i * 8192), 16, 0, 0); } while (0)
; #define PG8_LDA(dst, b, h) do { _Pragma("unroll") for (int m = 0; m < 4; ++m) _Pragma("unroll") for (int k = 0; k < 2; ++k) dst[m][k] = *(const LAS bf16x8*)(lds + PG8_SA(b, h) + aoff + m * 2048 + k * 1024); } while (0)
; #define PG8_MMA(ai, bj, At, Bt) do { __builtin_amdgcn_s_setprio(1); _Pragma("unroll") for (int m = 0; m < 4; ++m) _Pragma("unroll") for (int n = 0; n < 2; ++n) _Pragma("unroll") for (int k = 0; k < 2; ++k) \
;         acc[ai][bj][m][n] = __builtin_amdgcn_mfma_f32_16x16x32_bf16(Bt[n][k], At[m][k], acc[ai][bj][m][n], 0, 0, 0); __builtin_amdgcn_s_setprio(0); } while (0)
; #define PG8_WAIT_V(n) asm volatile("s_waitcnt vmcnt(" #n ")" ::: "memory")
; #define PG8_WAIT_L(n) asm volatile("s_waitcnt lgkmcnt(" #n ")" ::: "memory")
; #define PG8_BAR __builtin_amdgcn_s_barrier()
; #define PG8_SCHED __builtin_amdgcn_sched_barrier(0)
; template <class Epi, class Sched, bool ALIGN_EPI>
; __device__ __forceinline__ void gemm_phase(LAS unsigned char* lds, const Gemm g, const Sched& S, const Epi& E, int wave_id) {
;     ...
;             PG8_LDA(At, 1, 1); PG8_STAGE(PG8_SB(1, 0), b3, voffB); PG8_STAGE(PG8_SB(1, 1), b3 + hsB, voffB); PG8_STAGE(PG8_SA(1, 0), a3, voffA);
;             PG8_WAIT_V(8); PG8_WAIT_L(0); PG8_BAR; PG8_MMA(1, 0, At, B0); PG8_MMA(1, 1, At, B1); PG8_BAR; PG8_SCHED;
;         }
;         if constexpr (ALIGN_EPI) { if (wr == 0) PG8_BAR; }
	s_mov_b32 m0, s58
	v_lshl_add_u64 v[86:87], v[202:203], 0, s[92:93]
	s_add_u32 s38, s38, 0x80080
	s_nop 1
	global_load_lds_dwordx4 v[86:87], off
	v_lshl_add_u64 v[86:87], v[204:205], 0, s[92:93]
	s_mov_b32 m0, s59
	s_addc_u32 s39, s39, 0
	global_load_lds_dwordx4 v[86:87], off
	v_lshl_add_u64 v[86:87], s[38:39], 0, v[0:1]
	s_mov_b32 m0, s62
	s_nop 0
	global_load_lds_dwordx4 v[86:87], off
	v_lshl_add_u64 v[86:87], s[38:39], 0, v[210:211]
	s_mov_b32 m0, s63
	s_nop 0
	global_load_lds_dwordx4 v[86:87], off
	v_lshl_add_u64 v[86:87], v[220:221], 0, s[92:93]
	s_mov_b32 m0, s60
	s_nop 0
	global_load_lds_dwordx4 v[86:87], off
	v_lshl_add_u64 v[86:87], v[224:225], 0, s[92:93]
	s_mov_b32 m0, s61
	s_nop 0
	global_load_lds_dwordx4 v[86:87], off
	ds_read_b128 v[66:69], v234 offset:50176
	ds_read_b128 v[70:73], v234 offset:51200
	ds_read_b128 v[82:85], v234 offset:52224
	ds_read_b128 v[94:97], v234 offset:53248
	ds_read_b128 v[186:189], v234 offset:54272
	ds_read_b128 v[190:193], v234 offset:55296
	ds_read_b128 v[194:197], v234 offset:56320
	ds_read_b128 v[198:201], v234 offset:57344
	s_waitcnt vmcnt(8)
	s_waitcnt lgkmcnt(0)
	s_setprio 1
	s_barrier
	v_mfma_f32_16x16x32_bf16 v[86:89], v[50:53], v[66:69], v[102:105]
	v_mfma_f32_16x16x32_bf16 v[102:105], v[54:57], v[70:73], v[86:89]
	v_mfma_f32_16x16x32_bf16 v[86:89], v[58:61], v[66:69], v[98:101]
	v_mfma_f32_16x16x32_bf16 v[78:81], v[50:53], v[82:85], v[78:81]
	v_mfma_f32_16x16x32_bf16 v[74:77], v[58:61], v[82:85], v[74:77]
	v_mfma_f32_16x16x32_bf16 v[30:33], v[50:53], v[186:189], v[30:33]
	v_mfma_f32_16x16x32_bf16 v[26:29], v[58:61], v[186:189], v[26:29]
	v_mfma_f32_16x16x32_bf16 v[14:17], v[50:53], v[194:197], v[14:17]
	v_mfma_f32_16x16x32_bf16 v[10:13], v[58:61], v[194:197], v[10:13]
	v_mfma_f32_16x16x32_bf16 v[98:101], v[62:65], v[70:73], v[86:89]
	v_mfma_f32_16x16x32_bf16 v[78:81], v[54:57], v[94:97], v[78:81]
	v_mfma_f32_16x16x32_bf16 v[74:77], v[62:65], v[94:97], v[74:77]
	v_mfma_f32_16x16x32_bf16 v[30:33], v[54:57], v[190:193], v[30:33]
	v_mfma_f32_16x16x32_bf16 v[26:29], v[62:65], v[190:193], v[26:29]
	v_mfma_f32_16x16x32_bf16 v[14:17], v[54:57], v[198:201], v[14:17]
	v_mfma_f32_16x16x32_bf16 v[10:13], v[62:65], v[198:201], v[10:13]
	s_setprio 0
	s_setprio 1
	v_mfma_f32_16x16x32_bf16 v[34:37], v[170:173], v[66:69], v[34:37]
	v_mfma_f32_16x16x32_bf16 v[90:93], v[174:177], v[70:73], v[34:37]
	v_mfma_f32_16x16x32_bf16 v[34:37], v[178:181], v[66:69], v[38:41]
	v_mfma_f32_16x16x32_bf16 v[86:89], v[182:185], v[70:73], v[34:37]
	v_mfma_f32_16x16x32_bf16 v[34:37], v[170:173], v[82:85], v[42:45]
	v_mfma_f32_16x16x32_bf16 v[70:73], v[174:177], v[94:97], v[34:37]
	v_mfma_f32_16x16x32_bf16 v[34:37], v[178:181], v[82:85], v[46:49]
	v_mfma_f32_16x16x32_bf16 v[22:25], v[170:173], v[186:189], v[22:25]
	v_mfma_f32_16x16x32_bf16 v[18:21], v[178:181], v[186:189], v[18:21]
	v_mfma_f32_16x16x32_bf16 v[6:9], v[170:173], v[194:197], v[6:9]
	v_mfma_f32_16x16x32_bf16 v[2:5], v[178:181], v[194:197], v[2:5]
	v_mfma_f32_16x16x32_bf16 v[66:69], v[182:185], v[94:97], v[34:37]
	v_mfma_f32_16x16x32_bf16 v[22:25], v[174:177], v[190:193], v[22:25]
	v_mfma_f32_16x16x32_bf16 v[18:21], v[182:185], v[190:193], v[18:21]
	v_mfma_f32_16x16x32_bf16 v[6:9], v[174:177], v[198:201], v[6:9]
	v_mfma_f32_16x16x32_bf16 v[2:5], v[182:185], v[198:201], v[2:5]
	s_setprio 0
	s_barrier
	s_add_i32 s65, s65, 2
	s_add_u32 s29, s29, 0x100
	s_addc_u32 s33, s33, 0
	s_add_u32 s36, s36, 0x100
	s_addc_u32 s37, s37, 0
	s_cmp_gt_u32 s65, 29
	s_cbranch_scc0 .LBB0_2620
	s_and_b64 vcc, exec, s[22:23]
	s_cbranch_vccz .LBB0_2623
	s_barrier

; #define GAS __attribute__((address_space(1)))
; #define PG8_STAGE(bufoff, gbase, voff) do { _Pragma("unroll") for (int _i = 0; _i < 2; ++_i) \
;         __builtin_amdgcn_global_load_lds((const GAS unsigned*)((const GAS char*)(gbase) + (voff)[_i]), (LAS unsigned*)(lds + (bufoff) + ldsw + _i * 8192), 16, 0, 0); } while (0)
; #define PG8_LDA(dst, b, h) do { _Pragma("unroll") for (int m = 0; m < 4; ++m) _Pragma("unroll") for (int k = 0; k < 2; ++k) dst[m][k] = *(const LAS bf16x8*)(lds + PG8_SA(b, h) + aoff + m * 2048 + k * 1024); } while (0)
; #define PG8_LDB(dst, b, h) do { _Pragma("unroll") for (int n = 0; n < 2; ++n) _Pragma("unroll") for (int k = 0; k < 2; ++k) dst[n][k] = *(const LAS bf16x8*)(lds + PG8_SB(b, h) + boff + n * 2048 + k * 1024); } while (0)
; #define PG8_MMA(ai, bj, At, Bt) do { __builtin_amdgcn_s_setprio(1); _Pragma("unroll") for (int m = 0; m < 4; ++m) _Pragma("unroll") for (int n = 0; n < 2; ++n) _Pragma("unroll") for (int k = 0; k < 2; ++k) \
;         acc[ai][bj][m][n] = __builtin_amdgcn_mfma_f32_16x16x32_bf16(Bt[n][k], At[m][k], acc[ai][bj][m][n], 0, 0, 0); __builtin_amdgcn_s_setprio(0); } while (0)
; #define PG8_WAIT_V(n) asm volatile("s_waitcnt vmcnt(" #n ")" ::: "memory")
; #define PG8_WAIT_L(n) asm volatile("s_waitcnt lgkmcnt(" #n ")" ::: "memory")
; #define PG8_BAR __builtin_amdgcn_s_barrier()
; template <class Epi, class Sched, bool ALIGN_EPI>
; __device__ __forceinline__ void gemm_phase(LAS unsigned char* lds, const Gemm g, const Sched& S, const Epi& E, int wave_id) {
;     ...
;             const bool last = (t == nt - 2);
;             const GAS char* a1 = cA + (size_t)(t + 1) * kstep;
;             const GAS char* a2 = last ? nA : cA + (size_t)(t + 2) * kstep; const GAS char* b2 = last ? nB : cB + (size_t)(t + 2) * kstep;
;             const GAS char* a3 = a2 + kstep; const GAS char* b3 = b2 + kstep;
;             PG8_LDB(B0, 0, 0); PG8_LDB(B1, 0, 1); PG8_SCHED; PG8_LDA(At, 0, 0); PG8_STAGE(PG8_SA(1, 1), a1 + hsA, voffA);
;             PG8_WAIT_V(8); PG8_WAIT_L(0); PG8_BAR; PG8_MMA(0, 0, At, B0); PG8_MMA(0, 1, At, B1); PG8_BAR; PG8_SCHED;
;             PG8_LDA(At, 0, 1); PG8_STAGE(PG8_SB(0, 0), b2, voffB); PG8_STAGE(PG8_SB(0, 1), b2 + hsB, voffB); PG8_STAGE(PG8_SA(0, 0), a2, voffA);
;             PG8_WAIT_V(8); PG8_WAIT_L(0); PG8_BAR; PG8_MMA(1, 0, At, B0); PG8_MMA(1, 1, At, B1); PG8_BAR; PG8_SCHED;
.LBB0_2874:
	s_add_u32 s28, s2, 0xfff80080
	s_addc_u32 s29, s3, -1
	s_cmp_eq_u32 s67, 28
	s_cselect_b32 s31, s23, s29
	s_cselect_b32 s30, s22, s28
	s_cselect_b32 s29, s21, s66
	s_cselect_b32 s28, s27, s33
	v_lshl_add_u64 v[208:209], s[2:3], 0, v[232:233]
	s_add_i32 m0, s40, 0xc400
	s_nop 0
	global_load_lds_dwordx4 v[208:209], off
	v_lshl_add_u64 v[208:209], s[2:3], 0, v[230:231]
	s_add_i32 m0, s40, 0xe400
	s_nop 0
	global_load_lds_dwordx4 v[208:209], off
	v_add_u32_e32 v82, 0x10400, v240
	ds_read_b128 v[18:21], v82
	ds_read_b128 v[88:91], v82 offset:1024
	ds_read_b128 v[108:111], v82 offset:2048
	ds_read_b128 v[112:115], v82 offset:3072
	v_add_u32_e32 v82, 0x14400, v240
	ds_read_b128 v[116:119], v82
	ds_read_b128 v[120:123], v82 offset:1024
	ds_read_b128 v[128:131], v82 offset:2048
	ds_read_b128 v[132:135], v82 offset:3072
	ds_read_b128 v[136:139], v239 offset:1024
	ds_read_b128 v[140:143], v239 offset:2048
	ds_read_b128 v[144:147], v239 offset:3072
	ds_read_b128 v[164:167], v239 offset:4096
	ds_read_b128 v[180:183], v239 offset:5120
	ds_read_b128 v[184:187], v239 offset:6144
	ds_read_b128 v[188:191], v239 offset:7168
	ds_read_b128 v[192:195], v239 offset:8192
	s_waitcnt vmcnt(8)
	s_waitcnt lgkmcnt(0)
	s_setprio 1
	s_barrier
	v_mfma_f32_16x16x32_bf16 v[176:179], v[18:21], v[136:139], v[176:179]
	v_mfma_f32_16x16x32_bf16 v[30:33], v[108:111], v[136:139], v[30:33]
	v_mfma_f32_16x16x32_bf16 v[172:175], v[18:21], v[144:147], v[172:175]
	v_mfma_f32_16x16x32_bf16 v[50:53], v[108:111], v[144:147], v[50:53]
	v_mfma_f32_16x16x32_bf16 v[156:159], v[18:21], v[180:183], v[156:159]
	v_mfma_f32_16x16x32_bf16 v[78:81], v[108:111], v[180:183], v[78:81]
	v_mfma_f32_16x16x32_bf16 v[124:127], v[18:21], v[188:191], v[124:127]
	v_mfma_f32_16x16x32_bf16 v[104:107], v[108:111], v[188:191], v[104:107]
	v_mfma_f32_16x16x32_bf16 v[176:179], v[88:91], v[140:143], v[176:179]
	v_mfma_f32_16x16x32_bf16 v[30:33], v[112:115], v[140:143], v[30:33]
	v_mfma_f32_16x16x32_bf16 v[172:175], v[88:91], v[164:167], v[172:175]
	v_mfma_f32_16x16x32_bf16 v[50:53], v[112:115], v[164:167], v[50:53]
	v_mfma_f32_16x16x32_bf16 v[156:159], v[88:91], v[184:187], v[156:159]
	v_mfma_f32_16x16x32_bf16 v[78:81], v[112:115], v[184:187], v[78:81]
	v_mfma_f32_16x16x32_bf16 v[124:127], v[88:91], v[192:195], v[124:127]
	v_mfma_f32_16x16x32_bf16 v[104:107], v[112:115], v[192:195], v[104:107]
	s_setprio 0
	s_setprio 1
	v_mfma_f32_16x16x32_bf16 v[160:163], v[116:119], v[136:139], v[160:163]
	v_mfma_f32_16x16x32_bf16 v[62:65], v[128:131], v[136:139], v[62:65]
	v_mfma_f32_16x16x32_bf16 v[92:95], v[128:131], v[144:147], v[92:95]
	v_mfma_f32_16x16x32_bf16 v[100:103], v[116:119], v[188:191], v[100:103]
	v_mfma_f32_16x16x32_bf16 v[96:99], v[128:131], v[188:191], v[96:99]
	v_mfma_f32_16x16x32_bf16 v[160:163], v[120:123], v[140:143], v[160:163]
	v_mfma_f32_16x16x32_bf16 v[62:65], v[132:135], v[140:143], v[62:65]
	v_mfma_f32_16x16x32_bf16 v[136:139], v[116:119], v[144:147], v[168:171]
	v_mfma_f32_16x16x32_bf16 v[92:95], v[132:135], v[164:167], v[92:95]
	v_mfma_f32_16x16x32_bf16 v[140:143], v[116:119], v[180:183], v[152:155]
	v_mfma_f32_16x16x32_bf16 v[144:147], v[128:131], v[180:183], v[148:151]
	v_mfma_f32_16x16x32_bf16 v[100:103], v[120:123], v[192:195], v[100:103]
	v_mfma_f32_16x16x32_bf16 v[96:99], v[132:135], v[192:195], v[96:99]
	v_mfma_f32_16x16x32_bf16 v[136:139], v[120:123], v[164:167], v[136:139]
	v_mfma_f32_16x16x32_bf16 v[140:143], v[120:123], v[184:187], v[140:143]
	v_mfma_f32_16x16x32_bf16 v[144:147], v[132:135], v[184:187], v[144:147]
	s_setprio 0
	s_barrier
	s_mov_b32 m0, s41
	v_lshl_add_u64 v[200:201], s[28:29], 0, v[0:1]
	s_add_u32 s68, s28, 0x80000
	global_load_lds_dwordx4 v[200:201], off
	v_lshl_add_u64 v[202:203], s[28:29], 0, v[228:229]
	s_mov_b32 m0, s42
	s_addc_u32 s69, s29, 0
	global_load_lds_dwordx4 v[202:203], off
	v_lshl_add_u64 v[82:83], s[68:69], 0, v[0:1]
	s_mov_b32 m0, s43
	v_lshl_add_u64 v[204:205], s[30:31], 0, v[224:225]
	global_load_lds_dwordx4 v[82:83], off
	v_lshl_add_u64 v[82:83], s[68:69], 0, v[228:229]
	s_mov_b32 m0, s44
	v_lshl_add_u64 v[206:207], s[30:31], 0, v[226:227]
	global_load_lds_dwordx4 v[82:83], off
	s_mov_b32 m0, s45
	s_nop 0
	global_load_lds_dwordx4 v[204:205], off
	s_mov_b32 m0, s46
	s_nop 0
	global_load_lds_dwordx4 v[206:207], off
	ds_read_b128 v[148:151], v239 offset:17408
	ds_read_b128 v[152:155], v239 offset:18432
	ds_read_b128 v[164:167], v239 offset:19456
	ds_read_b128 v[168:171], v239 offset:20480
	ds_read_b128 v[180:183], v239 offset:21504
	ds_read_b128 v[184:187], v239 offset:22528
	ds_read_b128 v[188:191], v239 offset:23552
	ds_read_b128 v[192:195], v239 offset:24576
	s_waitcnt vmcnt(8)
	s_waitcnt lgkmcnt(0)
	s_setprio 1
	s_barrier
; #define PG8_STAGE(bufoff, gbase, voff) do { _Pragma("unroll") for (int _i = 0; _i < 2; ++_i) \
;         __builtin_amdgcn_global_load_lds((const GAS unsigned*)((const GAS char*)(gbase) + (voff)[_i]), (LAS unsigned*)(lds + (bufoff) + ldsw + _i * 8192), 16, 0, 0); } while (0)
; #define PG8_LDA(dst, b, h) do { _Pragma("unroll") for (int m = 0; m < 4; ++m) _Pragma("unroll") for (int k = 0; k < 2; ++k) dst[m][k] = *(const LAS bf16x8*)(lds + PG8_SA(b, h) + aoff + m * 2048 + k * 1024); } while (0)
; #define PG8_LDB(dst, b, h) do { _Pragma("unroll") for (int n = 0; n < 2; ++n) _Pragma("unroll") for (int k = 0; k < 2; ++k) dst[n][k] = *(const LAS bf16x8*)(lds + PG8_SB(b, h) + boff + n * 2048 + k * 1024); } while (0)
; #define PG8_MMA(ai, bj, At, Bt) do { __builtin_amdgcn_s_setprio(1); _Pragma("unroll") for (int m = 0; m < 4; ++m) _Pragma("unroll") for (int n = 0; n < 2; ++n) _Pragma("unroll") for (int k = 0; k < 2; ++k) \
;         acc[ai][bj][m][n] = __builtin_amdgcn_mfma_f32_16x16x32_bf16(Bt[n][k], At[m][k], acc[ai][bj][m][n], 0, 0, 0); __builtin_amdgcn_s_setprio(0); } while (0)
; #define PG8_WAIT_V(n) asm volatile("s_waitcnt vmcnt(" #n ")" ::: "memory")
; #define PG8_WAIT_L(n) asm volatile("s_waitcnt lgkmcnt(" #n ")" ::: "memory")
; #define PG8_BAR __builtin_amdgcn_s_barrier()
; #define PG8_SCHED __builtin_amdgcn_sched_barrier(0)
; template <class Epi, class Sched, bool ALIGN_EPI>
; __device__ __forceinline__ void gemm_phase(LAS unsigned char* lds, const Gemm g, const Sched& S, const Epi& E, int wave_id) {
;     ...
;             PG8_WAIT_V(8); PG8_WAIT_L(0); PG8_BAR; PG8_MMA(1, 0, At, B0); PG8_MMA(1, 1, At, B1); PG8_BAR; PG8_SCHED;
;             PG8_LDB(B0, 1, 0); PG8_LDB(B1, 1, 1); PG8_SCHED; PG8_LDA(At, 1, 0); PG8_STAGE(PG8_SA(0, 1), a2 + hsA, voffA);
;             PG8_WAIT_V(8); PG8_WAIT_L(0); PG8_BAR; PG8_MMA(0, 0, At, B0); PG8_MMA(0, 1, At, B1); PG8_BAR; PG8_SCHED;
	v_mfma_f32_16x16x32_bf16 v[82:85], v[18:21], v[148:151], v[84:87]
	v_mfma_f32_16x16x32_bf16 v[70:73], v[108:111], v[148:151], v[70:73]
	v_mfma_f32_16x16x32_bf16 v[58:61], v[18:21], v[164:167], v[58:61]
	v_mfma_f32_16x16x32_bf16 v[54:57], v[108:111], v[164:167], v[54:57]
	v_mfma_f32_16x16x32_bf16 v[38:41], v[18:21], v[180:183], v[38:41]
	v_mfma_f32_16x16x32_bf16 v[34:37], v[108:111], v[180:183], v[34:37]
	v_mfma_f32_16x16x32_bf16 v[14:17], v[18:21], v[188:191], v[14:17]
	v_mfma_f32_16x16x32_bf16 v[10:13], v[108:111], v[188:191], v[10:13]
	v_mfma_f32_16x16x32_bf16 v[82:85], v[88:91], v[152:155], v[82:85]
	v_mfma_f32_16x16x32_bf16 v[70:73], v[112:115], v[152:155], v[70:73]
	v_mfma_f32_16x16x32_bf16 v[58:61], v[88:91], v[168:171], v[58:61]
	v_mfma_f32_16x16x32_bf16 v[54:57], v[112:115], v[168:171], v[54:57]
	v_mfma_f32_16x16x32_bf16 v[38:41], v[88:91], v[184:187], v[38:41]
	v_mfma_f32_16x16x32_bf16 v[34:37], v[112:115], v[184:187], v[34:37]
	v_mfma_f32_16x16x32_bf16 v[14:17], v[88:91], v[192:195], v[14:17]
	v_mfma_f32_16x16x32_bf16 v[10:13], v[112:115], v[192:195], v[10:13]
	s_setprio 0
	s_setprio 1
	v_mfma_f32_16x16x32_bf16 v[66:69], v[128:131], v[148:151], v[66:69]
	v_mfma_f32_16x16x32_bf16 v[46:49], v[116:119], v[164:167], v[46:49]
	v_mfma_f32_16x16x32_bf16 v[42:45], v[128:131], v[164:167], v[42:45]
	v_mfma_f32_16x16x32_bf16 v[26:29], v[116:119], v[180:183], v[26:29]
	v_mfma_f32_16x16x32_bf16 v[22:25], v[128:131], v[180:183], v[22:25]
	v_mfma_f32_16x16x32_bf16 v[6:9], v[116:119], v[188:191], v[6:9]
	v_mfma_f32_16x16x32_bf16 v[2:5], v[128:131], v[188:191], v[2:5]
	v_mfma_f32_16x16x32_bf16 v[18:21], v[116:119], v[148:151], v[74:77]
	v_mfma_f32_16x16x32_bf16 v[66:69], v[132:135], v[152:155], v[66:69]
	v_mfma_f32_16x16x32_bf16 v[46:49], v[120:123], v[168:171], v[46:49]
	v_mfma_f32_16x16x32_bf16 v[42:45], v[132:135], v[168:171], v[42:45]
	v_mfma_f32_16x16x32_bf16 v[26:29], v[120:123], v[184:187], v[26:29]
	v_mfma_f32_16x16x32_bf16 v[22:25], v[132:135], v[184:187], v[22:25]
	v_mfma_f32_16x16x32_bf16 v[6:9], v[120:123], v[192:195], v[6:9]
	v_mfma_f32_16x16x32_bf16 v[2:5], v[132:135], v[192:195], v[2:5]
	v_mfma_f32_16x16x32_bf16 v[18:21], v[120:123], v[152:155], v[18:21]
	s_setprio 0
	s_barrier
	s_add_u32 s30, s30, 0x80000
	s_addc_u32 s31, s31, 0
	s_mov_b32 m0, s47
	v_lshl_add_u64 v[210:211], s[30:31], 0, v[224:225]
	global_load_lds_dwordx4 v[210:211], off
	v_lshl_add_u64 v[210:211], s[30:31], 0, v[226:227]
	s_mov_b32 m0, s48
	s_nop 0
	global_load_lds_dwordx4 v[210:211], off
	v_add_u32_e32 v86, 0x18400, v240
	ds_read_b128 v[74:77], v86
	ds_read_b128 v[88:91], v86 offset:1024
	ds_read_b128 v[108:111], v86 offset:2048
	ds_read_b128 v[112:115], v86 offset:3072
	v_add_u32_e32 v86, 0x1c400, v240
	ds_read_b128 v[116:119], v86
	ds_read_b128 v[120:123], v86 offset:1024
	ds_read_b128 v[128:131], v86 offset:2048
	ds_read_b128 v[132:135], v86 offset:3072
	ds_read_b128 v[148:151], v239 offset:33792
	ds_read_b128 v[152:155], v239 offset:34816
	ds_read_b128 v[164:167], v239 offset:35840
	ds_read_b128 v[180:183], v239 offset:36864
	ds_read_b128 v[184:187], v239 offset:37888
	ds_read_b128 v[188:191], v239 offset:38912
	ds_read_b128 v[192:195], v239 offset:39936
	ds_read_b128 v[196:199], v239 offset:40960
	s_waitcnt vmcnt(8)
	s_waitcnt lgkmcnt(0)
	s_setprio 1
	s_barrier
	v_mfma_f32_16x16x32_bf16 v[168:171], v[74:77], v[148:151], v[176:179]
	v_mfma_f32_16x16x32_bf16 v[176:179], v[88:91], v[152:155], v[168:171]
	v_mfma_f32_16x16x32_bf16 v[30:33], v[108:111], v[148:151], v[30:33]
	v_mfma_f32_16x16x32_bf16 v[168:171], v[74:77], v[164:167], v[172:175]
	v_mfma_f32_16x16x32_bf16 v[50:53], v[108:111], v[164:167], v[50:53]
	v_mfma_f32_16x16x32_bf16 v[156:159], v[74:77], v[184:187], v[156:159]
	v_mfma_f32_16x16x32_bf16 v[78:81], v[108:111], v[184:187], v[78:81]
	v_mfma_f32_16x16x32_bf16 v[124:127], v[74:77], v[192:195], v[124:127]
	v_mfma_f32_16x16x32_bf16 v[104:107], v[108:111], v[192:195], v[104:107]
	v_mfma_f32_16x16x32_bf16 v[30:33], v[112:115], v[152:155], v[30:33]
	v_mfma_f32_16x16x32_bf16 v[172:175], v[88:91], v[180:183], v[168:171]
	v_mfma_f32_16x16x32_bf16 v[50:53], v[112:115], v[180:183], v[50:53]
	v_mfma_f32_16x16x32_bf16 v[156:159], v[88:91], v[188:191], v[156:159]
	v_mfma_f32_16x16x32_bf16 v[78:81], v[112:115], v[188:191], v[78:81]
	v_mfma_f32_16x16x32_bf16 v[124:127], v[88:91], v[196:199], v[124:127]
	v_mfma_f32_16x16x32_bf16 v[104:107], v[112:115], v[196:199], v[104:107]
	s_setprio 0
	s_setprio 1
	v_mfma_f32_16x16x32_bf16 v[136:139], v[116:119], v[164:167], v[136:139]
	v_mfma_f32_16x16x32_bf16 v[160:163], v[116:119], v[148:151], v[160:163]
	v_mfma_f32_16x16x32_bf16 v[62:65], v[128:131], v[148:151], v[62:65]
	v_mfma_f32_16x16x32_bf16 v[168:171], v[120:123], v[180:183], v[136:139]
	v_mfma_f32_16x16x32_bf16 v[136:139], v[116:119], v[184:187], v[140:143]
	v_mfma_f32_16x16x32_bf16 v[160:163], v[120:123], v[152:155], v[160:163]
	v_mfma_f32_16x16x32_bf16 v[62:65], v[132:135], v[152:155], v[62:65]
	v_mfma_f32_16x16x32_bf16 v[92:95], v[128:131], v[164:167], v[92:95]
	v_mfma_f32_16x16x32_bf16 v[152:155], v[120:123], v[188:191], v[136:139]
	v_mfma_f32_16x16x32_bf16 v[136:139], v[128:131], v[184:187], v[144:147]
	v_mfma_f32_16x16x32_bf16 v[100:103], v[116:119], v[192:195], v[100:103]
	v_mfma_f32_16x16x32_bf16 v[96:99], v[128:131], v[192:195], v[96:99]
	v_mfma_f32_16x16x32_bf16 v[92:95], v[132:135], v[180:183], v[92:95]
	v_mfma_f32_16x16x32_bf16 v[148:151], v[132:135], v[188:191], v[136:139]
	v_mfma_f32_16x16x32_bf16 v[100:103], v[120:123], v[196:199], v[100:103]
	v_mfma_f32_16x16x32_bf16 v[96:99], v[132:135], v[196:199], v[96:99]
	s_setprio 0
	s_barrier
; #define PG8_STAGE(bufoff, gbase, voff) do { _Pragma("unroll") for (int _i = 0; _i < 2; ++_i) \
;         __builtin_amdgcn_global_load_lds((const GAS unsigned*)((const GAS char*)(gbase) + (voff)[_i]), (LAS unsigned*)(lds + (bufoff) + ldsw + _i * 8192), 16, 0, 0); } while (0)
; #define PG8_LDA(dst, b, h) do { _Pragma("unroll") for (int m = 0; m < 4; ++m) _Pragma("unroll") for (int k = 0; k < 2; ++k) dst[m][k] = *(const LAS bf16x8*)(lds + PG8_SA(b, h) + aoff + m * 2048 + k * 1024); } while (0)
; #define PG8_MMA(ai, bj, At, Bt) do { __builtin_amdgcn_s_setprio(1); _Pragma("unroll") for (int m = 0; m < 4; ++m) _Pragma("unroll") for (int n = 0; n < 2; ++n) _Pragma("unroll") for (int k = 0; k < 2; ++k) \
;         acc[ai][bj][m][n] = __builtin_amdgcn_mfma_f32_16x16x32_bf16(Bt[n][k], At[m][k], acc[ai][bj][m][n], 0, 0, 0); __builtin_amdgcn_s_setprio(0); } while (0)
; #define PG8_WAIT_V(n) asm volatile("s_waitcnt vmcnt(" #n ")" ::: "memory")
; #define PG8_WAIT_L(n) asm volatile("s_waitcnt lgkmcnt(" #n ")" ::: "memory")
; #define PG8_BAR __builtin_amdgcn_s_barrier()
; #define PG8_SCHED __builtin_amdgcn_sched_barrier(0)
; template <class Epi, class Sched, bool ALIGN_EPI>
; __device__ __forceinline__ void gemm_phase(LAS unsigned char* lds, const Gemm g, const Sched& S, const Epi& E, int wave_id) {
;     ...
;             PG8_LDA(At, 1, 1); PG8_STAGE(PG8_SB(1, 0), b3, voffB); PG8_STAGE(PG8_SB(1, 1), b3 + hsB, voffB); PG8_STAGE(PG8_SA(1, 0), a3, voffA);
;             PG8_WAIT_V(8); PG8_WAIT_L(0); PG8_BAR; PG8_MMA(1, 0, At, B0); PG8_MMA(1, 1, At, B1); PG8_BAR; PG8_SCHED;
;         }
;         if constexpr (ALIGN_EPI) { if (wr == 0) PG8_BAR; }
	s_mov_b32 m0, s52
	v_lshl_add_u64 v[86:87], v[200:201], 0, s[92:93]
	s_add_u32 s28, s28, 0x80080
	global_load_lds_dwordx4 v[86:87], off
	v_lshl_add_u64 v[86:87], v[202:203], 0, s[92:93]
	s_mov_b32 m0, s53
	s_addc_u32 s29, s29, 0
	global_load_lds_dwordx4 v[86:87], off
	v_lshl_add_u64 v[86:87], s[28:29], 0, v[0:1]
	s_mov_b32 m0, s56
	s_nop 0
	global_load_lds_dwordx4 v[86:87], off
	v_lshl_add_u64 v[86:87], s[28:29], 0, v[228:229]
	s_mov_b32 m0, s57
	s_nop 0
	global_load_lds_dwordx4 v[86:87], off
	v_lshl_add_u64 v[86:87], v[204:205], 0, s[92:93]
	s_mov_b32 m0, s54
	s_nop 0
	global_load_lds_dwordx4 v[86:87], off
	v_lshl_add_u64 v[86:87], v[206:207], 0, s[92:93]
	s_mov_b32 m0, s55
	s_nop 0
	global_load_lds_dwordx4 v[86:87], off
	ds_read_b128 v[136:139], v239 offset:50176
	ds_read_b128 v[140:143], v239 offset:51200
	ds_read_b128 v[144:147], v239 offset:52224
	ds_read_b128 v[164:167], v239 offset:53248
	ds_read_b128 v[180:183], v239 offset:54272
	ds_read_b128 v[184:187], v239 offset:55296
	ds_read_b128 v[188:191], v239 offset:56320
	ds_read_b128 v[192:195], v239 offset:57344
	s_waitcnt vmcnt(8)
	s_waitcnt lgkmcnt(0)
	s_setprio 1
	s_barrier
	v_mfma_f32_16x16x32_bf16 v[82:85], v[74:77], v[136:139], v[82:85]
	v_mfma_f32_16x16x32_bf16 v[70:73], v[108:111], v[136:139], v[70:73]
	v_mfma_f32_16x16x32_bf16 v[58:61], v[74:77], v[144:147], v[58:61]
	v_mfma_f32_16x16x32_bf16 v[54:57], v[108:111], v[144:147], v[54:57]
	v_mfma_f32_16x16x32_bf16 v[38:41], v[74:77], v[180:183], v[38:41]
	v_mfma_f32_16x16x32_bf16 v[34:37], v[108:111], v[180:183], v[34:37]
	v_mfma_f32_16x16x32_bf16 v[14:17], v[74:77], v[188:191], v[14:17]
	v_mfma_f32_16x16x32_bf16 v[10:13], v[108:111], v[188:191], v[10:13]
	v_mfma_f32_16x16x32_bf16 v[84:87], v[88:91], v[140:143], v[82:85]
	v_mfma_f32_16x16x32_bf16 v[70:73], v[112:115], v[140:143], v[70:73]
	v_mfma_f32_16x16x32_bf16 v[58:61], v[88:91], v[164:167], v[58:61]
	v_mfma_f32_16x16x32_bf16 v[54:57], v[112:115], v[164:167], v[54:57]
	v_mfma_f32_16x16x32_bf16 v[38:41], v[88:91], v[184:187], v[38:41]
	v_mfma_f32_16x16x32_bf16 v[34:37], v[112:115], v[184:187], v[34:37]
	v_mfma_f32_16x16x32_bf16 v[14:17], v[88:91], v[192:195], v[14:17]
	v_mfma_f32_16x16x32_bf16 v[10:13], v[112:115], v[192:195], v[10:13]
	s_setprio 0
	s_setprio 1
	v_mfma_f32_16x16x32_bf16 v[18:21], v[116:119], v[136:139], v[18:21]
	v_mfma_f32_16x16x32_bf16 v[74:77], v[120:123], v[140:143], v[18:21]
	v_mfma_f32_16x16x32_bf16 v[18:21], v[128:131], v[136:139], v[66:69]
	v_mfma_f32_16x16x32_bf16 v[66:69], v[132:135], v[140:143], v[18:21]
	v_mfma_f32_16x16x32_bf16 v[18:21], v[116:119], v[144:147], v[46:49]
	v_mfma_f32_16x16x32_bf16 v[46:49], v[120:123], v[164:167], v[18:21]
	v_mfma_f32_16x16x32_bf16 v[18:21], v[128:131], v[144:147], v[42:45]
	v_mfma_f32_16x16x32_bf16 v[42:45], v[132:135], v[164:167], v[18:21]
	v_mfma_f32_16x16x32_bf16 v[18:21], v[116:119], v[180:183], v[26:29]
	v_mfma_f32_16x16x32_bf16 v[26:29], v[120:123], v[184:187], v[18:21]
	v_mfma_f32_16x16x32_bf16 v[18:21], v[128:131], v[180:183], v[22:25]
	v_mfma_f32_16x16x32_bf16 v[6:9], v[116:119], v[188:191], v[6:9]
	v_mfma_f32_16x16x32_bf16 v[2:5], v[128:131], v[188:191], v[2:5]
	v_mfma_f32_16x16x32_bf16 v[22:25], v[132:135], v[184:187], v[18:21]
	v_mfma_f32_16x16x32_bf16 v[6:9], v[120:123], v[192:195], v[6:9]
	v_mfma_f32_16x16x32_bf16 v[2:5], v[132:135], v[192:195], v[2:5]
	s_setprio 0
	s_barrier
	s_add_i32 s67, s67, 2
	s_add_u32 s33, s33, 0x100
	s_addc_u32 s66, s66, 0
	s_add_u32 s2, s2, 0x100
	s_addc_u32 s3, s3, 0
	s_cmp_gt_u32 s67, 29
	s_cbranch_scc0 .LBB0_2874
	s_and_b64 vcc, exec, s[16:17]
	s_cbranch_vccz .LBB0_2877
	s_barrier

; #define GAS __attribute__((address_space(1)))
; #define PG8_STAGE(bufoff, gbase, voff) do { _Pragma("unroll") for (int _i = 0; _i < 2; ++_i) \
;         __builtin_amdgcn_global_load_lds((const GAS unsigned*)((const GAS char*)(gbase) + (voff)[_i]), (LAS unsigned*)(lds + (bufoff) + ldsw + _i * 8192), 16, 0, 0); } while (0)
; #define PG8_LDA(dst, b, h) do { _Pragma("unroll") for (int m = 0; m < 4; ++m) _Pragma("unroll") for (int k = 0; k < 2; ++k) dst[m][k] = *(const LAS bf16x8*)(lds + PG8_SA(b, h) + aoff + m * 2048 + k * 1024); } while (0)
; #define PG8_LDB(dst, b, h) do { _Pragma("unroll") for (int n = 0; n < 2; ++n) _Pragma("unroll") for (int k = 0; k < 2; ++k) dst[n][k] = *(const LAS bf16x8*)(lds + PG8_SB(b, h) + boff + n * 2048 + k * 1024); } while (0)
; #define PG8_MMA(ai, bj, At, Bt) do { __builtin_amdgcn_s_setprio(1); _Pragma("unroll") for (int m = 0; m < 4; ++m) _Pragma("unroll") for (int n = 0; n < 2; ++n) _Pragma("unroll") for (int k = 0; k < 2; ++k) \
;         acc[ai][bj][m][n] = __builtin_amdgcn_mfma_f32_16x16x32_bf16(Bt[n][k], At[m][k], acc[ai][bj][m][n], 0, 0, 0); __builtin_amdgcn_s_setprio(0); } while (0)
; #define PG8_WAIT_V(n) asm volatile("s_waitcnt vmcnt(" #n ")" ::: "memory")
; #define PG8_WAIT_L(n) asm volatile("s_waitcnt lgkmcnt(" #n ")" ::: "memory")
; #define PG8_BAR __builtin_amdgcn_s_barrier()
; template <class Epi, class Sched, bool ALIGN_EPI>
; __device__ __forceinline__ void gemm_phase(LAS unsigned char* lds, const Gemm g, const Sched& S, const Epi& E, int wave_id) {
;     ...
;             const bool last = (t == nt - 2);
;             const GAS char* a1 = cA + (size_t)(t + 1) * kstep;
;             const GAS char* a2 = last ? nA : cA + (size_t)(t + 2) * kstep; const GAS char* b2 = last ? nB : cB + (size_t)(t + 2) * kstep;
;             const GAS char* a3 = a2 + kstep; const GAS char* b3 = b2 + kstep;
;             PG8_LDB(B0, 0, 0); PG8_LDB(B1, 0, 1); PG8_SCHED; PG8_LDA(At, 0, 0); PG8_STAGE(PG8_SA(1, 1), a1 + hsA, voffA);
;             PG8_WAIT_V(8); PG8_WAIT_L(0); PG8_BAR; PG8_MMA(0, 0, At, B0); PG8_MMA(0, 1, At, B1); PG8_BAR; PG8_SCHED;
;             PG8_LDA(At, 0, 1); PG8_STAGE(PG8_SB(0, 0), b2, voffB); PG8_STAGE(PG8_SB(0, 1), b2 + hsB, voffB); PG8_STAGE(PG8_SA(0, 0), a2, voffA);
;             PG8_WAIT_V(8); PG8_WAIT_L(0); PG8_BAR; PG8_MMA(1, 0, At, B0); PG8_MMA(1, 1, At, B1); PG8_BAR; PG8_SCHED;
.LBB0_3681:
	s_add_u32 s0, s28, 0x100
	s_addc_u32 s1, s29, 0
	s_cmpk_eq_i32 s63, 0x54
	s_cselect_b32 s35, s25, s1
	s_cselect_b32 s34, s24, s0
	s_cselect_b32 s31, s27, s62
	s_cselect_b32 s30, s26, s61
	v_lshl_add_u64 v[204:205], s[28:29], 0, v[190:191]
	s_add_i32 m0, s41, 0xc400
	s_nop 0
	global_load_lds_dwordx4 v[204:205], off
	v_lshl_add_u64 v[204:205], s[28:29], 0, v[188:189]
	s_add_i32 m0, s41, 0xe400
	s_nop 0
	global_load_lds_dwordx4 v[204:205], off
	v_add_u32_e32 v46, 0x10400, v208
	v_add_u32_e32 v62, 0x14400, v208
	ds_read_b128 v[34:37], v46
	ds_read_b128 v[38:41], v46 offset:1024
	ds_read_b128 v[42:45], v46 offset:2048
	ds_read_b128 v[46:49], v46 offset:3072
	ds_read_b128 v[50:53], v62
	ds_read_b128 v[54:57], v62 offset:1024
	ds_read_b128 v[58:61], v62 offset:2048
	ds_read_b128 v[62:65], v62 offset:3072
	ds_read_b128 v[162:165], v207 offset:1024
	ds_read_b128 v[166:169], v207 offset:2048
	ds_read_b128 v[170:173], v207 offset:3072
	ds_read_b128 v[174:177], v207 offset:4096
	ds_read_b128 v[178:181], v207 offset:5120
	ds_read_b128 v[192:195], v207 offset:6144
	ds_read_b128 v[196:199], v207 offset:7168
	ds_read_b128 v[200:203], v207 offset:8192
	s_waitcnt vmcnt(8)
	s_waitcnt lgkmcnt(0)
	s_setprio 1
	s_barrier
	v_mfma_f32_16x16x32_bf16 v[158:161], v[34:37], v[162:165], v[158:161]
	v_mfma_f32_16x16x32_bf16 v[154:157], v[42:45], v[162:165], v[154:157]
	v_mfma_f32_16x16x32_bf16 v[142:145], v[34:37], v[170:173], v[142:145]
	v_mfma_f32_16x16x32_bf16 v[138:141], v[42:45], v[170:173], v[138:141]
	v_mfma_f32_16x16x32_bf16 v[126:129], v[34:37], v[178:181], v[126:129]
	v_mfma_f32_16x16x32_bf16 v[122:125], v[42:45], v[178:181], v[122:125]
	v_mfma_f32_16x16x32_bf16 v[110:113], v[34:37], v[196:199], v[110:113]
	v_mfma_f32_16x16x32_bf16 v[106:109], v[42:45], v[196:199], v[106:109]
	v_mfma_f32_16x16x32_bf16 v[158:161], v[38:41], v[166:169], v[158:161]
	v_mfma_f32_16x16x32_bf16 v[154:157], v[46:49], v[166:169], v[154:157]
	v_mfma_f32_16x16x32_bf16 v[142:145], v[38:41], v[174:177], v[142:145]
	v_mfma_f32_16x16x32_bf16 v[138:141], v[46:49], v[174:177], v[138:141]
	v_mfma_f32_16x16x32_bf16 v[126:129], v[38:41], v[192:195], v[126:129]
	v_mfma_f32_16x16x32_bf16 v[122:125], v[46:49], v[192:195], v[122:125]
	v_mfma_f32_16x16x32_bf16 v[110:113], v[38:41], v[200:203], v[110:113]
	v_mfma_f32_16x16x32_bf16 v[106:109], v[46:49], v[200:203], v[106:109]
	s_setprio 0
	s_setprio 1
	v_mfma_f32_16x16x32_bf16 v[150:153], v[50:53], v[162:165], v[150:153]
	v_mfma_f32_16x16x32_bf16 v[146:149], v[58:61], v[162:165], v[146:149]
	v_mfma_f32_16x16x32_bf16 v[134:137], v[50:53], v[170:173], v[134:137]
	v_mfma_f32_16x16x32_bf16 v[130:133], v[58:61], v[170:173], v[130:133]
	v_mfma_f32_16x16x32_bf16 v[118:121], v[50:53], v[178:181], v[118:121]
	v_mfma_f32_16x16x32_bf16 v[114:117], v[58:61], v[178:181], v[114:117]
	v_mfma_f32_16x16x32_bf16 v[102:105], v[50:53], v[196:199], v[102:105]
	v_mfma_f32_16x16x32_bf16 v[98:101], v[58:61], v[196:199], v[98:101]
	v_mfma_f32_16x16x32_bf16 v[150:153], v[54:57], v[166:169], v[150:153]
	v_mfma_f32_16x16x32_bf16 v[146:149], v[62:65], v[166:169], v[146:149]
	v_mfma_f32_16x16x32_bf16 v[134:137], v[54:57], v[174:177], v[134:137]
	v_mfma_f32_16x16x32_bf16 v[130:133], v[62:65], v[174:177], v[130:133]
	v_mfma_f32_16x16x32_bf16 v[118:121], v[54:57], v[192:195], v[118:121]
	v_mfma_f32_16x16x32_bf16 v[114:117], v[62:65], v[192:195], v[114:117]
	v_mfma_f32_16x16x32_bf16 v[102:105], v[54:57], v[200:203], v[102:105]
	v_mfma_f32_16x16x32_bf16 v[98:101], v[62:65], v[200:203], v[98:101]
	s_setprio 0
	s_barrier
	s_mov_b32 m0, s42
	v_lshl_add_u64 v[204:205], s[30:31], 0, v[0:1]
	s_add_u32 s28, s30, 0x160000
	global_load_lds_dwordx4 v[204:205], off
	v_lshl_add_u64 v[218:219], s[30:31], 0, v[186:187]
	s_mov_b32 m0, s43
	s_addc_u32 s29, s31, 0
	global_load_lds_dwordx4 v[218:219], off
	v_lshl_add_u64 v[210:211], s[28:29], 0, v[0:1]
	s_mov_b32 m0, s44
	v_lshl_add_u64 v[220:221], s[34:35], 0, v[182:183]
	global_load_lds_dwordx4 v[210:211], off
	v_lshl_add_u64 v[210:211], s[28:29], 0, v[186:187]
	s_mov_b32 m0, s45
	v_lshl_add_u64 v[224:225], s[34:35], 0, v[184:185]
	global_load_lds_dwordx4 v[210:211], off
	s_mov_b32 m0, s46
	s_nop 0
	global_load_lds_dwordx4 v[220:221], off
	s_mov_b32 m0, s47
	s_nop 0
	global_load_lds_dwordx4 v[224:225], off
	ds_read_b128 v[162:165], v207 offset:17408
	ds_read_b128 v[166:169], v207 offset:18432
	ds_read_b128 v[170:173], v207 offset:19456
	ds_read_b128 v[174:177], v207 offset:20480
	ds_read_b128 v[178:181], v207 offset:21504
	ds_read_b128 v[192:195], v207 offset:22528
	ds_read_b128 v[196:199], v207 offset:23552
	ds_read_b128 v[200:203], v207 offset:24576
	s_waitcnt vmcnt(8)
	s_waitcnt lgkmcnt(0)
	s_setprio 1
	s_barrier
; #define PG8_STAGE(bufoff, gbase, voff) do { _Pragma("unroll") for (int _i = 0; _i < 2; ++_i) \
;         __builtin_amdgcn_global_load_lds((const GAS unsigned*)((const GAS char*)(gbase) + (voff)[_i]), (LAS unsigned*)(lds + (bufoff) + ldsw + _i * 8192), 16, 0, 0); } while (0)
; #define PG8_LDA(dst, b, h) do { _Pragma("unroll") for (int m = 0; m < 4; ++m) _Pragma("unroll") for (int k = 0; k < 2; ++k) dst[m][k] = *(const LAS bf16x8*)(lds + PG8_SA(b, h) + aoff + m * 2048 + k * 1024); } while (0)
; #define PG8_LDB(dst, b, h) do { _Pragma("unroll") for (int n = 0; n < 2; ++n) _Pragma("unroll") for (int k = 0; k < 2; ++k) dst[n][k] = *(const LAS bf16x8*)(lds + PG8_SB(b, h) + boff + n * 2048 + k * 1024); } while (0)
; #define PG8_MMA(ai, bj, At, Bt) do { __builtin_amdgcn_s_setprio(1); _Pragma("unroll") for (int m = 0; m < 4; ++m) _Pragma("unroll") for (int n = 0; n < 2; ++n) _Pragma("unroll") for (int k = 0; k < 2; ++k) \
;         acc[ai][bj][m][n] = __builtin_amdgcn_mfma_f32_16x16x32_bf16(Bt[n][k], At[m][k], acc[ai][bj][m][n], 0, 0, 0); __builtin_amdgcn_s_setprio(0); } while (0)
; #define PG8_WAIT_V(n) asm volatile("s_waitcnt vmcnt(" #n ")" ::: "memory")
; #define PG8_WAIT_L(n) asm volatile("s_waitcnt lgkmcnt(" #n ")" ::: "memory")
; #define PG8_BAR __builtin_amdgcn_s_barrier()
; #define PG8_SCHED __builtin_amdgcn_sched_barrier(0)
; template <class Epi, class Sched, bool ALIGN_EPI>
; __device__ __forceinline__ void gemm_phase(LAS unsigned char* lds, const Gemm g, const Sched& S, const Epi& E, int wave_id) {
;     ...
;             PG8_WAIT_V(8); PG8_WAIT_L(0); PG8_BAR; PG8_MMA(1, 0, At, B0); PG8_MMA(1, 1, At, B1); PG8_BAR; PG8_SCHED;
;             PG8_LDB(B0, 1, 0); PG8_LDB(B1, 1, 1); PG8_SCHED; PG8_LDA(At, 1, 0); PG8_STAGE(PG8_SA(0, 1), a2 + hsA, voffA);
;             PG8_WAIT_V(8); PG8_WAIT_L(0); PG8_BAR; PG8_MMA(0, 0, At, B0); PG8_MMA(0, 1, At, B1); PG8_BAR; PG8_SCHED;
	v_mfma_f32_16x16x32_bf16 v[94:97], v[34:37], v[162:165], v[94:97]
	v_mfma_f32_16x16x32_bf16 v[90:93], v[42:45], v[162:165], v[90:93]
	v_mfma_f32_16x16x32_bf16 v[78:81], v[34:37], v[170:173], v[78:81]
	v_mfma_f32_16x16x32_bf16 v[74:77], v[42:45], v[170:173], v[74:77]
	v_mfma_f32_16x16x32_bf16 v[30:33], v[34:37], v[178:181], v[30:33]
	v_mfma_f32_16x16x32_bf16 v[26:29], v[42:45], v[178:181], v[26:29]
	v_mfma_f32_16x16x32_bf16 v[14:17], v[34:37], v[196:199], v[14:17]
	v_mfma_f32_16x16x32_bf16 v[10:13], v[42:45], v[196:199], v[10:13]
	v_mfma_f32_16x16x32_bf16 v[94:97], v[38:41], v[166:169], v[94:97]
	v_mfma_f32_16x16x32_bf16 v[90:93], v[46:49], v[166:169], v[90:93]
	v_mfma_f32_16x16x32_bf16 v[78:81], v[38:41], v[174:177], v[78:81]
	v_mfma_f32_16x16x32_bf16 v[74:77], v[46:49], v[174:177], v[74:77]
	v_mfma_f32_16x16x32_bf16 v[30:33], v[38:41], v[192:195], v[30:33]
	v_mfma_f32_16x16x32_bf16 v[26:29], v[46:49], v[192:195], v[26:29]
	v_mfma_f32_16x16x32_bf16 v[14:17], v[38:41], v[200:203], v[14:17]
	v_mfma_f32_16x16x32_bf16 v[10:13], v[46:49], v[200:203], v[10:13]
	s_setprio 0
	s_setprio 1
	v_mfma_f32_16x16x32_bf16 v[22:25], v[50:53], v[178:181], v[22:25]
	v_mfma_f32_16x16x32_bf16 v[18:21], v[58:61], v[178:181], v[18:21]
	v_mfma_f32_16x16x32_bf16 v[6:9], v[50:53], v[196:199], v[6:9]
	v_mfma_f32_16x16x32_bf16 v[2:5], v[58:61], v[196:199], v[2:5]
	v_mfma_f32_16x16x32_bf16 v[34:37], v[50:53], v[162:165], v[86:89]
	v_mfma_f32_16x16x32_bf16 v[38:41], v[58:61], v[162:165], v[82:85]
	v_mfma_f32_16x16x32_bf16 v[42:45], v[50:53], v[170:173], v[70:73]
	v_mfma_f32_16x16x32_bf16 v[46:49], v[58:61], v[170:173], v[66:69]
	v_mfma_f32_16x16x32_bf16 v[22:25], v[54:57], v[192:195], v[22:25]
	v_mfma_f32_16x16x32_bf16 v[18:21], v[62:65], v[192:195], v[18:21]
	v_mfma_f32_16x16x32_bf16 v[6:9], v[54:57], v[200:203], v[6:9]
	v_mfma_f32_16x16x32_bf16 v[2:5], v[62:65], v[200:203], v[2:5]
	v_mfma_f32_16x16x32_bf16 v[34:37], v[54:57], v[166:169], v[34:37]
	v_mfma_f32_16x16x32_bf16 v[38:41], v[62:65], v[166:169], v[38:41]
	v_mfma_f32_16x16x32_bf16 v[42:45], v[54:57], v[174:177], v[42:45]
	v_mfma_f32_16x16x32_bf16 v[46:49], v[62:65], v[174:177], v[46:49]
	s_setprio 0
	s_barrier
	s_add_u32 s28, s34, 0x160000
	s_addc_u32 s29, s35, 0
	s_mov_b32 m0, s48
	v_lshl_add_u64 v[210:211], s[28:29], 0, v[182:183]
	global_load_lds_dwordx4 v[210:211], off
	v_lshl_add_u64 v[210:211], s[28:29], 0, v[184:185]
	s_mov_b32 m0, s49
	s_nop 0
	global_load_lds_dwordx4 v[210:211], off
	v_add_u32_e32 v62, 0x18400, v208
	v_add_u32_e32 v66, 0x1c400, v208
	ds_read_b128 v[50:53], v62
	ds_read_b128 v[54:57], v62 offset:1024
	ds_read_b128 v[58:61], v62 offset:2048
	ds_read_b128 v[62:65], v62 offset:3072
	ds_read_b128 v[162:165], v66
	ds_read_b128 v[166:169], v66 offset:1024
	ds_read_b128 v[170:173], v66 offset:2048
	ds_read_b128 v[174:177], v66 offset:3072
	ds_read_b128 v[66:69], v207 offset:33792
	ds_read_b128 v[70:73], v207 offset:34816
	ds_read_b128 v[82:85], v207 offset:35840
	ds_read_b128 v[86:89], v207 offset:36864
	ds_read_b128 v[178:181], v207 offset:37888
	ds_read_b128 v[192:195], v207 offset:38912
	ds_read_b128 v[196:199], v207 offset:39936
	ds_read_b128 v[200:203], v207 offset:40960
	s_waitcnt vmcnt(8)
	s_waitcnt lgkmcnt(0)
	s_setprio 1
	s_barrier
	v_mfma_f32_16x16x32_bf16 v[158:161], v[50:53], v[66:69], v[158:161]
	v_mfma_f32_16x16x32_bf16 v[154:157], v[58:61], v[66:69], v[154:157]
	v_mfma_f32_16x16x32_bf16 v[142:145], v[50:53], v[82:85], v[142:145]
	v_mfma_f32_16x16x32_bf16 v[138:141], v[58:61], v[82:85], v[138:141]
	v_mfma_f32_16x16x32_bf16 v[126:129], v[50:53], v[178:181], v[126:129]
	v_mfma_f32_16x16x32_bf16 v[122:125], v[58:61], v[178:181], v[122:125]
	v_mfma_f32_16x16x32_bf16 v[110:113], v[50:53], v[196:199], v[110:113]
	v_mfma_f32_16x16x32_bf16 v[106:109], v[58:61], v[196:199], v[106:109]
	v_mfma_f32_16x16x32_bf16 v[158:161], v[54:57], v[70:73], v[158:161]
	v_mfma_f32_16x16x32_bf16 v[154:157], v[62:65], v[70:73], v[154:157]
	v_mfma_f32_16x16x32_bf16 v[142:145], v[54:57], v[86:89], v[142:145]
	v_mfma_f32_16x16x32_bf16 v[138:141], v[62:65], v[86:89], v[138:141]
	v_mfma_f32_16x16x32_bf16 v[126:129], v[54:57], v[192:195], v[126:129]
	v_mfma_f32_16x16x32_bf16 v[122:125], v[62:65], v[192:195], v[122:125]
	v_mfma_f32_16x16x32_bf16 v[110:113], v[54:57], v[200:203], v[110:113]
	v_mfma_f32_16x16x32_bf16 v[106:109], v[62:65], v[200:203], v[106:109]
	s_setprio 0
	s_setprio 1
	v_mfma_f32_16x16x32_bf16 v[150:153], v[162:165], v[66:69], v[150:153]
	v_mfma_f32_16x16x32_bf16 v[66:69], v[170:173], v[66:69], v[146:149]
	v_mfma_f32_16x16x32_bf16 v[146:149], v[174:177], v[70:73], v[66:69]
	v_mfma_f32_16x16x32_bf16 v[66:69], v[162:165], v[82:85], v[134:137]
	v_mfma_f32_16x16x32_bf16 v[134:137], v[166:169], v[86:89], v[66:69]
	v_mfma_f32_16x16x32_bf16 v[66:69], v[170:173], v[82:85], v[130:133]
	v_mfma_f32_16x16x32_bf16 v[130:133], v[174:177], v[86:89], v[66:69]
	v_mfma_f32_16x16x32_bf16 v[66:69], v[162:165], v[178:181], v[118:121]
	v_mfma_f32_16x16x32_bf16 v[118:121], v[166:169], v[192:195], v[66:69]
	v_mfma_f32_16x16x32_bf16 v[66:69], v[170:173], v[178:181], v[114:117]
	v_mfma_f32_16x16x32_bf16 v[114:117], v[174:177], v[192:195], v[66:69]
	v_mfma_f32_16x16x32_bf16 v[66:69], v[162:165], v[196:199], v[102:105]
	v_mfma_f32_16x16x32_bf16 v[102:105], v[166:169], v[200:203], v[66:69]
	v_mfma_f32_16x16x32_bf16 v[66:69], v[170:173], v[196:199], v[98:101]
	v_mfma_f32_16x16x32_bf16 v[150:153], v[166:169], v[70:73], v[150:153]
	v_mfma_f32_16x16x32_bf16 v[98:101], v[174:177], v[200:203], v[66:69]
	s_setprio 0
	s_barrier
; #define PG8_STAGE(bufoff, gbase, voff) do { _Pragma("unroll") for (int _i = 0; _i < 2; ++_i) \
;         __builtin_amdgcn_global_load_lds((const GAS unsigned*)((const GAS char*)(gbase) + (voff)[_i]), (LAS unsigned*)(lds + (bufoff) + ldsw + _i * 8192), 16, 0, 0); } while (0)
; #define PG8_LDA(dst, b, h) do { _Pragma("unroll") for (int m = 0; m < 4; ++m) _Pragma("unroll") for (int k = 0; k < 2; ++k) dst[m][k] = *(const LAS bf16x8*)(lds + PG8_SA(b, h) + aoff + m * 2048 + k * 1024); } while (0)
; #define PG8_MMA(ai, bj, At, Bt) do { __builtin_amdgcn_s_setprio(1); _Pragma("unroll") for (int m = 0; m < 4; ++m) _Pragma("unroll") for (int n = 0; n < 2; ++n) _Pragma("unroll") for (int k = 0; k < 2; ++k) \
;         acc[ai][bj][m][n] = __builtin_amdgcn_mfma_f32_16x16x32_bf16(Bt[n][k], At[m][k], acc[ai][bj][m][n], 0, 0, 0); __builtin_amdgcn_s_setprio(0); } while (0)
; #define PG8_WAIT_V(n) asm volatile("s_waitcnt vmcnt(" #n ")" ::: "memory")
; #define PG8_WAIT_L(n) asm volatile("s_waitcnt lgkmcnt(" #n ")" ::: "memory")
; #define PG8_BAR __builtin_amdgcn_s_barrier()
; #define PG8_SCHED __builtin_amdgcn_sched_barrier(0)
; template <class Epi, class Sched, bool ALIGN_EPI>
; __device__ __forceinline__ void gemm_phase(LAS unsigned char* lds, const Gemm g, const Sched& S, const Epi& E, int wave_id) {
;     ...
;             PG8_LDA(At, 1, 1); PG8_STAGE(PG8_SB(1, 0), b3, voffB); PG8_STAGE(PG8_SB(1, 1), b3 + hsB, voffB); PG8_STAGE(PG8_SA(1, 0), a3, voffA);
;             PG8_WAIT_V(8); PG8_WAIT_L(0); PG8_BAR; PG8_MMA(1, 0, At, B0); PG8_MMA(1, 1, At, B1); PG8_BAR; PG8_SCHED;
;         }
;         if constexpr (ALIGN_EPI) { if (wr == 0) PG8_BAR; }
	s_mov_b32 m0, s52
	v_lshl_add_u64 v[82:83], v[204:205], 0, s[92:93]
	s_add_u32 s28, s30, 0x160080
	s_nop 0
	global_load_lds_dwordx4 v[82:83], off
	v_lshl_add_u64 v[82:83], v[218:219], 0, s[92:93]
	s_mov_b32 m0, s53
	s_addc_u32 s29, s31, 0
	global_load_lds_dwordx4 v[82:83], off
	v_lshl_add_u64 v[82:83], s[28:29], 0, v[0:1]
	s_mov_b32 m0, s56
	s_nop 0
	global_load_lds_dwordx4 v[82:83], off
	v_lshl_add_u64 v[82:83], s[28:29], 0, v[186:187]
	s_mov_b32 m0, s57
	s_nop 0
	global_load_lds_dwordx4 v[82:83], off
	v_lshl_add_u64 v[82:83], v[220:221], 0, s[92:93]
	s_mov_b32 m0, s54
	s_nop 0
	global_load_lds_dwordx4 v[82:83], off
	v_lshl_add_u64 v[82:83], v[224:225], 0, s[92:93]
	s_mov_b32 m0, s55
	s_nop 0
	global_load_lds_dwordx4 v[82:83], off
	ds_read_b128 v[66:69], v207 offset:50176
	ds_read_b128 v[70:73], v207 offset:51200
	ds_read_b128 v[178:181], v207 offset:52224
	ds_read_b128 v[192:195], v207 offset:53248
	ds_read_b128 v[196:199], v207 offset:54272
	ds_read_b128 v[200:203], v207 offset:55296
	ds_read_b128 v[210:213], v207 offset:56320
	ds_read_b128 v[214:217], v207 offset:57344
	s_waitcnt vmcnt(8)
	s_waitcnt lgkmcnt(0)
	s_setprio 1
	s_barrier
	v_mfma_f32_16x16x32_bf16 v[82:85], v[50:53], v[66:69], v[94:97]
	v_mfma_f32_16x16x32_bf16 v[94:97], v[54:57], v[70:73], v[82:85]
	v_mfma_f32_16x16x32_bf16 v[82:85], v[58:61], v[66:69], v[90:93]
	v_mfma_f32_16x16x32_bf16 v[78:81], v[50:53], v[178:181], v[78:81]
	v_mfma_f32_16x16x32_bf16 v[74:77], v[58:61], v[178:181], v[74:77]
	v_mfma_f32_16x16x32_bf16 v[30:33], v[50:53], v[196:199], v[30:33]
	v_mfma_f32_16x16x32_bf16 v[26:29], v[58:61], v[196:199], v[26:29]
	v_mfma_f32_16x16x32_bf16 v[14:17], v[50:53], v[210:213], v[14:17]
	v_mfma_f32_16x16x32_bf16 v[10:13], v[58:61], v[210:213], v[10:13]
	v_mfma_f32_16x16x32_bf16 v[90:93], v[62:65], v[70:73], v[82:85]
	v_mfma_f32_16x16x32_bf16 v[78:81], v[54:57], v[192:195], v[78:81]
	v_mfma_f32_16x16x32_bf16 v[74:77], v[62:65], v[192:195], v[74:77]
	v_mfma_f32_16x16x32_bf16 v[30:33], v[54:57], v[200:203], v[30:33]
	v_mfma_f32_16x16x32_bf16 v[26:29], v[62:65], v[200:203], v[26:29]
	v_mfma_f32_16x16x32_bf16 v[14:17], v[54:57], v[214:217], v[14:17]
	v_mfma_f32_16x16x32_bf16 v[10:13], v[62:65], v[214:217], v[10:13]
	s_setprio 0
	s_setprio 1
	v_mfma_f32_16x16x32_bf16 v[34:37], v[162:165], v[66:69], v[34:37]
	v_mfma_f32_16x16x32_bf16 v[86:89], v[166:169], v[70:73], v[34:37]
	v_mfma_f32_16x16x32_bf16 v[34:37], v[170:173], v[66:69], v[38:41]
	v_mfma_f32_16x16x32_bf16 v[82:85], v[174:177], v[70:73], v[34:37]
	v_mfma_f32_16x16x32_bf16 v[34:37], v[162:165], v[178:181], v[42:45]
	v_mfma_f32_16x16x32_bf16 v[70:73], v[166:169], v[192:195], v[34:37]
	v_mfma_f32_16x16x32_bf16 v[34:37], v[170:173], v[178:181], v[46:49]
	v_mfma_f32_16x16x32_bf16 v[22:25], v[162:165], v[196:199], v[22:25]
	v_mfma_f32_16x16x32_bf16 v[18:21], v[170:173], v[196:199], v[18:21]
	v_mfma_f32_16x16x32_bf16 v[6:9], v[162:165], v[210:213], v[6:9]
	v_mfma_f32_16x16x32_bf16 v[2:5], v[170:173], v[210:213], v[2:5]
	v_mfma_f32_16x16x32_bf16 v[66:69], v[174:177], v[192:195], v[34:37]
	v_mfma_f32_16x16x32_bf16 v[22:25], v[166:169], v[200:203], v[22:25]
	v_mfma_f32_16x16x32_bf16 v[18:21], v[174:177], v[200:203], v[18:21]
	v_mfma_f32_16x16x32_bf16 v[6:9], v[166:169], v[214:217], v[6:9]
	v_mfma_f32_16x16x32_bf16 v[2:5], v[174:177], v[214:217], v[2:5]
	s_setprio 0
	s_barrier
	s_add_i32 s63, s63, 2
	s_add_u32 s61, s61, 0x100
	s_addc_u32 s62, s62, 0
	s_cmpk_gt_u32 s63, 0x55
	s_mov_b64 s[28:29], s[0:1]
	s_cbranch_scc0 .LBB0_3681
	s_and_b64 vcc, exec, s[22:23]
	s_cbranch_vccz .LBB0_3684
	s_barrier
